# GEMM K-loops regrouped into 4 hand-offs per iteration (two MFMA clusters per hand-off), reads drained before the mid barrier, one extra prologue barrier
# speedup vs baseline: 1.0096x; 1.0096x over previous
; #define PG8_STAGE(bufoff, gbase, voff) do { _Pragma("unroll") for (int _i = 0; _i < 2; ++_i) \
;     __builtin_amdgcn_global_load_lds((const unsigned*)((const char*)(gbase) + (voff)[_i]), (LAS unsigned*)(lds + (bufoff) + ldsw + _i * 8192), 16, 0, 0); } while (0)
; #define PG8_WAIT_V(n) asm volatile("s_waitcnt vmcnt(" #n ")" ::: "memory")
; #define PG8_BAR __builtin_amdgcn_s_barrier()
; template <class Epi, class Sched>
; DI void gemm_phase(LAS unsigned char* lds, const Gemm g, const Sched& S, const Epi& E) {
;     ...
;   for (int i = 0; i < 2; ++i) { int R, C; stage_rc(tid * 16 + i * 8192, R, C); const int Rb = Epi::PERM ? ((R & ~31) + perm32(R & 31)) : R;
;     voffA[i] = (unsigned)(R * K + C) * 2u; voffB[i] = (unsigned)(Rb * K + C) * 2u; }
;   const size_t kstep = (size_t)(BK * 2);
;   const size_t hstep = (size_t)HALF * K * 2;
;   const size_t tstep = 2 * hstep;
;   const unsigned ldsw = (unsigned)wid * 1024u;
;   const int aoff = lds_byte(wr * 64 + fr, fq * 8), boff = lds_byte(wc * 32 + fr, fq * 8);
;     ...
;   Unit cur, nxt; int ui = 0;
;   if (!S.next(0, cur)) return;
;   f32x4 acc[2][2][4][2];
; #pragma unroll
;   for (int a = 0; a < 2; ++a)
; #pragma unroll
;     for (int b = 0; b < 2; ++b)
; #pragma unroll
;       for (int m = 0; m < 4; ++m)
; #pragma unroll
;         for (int n = 0; n < 2; ++n) acc[a][b][m][n] = (f32x4){0.f, 0.f, 0.f, 0.f};
;   bf16x8 At[4][2], B0[2][2], B1[2][2];
;   const char* cA = (const char*)g.A + (size_t)cur.pm * tstep; const char* cB = (const char*)g.Bt + (size_t)cur.pn * tstep;
;   PG8_STAGE(PG8_SB(0, 0), cB, voffB); PG8_STAGE(PG8_SA(0, 0), cA, voffA); PG8_STAGE(PG8_SB(0, 1), cB + hstep, voffB); PG8_STAGE(PG8_SA(0, 1), cA + hstep, voffA);
;   if (wr == 1) PG8_BAR;
;   PG8_WAIT_V(4); PG8_BAR;
;   PG8_STAGE(PG8_SB(1, 0), cB + kstep, voffB); PG8_STAGE(PG8_SA(1, 0), cA + kstep, voffA); PG8_STAGE(PG8_SB(1, 1), cB + hstep + kstep, voffB);
;   PG8_WAIT_V(6); PG8_BAR;
.LBB0_365:
	s_lshl_b32 s12, s12, 5
	s_and_b32 s45, s12, 0x60
	s_lshl_b32 s44, s13, 6
	s_lshl_b32 s13, s13, 13
	s_lshl_b32 s12, s45, 7
	s_add_u32 s10, s10, 0xa3a8100
	v_and_b32_e32 v15, 48, v14
	v_lshlrev_b32_e32 v16, 6, v14
	s_movk_i32 s14, 0x3c0
	v_lshlrev_b32_e32 v14, 2, v14
	s_addc_u32 s11, s11, 0
	s_add_i32 m0, s40, 0x18000
	v_lshl_add_u64 v[6:7], v[6:7], 0, s[0:1]
	v_and_or_b32 v15, v16, s14, v15
	v_and_b32_e32 v14, 32, v14
	s_waitcnt vmcnt(4)
	s_barrier
	global_load_lds_dwordx4 v[6:7], off
	v_lshl_add_u64 v[4:5], v[4:5], 0, s[0:1]
	s_add_i32 m0, s40, 0x1a000
	s_add_i32 s46, s40, 0x8000
	s_add_i32 s47, s40, 0xa000
	v_bitop3_b32 v155, s12, v15, v14 bitop3:0xf6
	global_load_lds_dwordx4 v[4:5], off
	v_lshl_add_u64 v[2:3], v[2:3], 0, s[0:1]
	s_mov_b32 m0, s46
	s_add_u32 s12, s4, 0x40080
	v_bitop3_b32 v16, v15, s13, v14 bitop3:0xde
	global_load_lds_dwordx4 v[2:3], off
	v_lshl_add_u64 v[0:1], v[0:1], 0, s[0:1]
	s_mov_b32 m0, s47
	s_addc_u32 s13, s5, 0
	global_load_lds_dwordx4 v[0:1], off
	s_add_i32 m0, s40, 0x1c000
	v_lshl_add_u64 v[0:1], s[12:13], 0, v[136:137]
	global_load_lds_dwordx4 v[0:1], off
	v_lshl_add_u64 v[0:1], s[12:13], 0, v[132:133]
	s_add_i32 m0, s40, 0x1e000
	v_readlane_b32 s12, v241, 52
	global_load_lds_dwordx4 v[0:1], off
	v_lshlrev_b32_e32 v0, 14, v12
	v_and_b32_e32 v0, 0xffff8000, v0
	v_lshl_add_u32 v0, v11, 11, v0
	v_and_b32_e32 v1, 1, v12
	v_lshl_or_b32 v0, v1, 6, v0
	v_lshl_add_u32 v140, v13, 1, v0
	v_lshlrev_b32_e32 v0, 14, v8
	v_and_b32_e32 v0, 0xffff8000, v0
	s_waitcnt vmcnt(6)
	v_lshl_add_u32 v0, v9, 11, v0
	v_and_b32_e32 v1, 1, v8
	v_readlane_b32 s13, v241, 53
	v_lshl_or_b32 v0, v1, 6, v0
	s_mov_b32 s23, s12
	v_readlane_b32 s12, v241, 50
	v_mov_b32_e32 v141, v145
	v_lshl_add_u32 v142, v10, 1, v0
	v_mov_b32_e32 v143, v145
	s_mov_b32 s22, 0
	v_add_u32_e32 v158, 0, v16
	s_mov_b32 s28, s12
	s_barrier
	s_barrier
	v_readlane_b32 s13, v241, 51
	s_branch .LBB0_367

; #define PG8_STAGE(bufoff, gbase, voff) do { _Pragma("unroll") for (int _i = 0; _i < 2; ++_i) \
;     __builtin_amdgcn_global_load_lds((const unsigned*)((const char*)(gbase) + (voff)[_i]), (LAS unsigned*)(lds + (bufoff) + ldsw + _i * 8192), 16, 0, 0); } while (0)
; #define PG8_LDA(dst, b, h) do { _Pragma("unroll") for (int m = 0; m < 4; ++m) _Pragma("unroll") for (int k = 0; k < 2; ++k) dst[m][k] = *(const LAS bf16x8*)(lds + PG8_SA(b, h) + aoff + m * 2048 + k * 1024); } while (0)
; #define PG8_LDB(dst, b, h) do { _Pragma("unroll") for (int n = 0; n < 2; ++n) _Pragma("unroll") for (int k = 0; k < 2; ++k) dst[n][k] = *(const LAS bf16x8*)(lds + PG8_SB(b, h) + boff + n * 2048 + k * 1024); } while (0)
; #define PG8_MMA(ai, bj, At, Bt) do { __builtin_amdgcn_s_setprio(1); _Pragma("unroll") for (int m = 0; m < 4; ++m) _Pragma("unroll") for (int n = 0; n < 2; ++n) _Pragma("unroll") for (int k = 0; k < 2; ++k) \
;     acc[ai][bj][m][n] = __builtin_amdgcn_mfma_f32_16x16x32_bf16(Bt[n][k], At[m][k], acc[ai][bj][m][n], 0, 0, 0); __builtin_amdgcn_s_setprio(0); } while (0)
; #define PG8_WAIT_V(n) asm volatile("s_waitcnt vmcnt(" #n ")" ::: "memory")
; #define PG8_WAIT_L(n) asm volatile("s_waitcnt lgkmcnt(" #n ")" ::: "memory")
; #define PG8_BAR __builtin_amdgcn_s_barrier()
; #define PG8_SCHED __builtin_amdgcn_sched_barrier(0)
; template <class Epi, class Sched>
; DI void gemm_phase(LAS unsigned char* lds, const Gemm g, const Sched& S, const Epi& E) {
;     ...
;       PG8_LDB(B0, 0, 0); PG8_SCHED; PG8_LDA(At, 0, 0); PG8_STAGE(PG8_SA(1, 1), a1 + hstep, voffA);
;       PG8_WAIT_L(8); PG8_BAR; PG8_WAIT_L(0); PG8_MMA(0, 0, At, B0); PG8_BAR; PG8_SCHED;
;       PG8_LDB(B1, 0, 1); PG8_STAGE(PG8_SB(0, 0), b2, voffB);
;       PG8_BAR; PG8_WAIT_L(0); PG8_MMA(0, 1, At, B1); PG8_BAR;
;       PG8_LDA(At, 0, 1); PG8_STAGE(PG8_SA(0, 0), a2, voffA);
;       PG8_BAR; PG8_WAIT_L(0); PG8_MMA(1, 0, At, B0); PG8_BAR; PG8_SCHED;
;       PG8_STAGE(PG8_SB(0, 1), b2 + hstep, voffB);
;       PG8_WAIT_V(6); PG8_BAR; PG8_MMA(1, 1, At, B1); PG8_BAR;
.LBB0_370:
	ds_read_b128 v[128:131], v228
	ds_read_b128 v[146:149], v228 offset:1024
	ds_read_b128 v[150:153], v228 offset:2048
	ds_read_b128 v[160:163], v228 offset:3072
	ds_read_b128 v[164:167], v158
	ds_read_b128 v[168:171], v158 offset:1024
	ds_read_b128 v[172:175], v158 offset:2048
	ds_read_b128 v[176:179], v158 offset:3072
	ds_read_b128 v[196:199], v158 offset:4096
	ds_read_b128 v[200:203], v158 offset:5120
	ds_read_b128 v[204:207], v158 offset:6144
	ds_read_b128 v[208:211], v158 offset:7168
	ds_read_b128 v[212:215], v229
	ds_read_b128 v[216:219], v229 offset:1024
	ds_read_b128 v[220:223], v229 offset:2048
	ds_read_b128 v[224:227], v229 offset:3072
	s_add_u32 s4, s2, 0xfffc0080
	s_addc_u32 s5, s3, -1
	s_add_i32 s51, 0, 0x10000
	s_cmp_eq_u32 s50, 12
	s_cselect_b32 s21, s15, s5
	s_cselect_b32 s20, s29, s4
	s_cselect_b32 s5, s13, s49
	s_cselect_b32 s4, s36, s37
	s_add_i32 m0, s40, 0xc000
	s_nop 0
	global_load_lds_dwordx4 v140, s[2:3]
	s_add_i32 m0, s40, 0xe000
	s_nop 0
	global_load_lds_dwordx4 v142, s[2:3]
	s_waitcnt vmcnt(8)
	s_waitcnt lgkmcnt(0)
	s_barrier
	v_mfma_f32_16x16x32_bf16 v[124:127], v[128:131], v[164:167], v[124:127]
	v_mfma_f32_16x16x32_bf16 v[120:123], v[150:153], v[164:167], v[120:123]
	v_mfma_f32_16x16x32_bf16 v[108:111], v[128:131], v[172:175], v[108:111]
	v_mfma_f32_16x16x32_bf16 v[104:107], v[150:153], v[172:175], v[104:107]
	v_mfma_f32_16x16x32_bf16 v[92:95], v[128:131], v[196:199], v[92:95]
	v_mfma_f32_16x16x32_bf16 v[88:91], v[150:153], v[196:199], v[88:91]
	v_mfma_f32_16x16x32_bf16 v[76:79], v[128:131], v[204:207], v[76:79]
	v_mfma_f32_16x16x32_bf16 v[72:75], v[150:153], v[204:207], v[72:75]
	v_mfma_f32_16x16x32_bf16 v[124:127], v[146:149], v[168:171], v[124:127]
	v_mfma_f32_16x16x32_bf16 v[120:123], v[160:163], v[168:171], v[120:123]
	v_mfma_f32_16x16x32_bf16 v[108:111], v[146:149], v[176:179], v[108:111]
	v_mfma_f32_16x16x32_bf16 v[104:107], v[160:163], v[176:179], v[104:107]
	v_mfma_f32_16x16x32_bf16 v[92:95], v[146:149], v[200:203], v[92:95]
	v_mfma_f32_16x16x32_bf16 v[88:91], v[160:163], v[200:203], v[88:91]
	v_mfma_f32_16x16x32_bf16 v[76:79], v[146:149], v[208:211], v[76:79]
	v_mfma_f32_16x16x32_bf16 v[72:75], v[160:163], v[208:211], v[72:75]
	v_mfma_f32_16x16x32_bf16 v[116:119], v[212:215], v[164:167], v[116:119]
	v_mfma_f32_16x16x32_bf16 v[112:115], v[220:223], v[164:167], v[112:115]
	v_mfma_f32_16x16x32_bf16 v[100:103], v[212:215], v[172:175], v[100:103]
	v_mfma_f32_16x16x32_bf16 v[96:99], v[220:223], v[172:175], v[96:99]
	v_mfma_f32_16x16x32_bf16 v[84:87], v[212:215], v[196:199], v[84:87]
	v_mfma_f32_16x16x32_bf16 v[80:83], v[220:223], v[196:199], v[80:83]
	v_mfma_f32_16x16x32_bf16 v[68:71], v[212:215], v[204:207], v[68:71]
	v_mfma_f32_16x16x32_bf16 v[64:67], v[220:223], v[204:207], v[64:67]
	v_mfma_f32_16x16x32_bf16 v[116:119], v[216:219], v[168:171], v[116:119]
	v_mfma_f32_16x16x32_bf16 v[112:115], v[224:227], v[168:171], v[112:115]
	v_mfma_f32_16x16x32_bf16 v[100:103], v[216:219], v[176:179], v[100:103]
	v_mfma_f32_16x16x32_bf16 v[96:99], v[224:227], v[176:179], v[96:99]
	v_mfma_f32_16x16x32_bf16 v[84:87], v[216:219], v[200:203], v[84:87]
	v_mfma_f32_16x16x32_bf16 v[80:83], v[224:227], v[200:203], v[80:83]
	v_mfma_f32_16x16x32_bf16 v[68:71], v[216:219], v[208:211], v[68:71]
	v_mfma_f32_16x16x32_bf16 v[64:67], v[224:227], v[208:211], v[64:67]
	s_barrier
	ds_read_b128 v[164:167], v158 offset:16384
	ds_read_b128 v[168:171], v158 offset:17408
	ds_read_b128 v[172:175], v158 offset:18432
	ds_read_b128 v[176:179], v158 offset:19456
	ds_read_b128 v[196:199], v158 offset:20480
	ds_read_b128 v[200:203], v158 offset:21504
	ds_read_b128 v[204:207], v158 offset:22528
	ds_read_b128 v[208:211], v158 offset:23552
	s_add_i32 s54, 0, 0x14000
	s_add_i32 s51, s51, s34
	s_add_u32 vcc_lo, s4, s0
	s_addc_u32 vcc_hi, s5, s1
	s_mov_b32 m0, s51
	s_nop 0
	global_load_lds_dwordx4 v136, s[4:5]
	s_add_i32 m0, s51, 0x2000
	s_nop 0
	global_load_lds_dwordx4 v132, s[4:5]
	s_mov_b32 m0, s40
	s_add_u32 s100, s20, s0
	s_addc_u32 s101, s21, s1
	global_load_lds_dwordx4 v138, s[20:21]
	s_mov_b32 m0, s41
	s_nop 0
	global_load_lds_dwordx4 v134, s[20:21]
	s_add_u32 s52, s4, 0x40000
	s_addc_u32 s53, s5, 0
	s_add_i32 s51, s54, s34
	s_mov_b32 m0, s51
	s_nop 0
	global_load_lds_dwordx4 v136, s[52:53]
	s_add_i32 m0, s51, 0x2000
	s_nop 0
	global_load_lds_dwordx4 v132, s[52:53]
	s_add_i32 s51, 0, 0x18000
	s_waitcnt vmcnt(8)
	s_waitcnt lgkmcnt(0)
	s_barrier
	v_mfma_f32_16x16x32_bf16 v[60:63], v[128:131], v[164:167], v[60:63]
	v_mfma_f32_16x16x32_bf16 v[56:59], v[150:153], v[164:167], v[56:59]
	v_mfma_f32_16x16x32_bf16 v[44:47], v[128:131], v[172:175], v[44:47]
	v_mfma_f32_16x16x32_bf16 v[40:43], v[150:153], v[172:175], v[40:43]
	v_mfma_f32_16x16x32_bf16 v[28:31], v[128:131], v[196:199], v[28:31]
	v_mfma_f32_16x16x32_bf16 v[24:27], v[150:153], v[196:199], v[24:27]
	v_mfma_f32_16x16x32_bf16 v[12:15], v[128:131], v[204:207], v[12:15]
	v_mfma_f32_16x16x32_bf16 v[8:11], v[150:153], v[204:207], v[8:11]
	v_mfma_f32_16x16x32_bf16 v[60:63], v[146:149], v[168:171], v[60:63]
	v_mfma_f32_16x16x32_bf16 v[56:59], v[160:163], v[168:171], v[56:59]
	v_mfma_f32_16x16x32_bf16 v[44:47], v[146:149], v[176:179], v[44:47]
	v_mfma_f32_16x16x32_bf16 v[40:43], v[160:163], v[176:179], v[40:43]
	v_mfma_f32_16x16x32_bf16 v[28:31], v[146:149], v[200:203], v[28:31]
	v_mfma_f32_16x16x32_bf16 v[24:27], v[160:163], v[200:203], v[24:27]
	v_mfma_f32_16x16x32_bf16 v[12:15], v[146:149], v[208:211], v[12:15]
	v_mfma_f32_16x16x32_bf16 v[8:11], v[160:163], v[208:211], v[8:11]
	v_mfma_f32_16x16x32_bf16 v[52:55], v[212:215], v[164:167], v[52:55]
	v_mfma_f32_16x16x32_bf16 v[48:51], v[220:223], v[164:167], v[48:51]
	v_mfma_f32_16x16x32_bf16 v[36:39], v[212:215], v[172:175], v[36:39]
	v_mfma_f32_16x16x32_bf16 v[32:35], v[220:223], v[172:175], v[32:35]
	v_mfma_f32_16x16x32_bf16 v[20:23], v[212:215], v[196:199], v[20:23]
	v_mfma_f32_16x16x32_bf16 v[16:19], v[220:223], v[196:199], v[16:19]
	v_mfma_f32_16x16x32_bf16 v[4:7], v[212:215], v[204:207], v[4:7]
	v_mfma_f32_16x16x32_bf16 v[0:3], v[220:223], v[204:207], v[0:3]
	v_mfma_f32_16x16x32_bf16 v[52:55], v[216:219], v[168:171], v[52:55]
	v_mfma_f32_16x16x32_bf16 v[48:51], v[224:227], v[168:171], v[48:51]
	v_mfma_f32_16x16x32_bf16 v[36:39], v[216:219], v[176:179], v[36:39]
	v_mfma_f32_16x16x32_bf16 v[32:35], v[224:227], v[176:179], v[32:35]
	v_mfma_f32_16x16x32_bf16 v[20:23], v[216:219], v[200:203], v[20:23]
	v_mfma_f32_16x16x32_bf16 v[16:19], v[224:227], v[200:203], v[16:19]
	v_mfma_f32_16x16x32_bf16 v[4:7], v[216:219], v[208:211], v[4:7]
	v_mfma_f32_16x16x32_bf16 v[0:3], v[224:227], v[208:211], v[0:3]
	s_barrier
; #define PG8_STAGE(bufoff, gbase, voff) do { _Pragma("unroll") for (int _i = 0; _i < 2; ++_i) \
;     __builtin_amdgcn_global_load_lds((const unsigned*)((const char*)(gbase) + (voff)[_i]), (LAS unsigned*)(lds + (bufoff) + ldsw + _i * 8192), 16, 0, 0); } while (0)
; #define PG8_LDA(dst, b, h) do { _Pragma("unroll") for (int m = 0; m < 4; ++m) _Pragma("unroll") for (int k = 0; k < 2; ++k) dst[m][k] = *(const LAS bf16x8*)(lds + PG8_SA(b, h) + aoff + m * 2048 + k * 1024); } while (0)
; #define PG8_LDB(dst, b, h) do { _Pragma("unroll") for (int n = 0; n < 2; ++n) _Pragma("unroll") for (int k = 0; k < 2; ++k) dst[n][k] = *(const LAS bf16x8*)(lds + PG8_SB(b, h) + boff + n * 2048 + k * 1024); } while (0)
; #define PG8_MMA(ai, bj, At, Bt) do { __builtin_amdgcn_s_setprio(1); _Pragma("unroll") for (int m = 0; m < 4; ++m) _Pragma("unroll") for (int n = 0; n < 2; ++n) _Pragma("unroll") for (int k = 0; k < 2; ++k) \
;     acc[ai][bj][m][n] = __builtin_amdgcn_mfma_f32_16x16x32_bf16(Bt[n][k], At[m][k], acc[ai][bj][m][n], 0, 0, 0); __builtin_amdgcn_s_setprio(0); } while (0)
; #define PG8_WAIT_L(n) asm volatile("s_waitcnt lgkmcnt(" #n ")" ::: "memory")
; #define PG8_BAR __builtin_amdgcn_s_barrier()
; #define PG8_SCHED __builtin_amdgcn_sched_barrier(0)
; template <class Epi, class Sched>
; DI void gemm_phase(LAS unsigned char* lds, const Gemm g, const Sched& S, const Epi& E) {
;     ...
;       PG8_LDB(B0, 1, 0); PG8_SCHED; PG8_LDA(At, 1, 0); PG8_STAGE(PG8_SA(0, 1), a2 + hstep, voffA);
;       PG8_WAIT_L(8); PG8_BAR; PG8_WAIT_L(0); PG8_MMA(0, 0, At, B0); PG8_BAR; PG8_SCHED;
;       PG8_LDB(B1, 1, 1); PG8_STAGE(PG8_SB(1, 0), b3, voffB);
;       PG8_BAR; PG8_WAIT_L(0); PG8_MMA(0, 1, At, B1); PG8_BAR;
;       PG8_LDA(At, 1, 1); PG8_STAGE(PG8_SA(1, 0), a3, voffA);
;       PG8_BAR; PG8_WAIT_L(0); PG8_MMA(1, 0, At, B0); PG8_BAR; PG8_SCHED;
	ds_read_b128 v[128:131], v230
	ds_read_b128 v[146:149], v230 offset:1024
	ds_read_b128 v[150:153], v230 offset:2048
	ds_read_b128 v[160:163], v230 offset:3072
	ds_read_b128 v[164:167], v158 offset:32768
	ds_read_b128 v[168:171], v158 offset:33792
	ds_read_b128 v[172:175], v158 offset:34816
	ds_read_b128 v[176:179], v158 offset:35840
	ds_read_b128 v[196:199], v158 offset:36864
	ds_read_b128 v[200:203], v158 offset:37888
	ds_read_b128 v[204:207], v158 offset:38912
	ds_read_b128 v[208:211], v158 offset:39936
	ds_read_b128 v[212:215], v231
	ds_read_b128 v[216:219], v231 offset:1024
	ds_read_b128 v[220:223], v231 offset:2048
	ds_read_b128 v[224:227], v231 offset:3072
	s_add_u32 s20, s20, 0x40000
	s_addc_u32 s21, s21, 0
	s_mov_b32 m0, s42
	s_nop 0
	global_load_lds_dwordx4 v138, s[20:21]
	s_mov_b32 m0, s43
	s_nop 0
	global_load_lds_dwordx4 v134, s[20:21]
	s_waitcnt vmcnt(8)
	s_waitcnt lgkmcnt(0)
	s_barrier
	v_mfma_f32_16x16x32_bf16 v[124:127], v[128:131], v[164:167], v[124:127]
	v_mfma_f32_16x16x32_bf16 v[120:123], v[150:153], v[164:167], v[120:123]
	v_mfma_f32_16x16x32_bf16 v[108:111], v[128:131], v[172:175], v[108:111]
	v_mfma_f32_16x16x32_bf16 v[104:107], v[150:153], v[172:175], v[104:107]
	v_mfma_f32_16x16x32_bf16 v[92:95], v[128:131], v[196:199], v[92:95]
	v_mfma_f32_16x16x32_bf16 v[88:91], v[150:153], v[196:199], v[88:91]
	v_mfma_f32_16x16x32_bf16 v[76:79], v[128:131], v[204:207], v[76:79]
	v_mfma_f32_16x16x32_bf16 v[72:75], v[150:153], v[204:207], v[72:75]
	v_mfma_f32_16x16x32_bf16 v[124:127], v[146:149], v[168:171], v[124:127]
	v_mfma_f32_16x16x32_bf16 v[120:123], v[160:163], v[168:171], v[120:123]
	v_mfma_f32_16x16x32_bf16 v[108:111], v[146:149], v[176:179], v[108:111]
	v_mfma_f32_16x16x32_bf16 v[104:107], v[160:163], v[176:179], v[104:107]
	v_mfma_f32_16x16x32_bf16 v[92:95], v[146:149], v[200:203], v[92:95]
	v_mfma_f32_16x16x32_bf16 v[88:91], v[160:163], v[200:203], v[88:91]
	v_mfma_f32_16x16x32_bf16 v[76:79], v[146:149], v[208:211], v[76:79]
	v_mfma_f32_16x16x32_bf16 v[72:75], v[160:163], v[208:211], v[72:75]
	v_mfma_f32_16x16x32_bf16 v[116:119], v[212:215], v[164:167], v[116:119]
	v_mfma_f32_16x16x32_bf16 v[112:115], v[220:223], v[164:167], v[112:115]
	v_mfma_f32_16x16x32_bf16 v[100:103], v[212:215], v[172:175], v[100:103]
	v_mfma_f32_16x16x32_bf16 v[96:99], v[220:223], v[172:175], v[96:99]
	v_mfma_f32_16x16x32_bf16 v[84:87], v[212:215], v[196:199], v[84:87]
	v_mfma_f32_16x16x32_bf16 v[80:83], v[220:223], v[196:199], v[80:83]
	v_mfma_f32_16x16x32_bf16 v[68:71], v[212:215], v[204:207], v[68:71]
	v_mfma_f32_16x16x32_bf16 v[64:67], v[220:223], v[204:207], v[64:67]
	v_mfma_f32_16x16x32_bf16 v[116:119], v[216:219], v[168:171], v[116:119]
	v_mfma_f32_16x16x32_bf16 v[112:115], v[224:227], v[168:171], v[112:115]
	v_mfma_f32_16x16x32_bf16 v[100:103], v[216:219], v[176:179], v[100:103]
	v_mfma_f32_16x16x32_bf16 v[96:99], v[224:227], v[176:179], v[96:99]
	v_mfma_f32_16x16x32_bf16 v[84:87], v[216:219], v[200:203], v[84:87]
	v_mfma_f32_16x16x32_bf16 v[80:83], v[224:227], v[200:203], v[80:83]
	v_mfma_f32_16x16x32_bf16 v[68:71], v[216:219], v[208:211], v[68:71]
	v_mfma_f32_16x16x32_bf16 v[64:67], v[224:227], v[208:211], v[64:67]
	s_barrier
	ds_read_b128 v[164:167], v158 offset:49152
	ds_read_b128 v[168:171], v158 offset:50176
	ds_read_b128 v[172:175], v158 offset:51200
	ds_read_b128 v[176:179], v158 offset:52224
	ds_read_b128 v[196:199], v158 offset:53248
	ds_read_b128 v[200:203], v158 offset:54272
	ds_read_b128 v[204:207], v158 offset:55296
	ds_read_b128 v[208:211], v158 offset:56320
	s_add_i32 s20, 0, 0x1c000
	s_add_i32 s21, s51, s34
	s_mov_b32 m0, s21
	s_nop 0
	global_load_lds_dwordx4 v136, vcc
	s_add_i32 m0, s21, 0x2000
	s_nop 0
	global_load_lds_dwordx4 v132, vcc
	s_mov_b32 m0, s46
	s_nop 0
	global_load_lds_dwordx4 v138, s[100:101]
	s_mov_b32 m0, s47
	s_nop 0
	global_load_lds_dwordx4 v134, s[100:101]
	s_add_u32 s4, s4, 0x40080
	s_addc_u32 s5, s5, 0
	s_add_i32 s20, s20, s34
	s_mov_b32 m0, s20
	s_nop 0
	global_load_lds_dwordx4 v136, s[4:5]
	s_add_i32 m0, s20, 0x2000
	s_nop 0
	global_load_lds_dwordx4 v132, s[4:5]
	s_add_i32 s50, s50, 2
	s_add_u32 s2, s2, 0x100
	s_addc_u32 s3, s3, 0
	s_add_u32 s37, s37, 0x100
	s_addc_u32 s49, s49, 0
	s_cmp_gt_u32 s50, 13
	s_waitcnt vmcnt(8)
	s_waitcnt lgkmcnt(0)
	s_barrier
; #define PG8_STAGE(bufoff, gbase, voff) do { _Pragma("unroll") for (int _i = 0; _i < 2; ++_i) \
;     __builtin_amdgcn_global_load_lds((const unsigned*)((const char*)(gbase) + (voff)[_i]), (LAS unsigned*)(lds + (bufoff) + ldsw + _i * 8192), 16, 0, 0); } while (0)
; #define PG8_MMA(ai, bj, At, Bt) do { __builtin_amdgcn_s_setprio(1); _Pragma("unroll") for (int m = 0; m < 4; ++m) _Pragma("unroll") for (int n = 0; n < 2; ++n) _Pragma("unroll") for (int k = 0; k < 2; ++k) \
;     acc[ai][bj][m][n] = __builtin_amdgcn_mfma_f32_16x16x32_bf16(Bt[n][k], At[m][k], acc[ai][bj][m][n], 0, 0, 0); __builtin_amdgcn_s_setprio(0); } while (0)
; #define PG8_WAIT_V(n) asm volatile("s_waitcnt vmcnt(" #n ")" ::: "memory")
; #define PG8_WAIT_L(n) asm volatile("s_waitcnt lgkmcnt(" #n ")" ::: "memory")
; #define PG8_BAR __builtin_amdgcn_s_barrier()
; #define PG8_SCHED __builtin_amdgcn_sched_barrier(0)
; template <class Epi, class Sched>
; DI void gemm_phase(LAS unsigned char* lds, const Gemm g, const Sched& S, const Epi& E) {
;     ...
;       PG8_BAR; PG8_WAIT_L(0); PG8_MMA(1, 0, At, B0); PG8_BAR; PG8_SCHED;
;       PG8_STAGE(PG8_SB(1, 1), b3 + hstep, voffB);
;       PG8_WAIT_V(6); PG8_BAR; PG8_MMA(1, 1, At, B1); PG8_BAR;
;     }
;   DI void operator()(const f32x4 (&acc)[2][2][4][2], const pg8::Unit& u, int wr, int wc, int fr_, int fq_) const {
;     ...
;             } else if (EPI == EPI_CIN) {
;               if (n == 0) {
;                 const int gb = u.pn * 256 + bj * 128 + wc * 32;
;                 const int f8 = gb + 8 * fq;
;                 const f32x4 v1 = acc[ai][bj][m][1];
;                 if (gb < 1024) st_bf8((u16*)(big + O_QD) + (size_t)token * 1024 + f8, v, v1, rinv * (0.125f * LOG2E));
;                 else if (gb < 2048) st_bf8((u16*)(big + O_KD) + (size_t)token * 1024 + (f8 - 1024), v, v1, rinv);
;                 else st_bf8((u16*)(big + O_VDT) + (size_t)token * 1024 + (f8 - 2048), v, v1, rinv);
;               }
	v_mfma_f32_16x16x32_bf16 v[60:63], v[128:131], v[164:167], v[60:63]
	v_mfma_f32_16x16x32_bf16 v[56:59], v[150:153], v[164:167], v[56:59]
	v_mfma_f32_16x16x32_bf16 v[44:47], v[128:131], v[172:175], v[44:47]
	v_mfma_f32_16x16x32_bf16 v[40:43], v[150:153], v[172:175], v[40:43]
	v_mfma_f32_16x16x32_bf16 v[28:31], v[128:131], v[196:199], v[28:31]
	v_mfma_f32_16x16x32_bf16 v[24:27], v[150:153], v[196:199], v[24:27]
	v_mfma_f32_16x16x32_bf16 v[12:15], v[128:131], v[204:207], v[12:15]
	v_mfma_f32_16x16x32_bf16 v[8:11], v[150:153], v[204:207], v[8:11]
	v_mfma_f32_16x16x32_bf16 v[60:63], v[146:149], v[168:171], v[60:63]
	v_mfma_f32_16x16x32_bf16 v[56:59], v[160:163], v[168:171], v[56:59]
	v_mfma_f32_16x16x32_bf16 v[44:47], v[146:149], v[176:179], v[44:47]
	v_mfma_f32_16x16x32_bf16 v[40:43], v[160:163], v[176:179], v[40:43]
	v_mfma_f32_16x16x32_bf16 v[28:31], v[146:149], v[200:203], v[28:31]
	v_mfma_f32_16x16x32_bf16 v[24:27], v[160:163], v[200:203], v[24:27]
	v_mfma_f32_16x16x32_bf16 v[12:15], v[146:149], v[208:211], v[12:15]
	v_mfma_f32_16x16x32_bf16 v[8:11], v[160:163], v[208:211], v[8:11]
	v_mfma_f32_16x16x32_bf16 v[52:55], v[212:215], v[164:167], v[52:55]
	v_mfma_f32_16x16x32_bf16 v[48:51], v[220:223], v[164:167], v[48:51]
	v_mfma_f32_16x16x32_bf16 v[36:39], v[212:215], v[172:175], v[36:39]
	v_mfma_f32_16x16x32_bf16 v[32:35], v[220:223], v[172:175], v[32:35]
	v_mfma_f32_16x16x32_bf16 v[20:23], v[212:215], v[196:199], v[20:23]
	v_mfma_f32_16x16x32_bf16 v[16:19], v[220:223], v[196:199], v[16:19]
	v_mfma_f32_16x16x32_bf16 v[4:7], v[212:215], v[204:207], v[4:7]
	v_mfma_f32_16x16x32_bf16 v[0:3], v[220:223], v[204:207], v[0:3]
	v_mfma_f32_16x16x32_bf16 v[52:55], v[216:219], v[168:171], v[52:55]
	v_mfma_f32_16x16x32_bf16 v[48:51], v[224:227], v[168:171], v[48:51]
	v_mfma_f32_16x16x32_bf16 v[36:39], v[216:219], v[176:179], v[36:39]
	v_mfma_f32_16x16x32_bf16 v[32:35], v[224:227], v[176:179], v[32:35]
	v_mfma_f32_16x16x32_bf16 v[20:23], v[216:219], v[200:203], v[20:23]
	v_mfma_f32_16x16x32_bf16 v[16:19], v[224:227], v[200:203], v[16:19]
	v_mfma_f32_16x16x32_bf16 v[4:7], v[216:219], v[208:211], v[4:7]
	v_mfma_f32_16x16x32_bf16 v[0:3], v[224:227], v[208:211], v[0:3]
	s_barrier
	s_cbranch_scc0 .LBB0_370
	v_mov_b32_e32 v128, v182
	s_lshl_b32 s2, s22, 10
	v_and_or_b32 v160, v128, 15, s44
	v_lshrrev_b32_e32 v128, 1, v128
	s_add_i32 s2, s2, 0
	v_and_b32_e32 v146, 24, v128
	v_lshl_add_u32 v128, v160, 2, s2
	v_add_u32_e32 v159, 0x20000, v128
	s_lshl_b32 s13, s28, 8
	s_lshl_b32 s3, s23, 8
	ds_read_b32 v154, v159
	v_add_u32_e32 v150, s13, v160
	s_or_b32 s20, s3, s45
	v_ashrrev_i32_e32 v151, 31, v150
	s_cmpk_gt_i32 s20, 0x3ff
	v_lshlrev_b64 v[128:129], 11, v[150:151]
	v_or_b32_e32 v148, s20, v146
	s_cselect_b64 s[4:5], -1, 0
	s_cmpk_gt_u32 s3, 0x7ff
	s_cselect_b64 s[2:3], -1, 0
	v_mov_b32_e32 v144, v148
	v_lshl_add_u64 v[152:153], s[10:11], 0, v[128:129]
	s_mov_b64 s[22:23], -1
	s_and_b64 vcc, exec, s[4:5]
	s_cbranch_vccz .LBB0_377
	s_waitcnt lgkmcnt(0)
	v_pk_mul_f32 v[128:129], v[124:125], v[154:155] op_sel_hi:[1,0]
	v_pk_mul_f32 v[130:131], v[126:127], v[154:155] op_sel_hi:[1,0]
	v_cvt_pk_bf16_f32 v128, v128, v129
	v_cvt_pk_bf16_f32 v129, v130, v131
	v_pk_mul_f32 v[130:131], v[120:121], v[154:155] op_sel_hi:[1,0]
	v_pk_mul_f32 v[162:163], v[122:123], v[154:155] op_sel_hi:[1,0]
	v_lshl_add_u64 v[156:157], v[144:145], 1, v[152:153]
	v_cvt_pk_bf16_f32 v130, v130, v131
	v_cvt_pk_bf16_f32 v131, v162, v163
	s_and_b64 vcc, exec, s[2:3]
	s_cbranch_vccz .LBB0_374
	v_add_co_u32_e32 v162, vcc, 0x7fff000, v156
	s_mov_b64 s[22:23], 0
	s_nop 0
	v_addc_co_u32_e32 v163, vcc, 0, v157, vcc
	global_store_dwordx4 v[162:163], v[128:131], off

; #define PG8_STAGE(bufoff, gbase, voff) do { _Pragma("unroll") for (int _i = 0; _i < 2; ++_i) \
;     __builtin_amdgcn_global_load_lds((const unsigned*)((const char*)(gbase) + (voff)[_i]), (LAS unsigned*)(lds + (bufoff) + ldsw + _i * 8192), 16, 0, 0); } while (0)
; #define PG8_WAIT_V(n) asm volatile("s_waitcnt vmcnt(" #n ")" ::: "memory")
; #define PG8_BAR __builtin_amdgcn_s_barrier()
; template <class Epi, class Sched>
; DI void gemm_phase(LAS unsigned char* lds, const Gemm g, const Sched& S, const Epi& E) {
;     ...
;   for (int i = 0; i < 2; ++i) { int R, C; stage_rc(tid * 16 + i * 8192, R, C); const int Rb = Epi::PERM ? ((R & ~31) + perm32(R & 31)) : R;
;     voffA[i] = (unsigned)(R * K + C) * 2u; voffB[i] = (unsigned)(Rb * K + C) * 2u; }
;   const size_t kstep = (size_t)(BK * 2);
;   const size_t hstep = (size_t)HALF * K * 2;
;   const size_t tstep = 2 * hstep;
;   const unsigned ldsw = (unsigned)wid * 1024u;
;   const int aoff = lds_byte(wr * 64 + fr, fq * 8), boff = lds_byte(wc * 32 + fr, fq * 8);
;     ...
;   Unit cur, nxt; int ui = 0;
;   if (!S.next(0, cur)) return;
;   f32x4 acc[2][2][4][2];
; #pragma unroll
;   for (int a = 0; a < 2; ++a)
; #pragma unroll
;     for (int b = 0; b < 2; ++b)
; #pragma unroll
;       for (int m = 0; m < 4; ++m)
; #pragma unroll
;         for (int n = 0; n < 2; ++n) acc[a][b][m][n] = (f32x4){0.f, 0.f, 0.f, 0.f};
;   bf16x8 At[4][2], B0[2][2], B1[2][2];
;   const char* cA = (const char*)g.A + (size_t)cur.pm * tstep; const char* cB = (const char*)g.Bt + (size_t)cur.pn * tstep;
;   PG8_STAGE(PG8_SB(0, 0), cB, voffB); PG8_STAGE(PG8_SA(0, 0), cA, voffA); PG8_STAGE(PG8_SB(0, 1), cB + hstep, voffB); PG8_STAGE(PG8_SA(0, 1), cA + hstep, voffA);
;   if (wr == 1) PG8_BAR;
;   PG8_WAIT_V(4); PG8_BAR;
;   PG8_STAGE(PG8_SB(1, 0), cB + kstep, voffB); PG8_STAGE(PG8_SA(1, 0), cA + kstep, voffA); PG8_STAGE(PG8_SB(1, 1), cB + hstep + kstep, voffB);
;   PG8_WAIT_V(6); PG8_BAR;
.LBB0_684:
	s_lshl_b32 s2, s2, 5
	s_and_b32 s61, s2, 0x60
	s_lshl_b32 s60, s3, 6
	s_lshl_b32 s14, s3, 13
	s_lshl_b32 s15, s61, 7
	s_add_u32 s2, s10, 0xa3a8100
	s_addc_u32 s3, s11, 0
	s_add_u32 s4, s10, 0x5f20000
	s_addc_u32 s5, s11, 0
	s_add_u32 s6, s10, 0x5f60000
	s_addc_u32 s7, s11, 0
	s_add_i32 m0, s56, 0x18000
	v_lshl_add_u64 v[6:7], v[6:7], 0, s[0:1]
	s_waitcnt vmcnt(4)
	s_barrier
	global_load_lds_dwordx4 v[6:7], off
	v_lshl_add_u64 v[4:5], v[4:5], 0, s[0:1]
	s_add_i32 m0, s56, 0x1a000
	s_add_i32 s62, s56, 0x8000
	s_add_i32 s63, s56, 0xa000
	global_load_lds_dwordx4 v[4:5], off
	v_lshl_add_u64 v[2:3], v[2:3], 0, s[0:1]
	s_mov_b32 m0, s62
	s_add_u32 s12, s22, 0x40080
	global_load_lds_dwordx4 v[2:3], off
	v_lshl_add_u64 v[0:1], v[0:1], 0, s[0:1]
	s_mov_b32 m0, s63
	s_addc_u32 s13, s23, 0
	global_load_lds_dwordx4 v[0:1], off
	s_add_i32 m0, s56, 0x1c000
	v_lshl_add_u64 v[0:1], s[12:13], 0, v[140:141]
	global_load_lds_dwordx4 v[0:1], off
	v_lshl_add_u64 v[0:1], s[12:13], 0, v[136:137]
	s_add_i32 m0, s56, 0x1e000
	s_movk_i32 s12, 0x3c0
	global_load_lds_dwordx4 v[0:1], off
	v_and_b32_e32 v0, 48, v8
	v_lshlrev_b32_e32 v1, 6, v8
	v_and_or_b32 v0, v1, s12, v0
	v_lshlrev_b32_e32 v1, 2, v8
	v_and_b32_e32 v1, 32, v1
	v_bitop3_b32 v2, v0, s14, v1 bitop3:0xde
	v_bitop3_b32 v196, s15, v0, v1 bitop3:0xf6
	v_lshlrev_b32_e32 v0, 14, v13
	v_and_b32_e32 v0, 0xffff8000, v0
	v_lshl_add_u32 v0, v12, 11, v0
	v_and_b32_e32 v1, 1, v13
	v_lshl_or_b32 v0, v1, 6, v0
	v_lshl_add_u32 v146, v14, 1, v0
	v_lshlrev_b32_e32 v0, 14, v9
	v_and_b32_e32 v0, 0xffff8000, v0
	v_readlane_b32 s12, v240, 32
	s_waitcnt vmcnt(6)
	v_lshl_add_u32 v0, v10, 11, v0
	v_and_b32_e32 v1, 1, v9
	v_readlane_b32 s13, v240, 33
	s_add_u32 s10, s10, 0xcba8100
	v_lshl_or_b32 v0, v1, 6, v0
	s_mov_b32 s35, s12
	v_readlane_b32 s12, v240, 30
	s_addc_u32 s11, s11, 0
	v_mov_b32_e32 v147, v145
	v_lshl_add_u32 v148, v11, 1, v0
	v_mov_b32_e32 v149, v145
	s_mov_b32 s34, 0
	v_add_u32_e32 v197, 0, v2
	s_mov_b32 s36, s12
	s_barrier
	s_barrier
	v_readlane_b32 s13, v240, 31
	s_branch .LBB0_686

; #define PG8_STAGE(bufoff, gbase, voff) do { _Pragma("unroll") for (int _i = 0; _i < 2; ++_i) \
;     __builtin_amdgcn_global_load_lds((const unsigned*)((const char*)(gbase) + (voff)[_i]), (LAS unsigned*)(lds + (bufoff) + ldsw + _i * 8192), 16, 0, 0); } while (0)
; #define PG8_LDA(dst, b, h) do { _Pragma("unroll") for (int m = 0; m < 4; ++m) _Pragma("unroll") for (int k = 0; k < 2; ++k) dst[m][k] = *(const LAS bf16x8*)(lds + PG8_SA(b, h) + aoff + m * 2048 + k * 1024); } while (0)
; #define PG8_LDB(dst, b, h) do { _Pragma("unroll") for (int n = 0; n < 2; ++n) _Pragma("unroll") for (int k = 0; k < 2; ++k) dst[n][k] = *(const LAS bf16x8*)(lds + PG8_SB(b, h) + boff + n * 2048 + k * 1024); } while (0)
; #define PG8_MMA(ai, bj, At, Bt) do { __builtin_amdgcn_s_setprio(1); _Pragma("unroll") for (int m = 0; m < 4; ++m) _Pragma("unroll") for (int n = 0; n < 2; ++n) _Pragma("unroll") for (int k = 0; k < 2; ++k) \
;     acc[ai][bj][m][n] = __builtin_amdgcn_mfma_f32_16x16x32_bf16(Bt[n][k], At[m][k], acc[ai][bj][m][n], 0, 0, 0); __builtin_amdgcn_s_setprio(0); } while (0)
; #define PG8_WAIT_V(n) asm volatile("s_waitcnt vmcnt(" #n ")" ::: "memory")
; #define PG8_WAIT_L(n) asm volatile("s_waitcnt lgkmcnt(" #n ")" ::: "memory")
; #define PG8_BAR __builtin_amdgcn_s_barrier()
; #define PG8_SCHED __builtin_amdgcn_sched_barrier(0)
; template <class Epi, class Sched>
; DI void gemm_phase(LAS unsigned char* lds, const Gemm g, const Sched& S, const Epi& E) {
;     ...
;       PG8_LDB(B0, 0, 0); PG8_SCHED; PG8_LDA(At, 0, 0); PG8_STAGE(PG8_SA(1, 1), a1 + hstep, voffA);
;       PG8_WAIT_L(8); PG8_BAR; PG8_WAIT_L(0); PG8_MMA(0, 0, At, B0); PG8_BAR; PG8_SCHED;
;       PG8_LDB(B1, 0, 1); PG8_STAGE(PG8_SB(0, 0), b2, voffB);
;       PG8_BAR; PG8_WAIT_L(0); PG8_MMA(0, 1, At, B1); PG8_BAR;
;       PG8_LDA(At, 0, 1); PG8_STAGE(PG8_SA(0, 0), a2, voffA);
;       PG8_BAR; PG8_WAIT_L(0); PG8_MMA(1, 0, At, B0); PG8_BAR; PG8_SCHED;
;       PG8_STAGE(PG8_SB(0, 1), b2 + hstep, voffB);
;       PG8_WAIT_V(6); PG8_BAR; PG8_MMA(1, 1, At, B1); PG8_BAR;
.LBB0_689:
	ds_read_b128 v[128:131], v222
	ds_read_b128 v[132:135], v222 offset:1024
	ds_read_b128 v[150:153], v222 offset:2048
	ds_read_b128 v[154:157], v222 offset:3072
	ds_read_b128 v[158:161], v197
	ds_read_b128 v[162:165], v197 offset:1024
	ds_read_b128 v[166:169], v197 offset:2048
	ds_read_b128 v[170:173], v197 offset:3072
	ds_read_b128 v[174:177], v197 offset:4096
	ds_read_b128 v[178:181], v197 offset:5120
	ds_read_b128 v[198:201], v197 offset:6144
	ds_read_b128 v[202:205], v197 offset:7168
	ds_read_b128 v[206:209], v223
	ds_read_b128 v[210:213], v223 offset:1024
	ds_read_b128 v[214:217], v223 offset:2048
	ds_read_b128 v[218:221], v223 offset:3072
	s_add_u32 s22, s20, 0xfffc0080
	s_addc_u32 s23, s21, -1
	s_add_i32 s42, 0, 0x10000
	s_cmp_eq_u32 s41, 12
	s_cselect_b32 s29, s13, s23
	s_cselect_b32 s28, s37, s22
	s_cselect_b32 s23, s15, s40
	s_cselect_b32 s22, s38, s39
	s_add_i32 m0, s56, 0xc000
	s_nop 0
	global_load_lds_dwordx4 v146, s[20:21]
	s_add_i32 m0, s56, 0xe000
	s_nop 0
	global_load_lds_dwordx4 v148, s[20:21]
	s_waitcnt vmcnt(8)
	s_waitcnt lgkmcnt(0)
	s_barrier
	v_mfma_f32_16x16x32_bf16 v[124:127], v[128:131], v[158:161], v[124:127]
	v_mfma_f32_16x16x32_bf16 v[120:123], v[150:153], v[158:161], v[120:123]
	v_mfma_f32_16x16x32_bf16 v[108:111], v[128:131], v[166:169], v[108:111]
	v_mfma_f32_16x16x32_bf16 v[104:107], v[150:153], v[166:169], v[104:107]
	v_mfma_f32_16x16x32_bf16 v[92:95], v[128:131], v[174:177], v[92:95]
	v_mfma_f32_16x16x32_bf16 v[88:91], v[150:153], v[174:177], v[88:91]
	v_mfma_f32_16x16x32_bf16 v[76:79], v[128:131], v[198:201], v[76:79]
	v_mfma_f32_16x16x32_bf16 v[72:75], v[150:153], v[198:201], v[72:75]
	v_mfma_f32_16x16x32_bf16 v[124:127], v[132:135], v[162:165], v[124:127]
	v_mfma_f32_16x16x32_bf16 v[120:123], v[154:157], v[162:165], v[120:123]
	v_mfma_f32_16x16x32_bf16 v[108:111], v[132:135], v[170:173], v[108:111]
	v_mfma_f32_16x16x32_bf16 v[104:107], v[154:157], v[170:173], v[104:107]
	v_mfma_f32_16x16x32_bf16 v[92:95], v[132:135], v[178:181], v[92:95]
	v_mfma_f32_16x16x32_bf16 v[88:91], v[154:157], v[178:181], v[88:91]
	v_mfma_f32_16x16x32_bf16 v[76:79], v[132:135], v[202:205], v[76:79]
	v_mfma_f32_16x16x32_bf16 v[72:75], v[154:157], v[202:205], v[72:75]
	v_mfma_f32_16x16x32_bf16 v[116:119], v[206:209], v[158:161], v[116:119]
	v_mfma_f32_16x16x32_bf16 v[112:115], v[214:217], v[158:161], v[112:115]
	v_mfma_f32_16x16x32_bf16 v[100:103], v[206:209], v[166:169], v[100:103]
	v_mfma_f32_16x16x32_bf16 v[96:99], v[214:217], v[166:169], v[96:99]
	v_mfma_f32_16x16x32_bf16 v[84:87], v[206:209], v[174:177], v[84:87]
	v_mfma_f32_16x16x32_bf16 v[80:83], v[214:217], v[174:177], v[80:83]
	v_mfma_f32_16x16x32_bf16 v[68:71], v[206:209], v[198:201], v[68:71]
	v_mfma_f32_16x16x32_bf16 v[64:67], v[214:217], v[198:201], v[64:67]
	v_mfma_f32_16x16x32_bf16 v[116:119], v[210:213], v[162:165], v[116:119]
	v_mfma_f32_16x16x32_bf16 v[112:115], v[218:221], v[162:165], v[112:115]
	v_mfma_f32_16x16x32_bf16 v[100:103], v[210:213], v[170:173], v[100:103]
	v_mfma_f32_16x16x32_bf16 v[96:99], v[218:221], v[170:173], v[96:99]
	v_mfma_f32_16x16x32_bf16 v[84:87], v[210:213], v[178:181], v[84:87]
	v_mfma_f32_16x16x32_bf16 v[80:83], v[218:221], v[178:181], v[80:83]
	v_mfma_f32_16x16x32_bf16 v[68:71], v[210:213], v[202:205], v[68:71]
	v_mfma_f32_16x16x32_bf16 v[64:67], v[218:221], v[202:205], v[64:67]
	s_barrier
	ds_read_b128 v[158:161], v197 offset:16384
	ds_read_b128 v[162:165], v197 offset:17408
	ds_read_b128 v[166:169], v197 offset:18432
	ds_read_b128 v[170:173], v197 offset:19456
	ds_read_b128 v[174:177], v197 offset:20480
	ds_read_b128 v[178:181], v197 offset:21504
	ds_read_b128 v[198:201], v197 offset:22528
	ds_read_b128 v[202:205], v197 offset:23552
	s_add_i32 s44, 0, 0x14000
	s_add_i32 s42, s42, s52
	s_add_u32 vcc_lo, s22, s0
	s_addc_u32 vcc_hi, s23, s1
	s_mov_b32 m0, s42
	s_nop 0
	global_load_lds_dwordx4 v140, s[22:23]
	s_add_i32 m0, s42, 0x2000
	s_nop 0
	global_load_lds_dwordx4 v136, s[22:23]
	s_mov_b32 m0, s56
	s_add_u32 s100, s28, s0
	s_addc_u32 s101, s29, s1
	global_load_lds_dwordx4 v142, s[28:29]
	s_mov_b32 m0, s57
	s_nop 0
	global_load_lds_dwordx4 v138, s[28:29]
	s_add_u32 s42, s22, 0x40000
	s_addc_u32 s43, s23, 0
	s_add_i32 s44, s44, s52
	s_mov_b32 m0, s44
	s_nop 0
	global_load_lds_dwordx4 v140, s[42:43]
	s_add_i32 m0, s44, 0x2000
	s_nop 0
	global_load_lds_dwordx4 v136, s[42:43]
	s_add_i32 s42, 0, 0x18000
	s_waitcnt vmcnt(8)
	s_waitcnt lgkmcnt(0)
	s_barrier
	v_mfma_f32_16x16x32_bf16 v[60:63], v[128:131], v[158:161], v[60:63]
	v_mfma_f32_16x16x32_bf16 v[56:59], v[150:153], v[158:161], v[56:59]
	v_mfma_f32_16x16x32_bf16 v[44:47], v[128:131], v[166:169], v[44:47]
	v_mfma_f32_16x16x32_bf16 v[40:43], v[150:153], v[166:169], v[40:43]
	v_mfma_f32_16x16x32_bf16 v[28:31], v[128:131], v[174:177], v[28:31]
	v_mfma_f32_16x16x32_bf16 v[24:27], v[150:153], v[174:177], v[24:27]
	v_mfma_f32_16x16x32_bf16 v[12:15], v[128:131], v[198:201], v[12:15]
	v_mfma_f32_16x16x32_bf16 v[8:11], v[150:153], v[198:201], v[8:11]
	v_mfma_f32_16x16x32_bf16 v[60:63], v[132:135], v[162:165], v[60:63]
	v_mfma_f32_16x16x32_bf16 v[56:59], v[154:157], v[162:165], v[56:59]
	v_mfma_f32_16x16x32_bf16 v[44:47], v[132:135], v[170:173], v[44:47]
	v_mfma_f32_16x16x32_bf16 v[40:43], v[154:157], v[170:173], v[40:43]
	v_mfma_f32_16x16x32_bf16 v[28:31], v[132:135], v[178:181], v[28:31]
	v_mfma_f32_16x16x32_bf16 v[24:27], v[154:157], v[178:181], v[24:27]
	v_mfma_f32_16x16x32_bf16 v[12:15], v[132:135], v[202:205], v[12:15]
	v_mfma_f32_16x16x32_bf16 v[8:11], v[154:157], v[202:205], v[8:11]
	v_mfma_f32_16x16x32_bf16 v[52:55], v[206:209], v[158:161], v[52:55]
	v_mfma_f32_16x16x32_bf16 v[48:51], v[214:217], v[158:161], v[48:51]
	v_mfma_f32_16x16x32_bf16 v[36:39], v[206:209], v[166:169], v[36:39]
	v_mfma_f32_16x16x32_bf16 v[32:35], v[214:217], v[166:169], v[32:35]
	v_mfma_f32_16x16x32_bf16 v[20:23], v[206:209], v[174:177], v[20:23]
	v_mfma_f32_16x16x32_bf16 v[16:19], v[214:217], v[174:177], v[16:19]
	v_mfma_f32_16x16x32_bf16 v[4:7], v[206:209], v[198:201], v[4:7]
	v_mfma_f32_16x16x32_bf16 v[0:3], v[214:217], v[198:201], v[0:3]
	v_mfma_f32_16x16x32_bf16 v[52:55], v[210:213], v[162:165], v[52:55]
	v_mfma_f32_16x16x32_bf16 v[48:51], v[218:221], v[162:165], v[48:51]
	v_mfma_f32_16x16x32_bf16 v[36:39], v[210:213], v[170:173], v[36:39]
	v_mfma_f32_16x16x32_bf16 v[32:35], v[218:221], v[170:173], v[32:35]
	v_mfma_f32_16x16x32_bf16 v[20:23], v[210:213], v[178:181], v[20:23]
	v_mfma_f32_16x16x32_bf16 v[16:19], v[218:221], v[178:181], v[16:19]
	v_mfma_f32_16x16x32_bf16 v[4:7], v[210:213], v[202:205], v[4:7]
	v_mfma_f32_16x16x32_bf16 v[0:3], v[218:221], v[202:205], v[0:3]
	s_barrier
; #define PG8_STAGE(bufoff, gbase, voff) do { _Pragma("unroll") for (int _i = 0; _i < 2; ++_i) \
;     __builtin_amdgcn_global_load_lds((const unsigned*)((const char*)(gbase) + (voff)[_i]), (LAS unsigned*)(lds + (bufoff) + ldsw + _i * 8192), 16, 0, 0); } while (0)
; #define PG8_LDA(dst, b, h) do { _Pragma("unroll") for (int m = 0; m < 4; ++m) _Pragma("unroll") for (int k = 0; k < 2; ++k) dst[m][k] = *(const LAS bf16x8*)(lds + PG8_SA(b, h) + aoff + m * 2048 + k * 1024); } while (0)
; #define PG8_LDB(dst, b, h) do { _Pragma("unroll") for (int n = 0; n < 2; ++n) _Pragma("unroll") for (int k = 0; k < 2; ++k) dst[n][k] = *(const LAS bf16x8*)(lds + PG8_SB(b, h) + boff + n * 2048 + k * 1024); } while (0)
; #define PG8_MMA(ai, bj, At, Bt) do { __builtin_amdgcn_s_setprio(1); _Pragma("unroll") for (int m = 0; m < 4; ++m) _Pragma("unroll") for (int n = 0; n < 2; ++n) _Pragma("unroll") for (int k = 0; k < 2; ++k) \
;     acc[ai][bj][m][n] = __builtin_amdgcn_mfma_f32_16x16x32_bf16(Bt[n][k], At[m][k], acc[ai][bj][m][n], 0, 0, 0); __builtin_amdgcn_s_setprio(0); } while (0)
; #define PG8_WAIT_L(n) asm volatile("s_waitcnt lgkmcnt(" #n ")" ::: "memory")
; #define PG8_BAR __builtin_amdgcn_s_barrier()
; #define PG8_SCHED __builtin_amdgcn_sched_barrier(0)
; template <class Epi, class Sched>
; DI void gemm_phase(LAS unsigned char* lds, const Gemm g, const Sched& S, const Epi& E) {
;     ...
;       PG8_LDB(B0, 1, 0); PG8_SCHED; PG8_LDA(At, 1, 0); PG8_STAGE(PG8_SA(0, 1), a2 + hstep, voffA);
;       PG8_WAIT_L(8); PG8_BAR; PG8_WAIT_L(0); PG8_MMA(0, 0, At, B0); PG8_BAR; PG8_SCHED;
;       PG8_LDB(B1, 1, 1); PG8_STAGE(PG8_SB(1, 0), b3, voffB);
;       PG8_BAR; PG8_WAIT_L(0); PG8_MMA(0, 1, At, B1); PG8_BAR;
;       PG8_LDA(At, 1, 1); PG8_STAGE(PG8_SA(1, 0), a3, voffA);
;       PG8_BAR; PG8_WAIT_L(0); PG8_MMA(1, 0, At, B0); PG8_BAR; PG8_SCHED;
	ds_read_b128 v[128:131], v224
	ds_read_b128 v[132:135], v224 offset:1024
	ds_read_b128 v[150:153], v224 offset:2048
	ds_read_b128 v[154:157], v224 offset:3072
	ds_read_b128 v[158:161], v197 offset:32768
	ds_read_b128 v[162:165], v197 offset:33792
	ds_read_b128 v[166:169], v197 offset:34816
	ds_read_b128 v[170:173], v197 offset:35840
	ds_read_b128 v[174:177], v197 offset:36864
	ds_read_b128 v[178:181], v197 offset:37888
	ds_read_b128 v[198:201], v197 offset:38912
	ds_read_b128 v[202:205], v197 offset:39936
	ds_read_b128 v[206:209], v225
	ds_read_b128 v[210:213], v225 offset:1024
	ds_read_b128 v[214:217], v225 offset:2048
	ds_read_b128 v[218:221], v225 offset:3072
	s_add_u32 s28, s28, 0x40000
	s_addc_u32 s29, s29, 0
	s_mov_b32 m0, s58
	s_nop 0
	global_load_lds_dwordx4 v142, s[28:29]
	s_mov_b32 m0, s59
	s_nop 0
	global_load_lds_dwordx4 v138, s[28:29]
	s_waitcnt vmcnt(8)
	s_waitcnt lgkmcnt(0)
	s_barrier
	v_mfma_f32_16x16x32_bf16 v[124:127], v[128:131], v[158:161], v[124:127]
	v_mfma_f32_16x16x32_bf16 v[120:123], v[150:153], v[158:161], v[120:123]
	v_mfma_f32_16x16x32_bf16 v[108:111], v[128:131], v[166:169], v[108:111]
	v_mfma_f32_16x16x32_bf16 v[104:107], v[150:153], v[166:169], v[104:107]
	v_mfma_f32_16x16x32_bf16 v[92:95], v[128:131], v[174:177], v[92:95]
	v_mfma_f32_16x16x32_bf16 v[88:91], v[150:153], v[174:177], v[88:91]
	v_mfma_f32_16x16x32_bf16 v[76:79], v[128:131], v[198:201], v[76:79]
	v_mfma_f32_16x16x32_bf16 v[72:75], v[150:153], v[198:201], v[72:75]
	v_mfma_f32_16x16x32_bf16 v[124:127], v[132:135], v[162:165], v[124:127]
	v_mfma_f32_16x16x32_bf16 v[120:123], v[154:157], v[162:165], v[120:123]
	v_mfma_f32_16x16x32_bf16 v[108:111], v[132:135], v[170:173], v[108:111]
	v_mfma_f32_16x16x32_bf16 v[104:107], v[154:157], v[170:173], v[104:107]
	v_mfma_f32_16x16x32_bf16 v[92:95], v[132:135], v[178:181], v[92:95]
	v_mfma_f32_16x16x32_bf16 v[88:91], v[154:157], v[178:181], v[88:91]
	v_mfma_f32_16x16x32_bf16 v[76:79], v[132:135], v[202:205], v[76:79]
	v_mfma_f32_16x16x32_bf16 v[72:75], v[154:157], v[202:205], v[72:75]
	v_mfma_f32_16x16x32_bf16 v[116:119], v[206:209], v[158:161], v[116:119]
	v_mfma_f32_16x16x32_bf16 v[112:115], v[214:217], v[158:161], v[112:115]
	v_mfma_f32_16x16x32_bf16 v[100:103], v[206:209], v[166:169], v[100:103]
	v_mfma_f32_16x16x32_bf16 v[96:99], v[214:217], v[166:169], v[96:99]
	v_mfma_f32_16x16x32_bf16 v[84:87], v[206:209], v[174:177], v[84:87]
	v_mfma_f32_16x16x32_bf16 v[80:83], v[214:217], v[174:177], v[80:83]
	v_mfma_f32_16x16x32_bf16 v[68:71], v[206:209], v[198:201], v[68:71]
	v_mfma_f32_16x16x32_bf16 v[64:67], v[214:217], v[198:201], v[64:67]
	v_mfma_f32_16x16x32_bf16 v[116:119], v[210:213], v[162:165], v[116:119]
	v_mfma_f32_16x16x32_bf16 v[112:115], v[218:221], v[162:165], v[112:115]
	v_mfma_f32_16x16x32_bf16 v[100:103], v[210:213], v[170:173], v[100:103]
	v_mfma_f32_16x16x32_bf16 v[96:99], v[218:221], v[170:173], v[96:99]
	v_mfma_f32_16x16x32_bf16 v[84:87], v[210:213], v[178:181], v[84:87]
	v_mfma_f32_16x16x32_bf16 v[80:83], v[218:221], v[178:181], v[80:83]
	v_mfma_f32_16x16x32_bf16 v[68:71], v[210:213], v[202:205], v[68:71]
	v_mfma_f32_16x16x32_bf16 v[64:67], v[218:221], v[202:205], v[64:67]
	s_barrier
	ds_read_b128 v[158:161], v197 offset:49152
	ds_read_b128 v[162:165], v197 offset:50176
	ds_read_b128 v[166:169], v197 offset:51200
	ds_read_b128 v[170:173], v197 offset:52224
	ds_read_b128 v[174:177], v197 offset:53248
	ds_read_b128 v[178:181], v197 offset:54272
	ds_read_b128 v[198:201], v197 offset:55296
	ds_read_b128 v[202:205], v197 offset:56320
	s_add_i32 s28, 0, 0x1c000
	s_add_i32 s29, s42, s52
	s_mov_b32 m0, s29
	s_nop 0
	global_load_lds_dwordx4 v140, vcc
	s_add_i32 m0, s29, 0x2000
	s_nop 0
	global_load_lds_dwordx4 v136, vcc
	s_mov_b32 m0, s62
	s_nop 0
	global_load_lds_dwordx4 v142, s[100:101]
	s_mov_b32 m0, s63
	s_nop 0
	global_load_lds_dwordx4 v138, s[100:101]
	s_add_u32 s22, s22, 0x40080
	s_addc_u32 s23, s23, 0
	s_add_i32 s28, s28, s52
	s_mov_b32 m0, s28
	s_nop 0
	global_load_lds_dwordx4 v140, s[22:23]
	s_add_i32 m0, s28, 0x2000
	s_nop 0
	global_load_lds_dwordx4 v136, s[22:23]
	s_add_i32 s41, s41, 2
	s_add_u32 s20, s20, 0x100
	s_addc_u32 s21, s21, 0
	s_add_u32 s39, s39, 0x100
	s_addc_u32 s40, s40, 0
	s_cmp_gt_u32 s41, 13
	s_waitcnt vmcnt(8)
	s_waitcnt lgkmcnt(0)
	s_barrier
; #define PG8_STAGE(bufoff, gbase, voff) do { _Pragma("unroll") for (int _i = 0; _i < 2; ++_i) \
;     __builtin_amdgcn_global_load_lds((const unsigned*)((const char*)(gbase) + (voff)[_i]), (LAS unsigned*)(lds + (bufoff) + ldsw + _i * 8192), 16, 0, 0); } while (0)
; #define PG8_MMA(ai, bj, At, Bt) do { __builtin_amdgcn_s_setprio(1); _Pragma("unroll") for (int m = 0; m < 4; ++m) _Pragma("unroll") for (int n = 0; n < 2; ++n) _Pragma("unroll") for (int k = 0; k < 2; ++k) \
;     acc[ai][bj][m][n] = __builtin_amdgcn_mfma_f32_16x16x32_bf16(Bt[n][k], At[m][k], acc[ai][bj][m][n], 0, 0, 0); __builtin_amdgcn_s_setprio(0); } while (0)
; #define PG8_WAIT_V(n) asm volatile("s_waitcnt vmcnt(" #n ")" ::: "memory")
; #define PG8_WAIT_L(n) asm volatile("s_waitcnt lgkmcnt(" #n ")" ::: "memory")
; #define PG8_BAR __builtin_amdgcn_s_barrier()
; template <class Epi, class Sched>
; DI void gemm_phase(LAS unsigned char* lds, const Gemm g, const Sched& S, const Epi& E) {
;     ...
;       PG8_BAR; PG8_WAIT_L(0); PG8_MMA(1, 0, At, B0); PG8_BAR; PG8_SCHED;
;       PG8_STAGE(PG8_SB(1, 1), b3 + hstep, voffB);
;       PG8_WAIT_V(6); PG8_BAR; PG8_MMA(1, 1, At, B1); PG8_BAR;
;     }
;   DI void operator()(const f32x4 (&acc)[2][2][4][2], const pg8::Unit& u, int wr, int wc, int fr_, int fq_) const {
;     ...
;             if (EPI == EPI_ABIN) {
;               if (n == 0) {
;                 const int gb = u.pn * 256 + bj * 128 + wc * 32; const int f8 = gb + 8 * fq;
;                 const f32x4 v1 = acc[ai][bj][m][1];
;                 if (gb < 384) st_bf8((u16*)(big + E_CQ) + (size_t)token * 384 + f8, v, v1, rinv);
;                 else if (gb < 640) st_bf8((u16*)(big + E_CKV) + (size_t)token * 256 + (f8 - 384), v, v1, rinv);
;                 else if (gb < 672) {
;                   f32x4 a0 = v, a1 = v1;
;                   rope_perm(a0, a1, fq, t_ & 63, tcos, tsin, token & (S_ - 1));
;                   st_bf8((u16*)(big + E_KPE) + (size_t)token * 32 + 8 * fq, a0, a1, rinv);
;                 }
;                 else if (gb < 1184) st_bf8((u16*)(big + E_QNA) + (size_t)token * 512 + (f8 - 672), v, v1, rinv * (0.125f * LOG2E));
;                 else if (gb < 1696) st_bf8((u16*)(big + E_KNA) + (size_t)token * 512 + (f8 - 1184), v, v1, rinv);
;                 else if (gb < 2208) st_bf8((u16*)(big + E_VNAT) + (size_t)token * 512 + (f8 - 1696), v, v1, rinv);
	v_mfma_f32_16x16x32_bf16 v[60:63], v[128:131], v[158:161], v[60:63]
	v_mfma_f32_16x16x32_bf16 v[56:59], v[150:153], v[158:161], v[56:59]
	v_mfma_f32_16x16x32_bf16 v[44:47], v[128:131], v[166:169], v[44:47]
	v_mfma_f32_16x16x32_bf16 v[40:43], v[150:153], v[166:169], v[40:43]
	v_mfma_f32_16x16x32_bf16 v[28:31], v[128:131], v[174:177], v[28:31]
	v_mfma_f32_16x16x32_bf16 v[24:27], v[150:153], v[174:177], v[24:27]
	v_mfma_f32_16x16x32_bf16 v[12:15], v[128:131], v[198:201], v[12:15]
	v_mfma_f32_16x16x32_bf16 v[8:11], v[150:153], v[198:201], v[8:11]
	v_mfma_f32_16x16x32_bf16 v[60:63], v[132:135], v[162:165], v[60:63]
	v_mfma_f32_16x16x32_bf16 v[56:59], v[154:157], v[162:165], v[56:59]
	v_mfma_f32_16x16x32_bf16 v[44:47], v[132:135], v[170:173], v[44:47]
	v_mfma_f32_16x16x32_bf16 v[40:43], v[154:157], v[170:173], v[40:43]
	v_mfma_f32_16x16x32_bf16 v[28:31], v[132:135], v[178:181], v[28:31]
	v_mfma_f32_16x16x32_bf16 v[24:27], v[154:157], v[178:181], v[24:27]
	v_mfma_f32_16x16x32_bf16 v[12:15], v[132:135], v[202:205], v[12:15]
	v_mfma_f32_16x16x32_bf16 v[8:11], v[154:157], v[202:205], v[8:11]
	v_mfma_f32_16x16x32_bf16 v[52:55], v[206:209], v[158:161], v[52:55]
	v_mfma_f32_16x16x32_bf16 v[48:51], v[214:217], v[158:161], v[48:51]
	v_mfma_f32_16x16x32_bf16 v[36:39], v[206:209], v[166:169], v[36:39]
	v_mfma_f32_16x16x32_bf16 v[32:35], v[214:217], v[166:169], v[32:35]
	v_mfma_f32_16x16x32_bf16 v[20:23], v[206:209], v[174:177], v[20:23]
	v_mfma_f32_16x16x32_bf16 v[16:19], v[214:217], v[174:177], v[16:19]
	v_mfma_f32_16x16x32_bf16 v[4:7], v[206:209], v[198:201], v[4:7]
	v_mfma_f32_16x16x32_bf16 v[0:3], v[214:217], v[198:201], v[0:3]
	v_mfma_f32_16x16x32_bf16 v[52:55], v[210:213], v[162:165], v[52:55]
	v_mfma_f32_16x16x32_bf16 v[48:51], v[218:221], v[162:165], v[48:51]
	v_mfma_f32_16x16x32_bf16 v[36:39], v[210:213], v[170:173], v[36:39]
	v_mfma_f32_16x16x32_bf16 v[32:35], v[218:221], v[170:173], v[32:35]
	v_mfma_f32_16x16x32_bf16 v[20:23], v[210:213], v[178:181], v[20:23]
	v_mfma_f32_16x16x32_bf16 v[16:19], v[218:221], v[178:181], v[16:19]
	v_mfma_f32_16x16x32_bf16 v[4:7], v[210:213], v[202:205], v[4:7]
	v_mfma_f32_16x16x32_bf16 v[0:3], v[218:221], v[202:205], v[0:3]
	s_barrier
	s_cbranch_scc0 .LBB0_689
	v_mov_b32_e32 v128, v182
	s_lshl_b32 s20, s34, 10
	v_bfe_u32 v129, v128, 4, 2
	v_and_or_b32 v201, v128, 15, s60
	s_lshl_b32 s13, s35, 8
	v_lshlrev_b32_e32 v128, 2, v128
	s_movk_i32 s21, 0x80
	s_add_i32 s20, s20, 0
	s_lshl_b32 s15, s36, 8
	v_bitop3_b32 v198, v128, s21, v190 bitop3:0x6c
	v_lshl_add_u32 v128, v201, 2, s20
	s_or_b32 s20, s13, s61
	v_add_u32_e32 v200, 0x20000, v128
	s_cmpk_gt_i32 s20, 0x17f
	ds_read_b32 v156, v200
	s_cselect_b64 s[28:29], -1, 0
	s_cmpk_gt_u32 s13, 0x27f
	s_cselect_b64 s[46:47], -1, 0
	s_cmpk_gt_u32 s20, 0x29f
	s_cselect_b64 s[40:41], -1, 0
	s_cmpk_gt_u32 s20, 0x49f
	v_lshlrev_b32_e32 v144, 3, v129
	v_add_u32_e32 v154, s15, v201
	s_cselect_b64 s[34:35], -1, 0
	s_cmpk_gt_u32 s20, 0x69f
	v_ashrrev_i32_e32 v155, 31, v154
	v_lshlrev_b32_e32 v128, 4, v154
	v_or_b32_e32 v150, s20, v144
	s_cselect_b64 s[22:23], -1, 0
	s_cmpk_lt_u32 s20, 0x8a0
	v_and_b32_e32 v199, 8, v144
	v_cmp_lt_u32_e64 s[92:93], 1, v129
	v_lshlrev_b64 v[164:165], 10, v[154:155]
	s_waitcnt lgkmcnt(0)
	v_mul_f32_e32 v162, 0x3e38aa3b, v156
	v_and_b32_e32 v157, 0xfcf0, v128
	v_lshlrev_b64 v[160:161], 6, v[154:155]
	v_lshlrev_b64 v[158:159], 9, v[154:155]
	s_cselect_b64 s[20:21], -1, 0
	v_mov_b32_e32 v152, v150
	v_mov_b32_e32 v153, v145
	s_mov_b64 s[36:37], -1
	s_and_b64 vcc, exec, s[28:29]
	s_cbranch_vccz .LBB0_714
	s_and_b64 vcc, exec, s[46:47]
	s_cbranch_vccz .LBB0_711
	s_and_b64 vcc, exec, s[40:41]
	s_cbranch_vccz .LBB0_704
	s_and_b64 vcc, exec, s[34:35]
	s_cbranch_vccz .LBB0_701
	s_and_b64 vcc, exec, s[22:23]
	s_cbranch_vccz .LBB0_698
	s_andn2_b64 vcc, exec, s[20:21]
	s_cbranch_vccnz .LBB0_697
	v_lshl_add_u64 v[128:129], s[2:3], 0, v[164:165]
	v_lshl_add_u64 v[132:133], v[152:153], 1, v[128:129]
	v_pk_mul_f32 v[128:129], v[124:125], v[156:157] op_sel_hi:[1,0]
	v_pk_mul_f32 v[130:131], v[126:127], v[156:157] op_sel_hi:[1,0]
	v_cvt_pk_bf16_f32 v128, v128, v129
	v_cvt_pk_bf16_f32 v129, v130, v131
	v_pk_mul_f32 v[130:131], v[120:121], v[156:157] op_sel_hi:[1,0]
	v_pk_mul_f32 v[134:135], v[122:123], v[156:157] op_sel_hi:[1,0]
	v_add_co_u32_e32 v132, vcc, 0x69ff000, v132
	v_cvt_pk_bf16_f32 v130, v130, v131
	v_cvt_pk_bf16_f32 v131, v134, v135
	v_addc_co_u32_e32 v133, vcc, 0, v133, vcc
	global_store_dwordx4 v[132:133], v[128:131], off offset:704

; #define PG8_STAGE(bufoff, gbase, voff) do { _Pragma("unroll") for (int _i = 0; _i < 2; ++_i) \
;     __builtin_amdgcn_global_load_lds((const unsigned*)((const char*)(gbase) + (voff)[_i]), (LAS unsigned*)(lds + (bufoff) + ldsw + _i * 8192), 16, 0, 0); } while (0)
; #define PG8_WAIT_V(n) asm volatile("s_waitcnt vmcnt(" #n ")" ::: "memory")
; #define PG8_BAR __builtin_amdgcn_s_barrier()
; template <class Epi, class Sched>
; DI void gemm_phase(LAS unsigned char* lds, const Gemm g, const Sched& S, const Epi& E) {
;     ...
;   for (int i = 0; i < 2; ++i) { int R, C; stage_rc(tid * 16 + i * 8192, R, C); const int Rb = Epi::PERM ? ((R & ~31) + perm32(R & 31)) : R;
;     voffA[i] = (unsigned)(R * K + C) * 2u; voffB[i] = (unsigned)(Rb * K + C) * 2u; }
;   const size_t kstep = (size_t)(BK * 2);
;   const size_t hstep = (size_t)HALF * K * 2;
;   const size_t tstep = 2 * hstep;
;   const unsigned ldsw = (unsigned)wid * 1024u;
;   const int aoff = lds_byte(wr * 64 + fr, fq * 8), boff = lds_byte(wc * 32 + fr, fq * 8);
;     ...
;   Unit cur, nxt; int ui = 0;
;   if (!S.next(0, cur)) return;
;   f32x4 acc[2][2][4][2];
; #pragma unroll
;   for (int a = 0; a < 2; ++a)
; #pragma unroll
;     for (int b = 0; b < 2; ++b)
; #pragma unroll
;       for (int m = 0; m < 4; ++m)
; #pragma unroll
;         for (int n = 0; n < 2; ++n) acc[a][b][m][n] = (f32x4){0.f, 0.f, 0.f, 0.f};
;   bf16x8 At[4][2], B0[2][2], B1[2][2];
;   const char* cA = (const char*)g.A + (size_t)cur.pm * tstep; const char* cB = (const char*)g.Bt + (size_t)cur.pn * tstep;
;   PG8_STAGE(PG8_SB(0, 0), cB, voffB); PG8_STAGE(PG8_SA(0, 0), cA, voffA); PG8_STAGE(PG8_SB(0, 1), cB + hstep, voffB); PG8_STAGE(PG8_SA(0, 1), cA + hstep, voffA);
;   if (wr == 1) PG8_BAR;
;   PG8_WAIT_V(4); PG8_BAR;
;   PG8_STAGE(PG8_SB(1, 0), cB + kstep, voffB); PG8_STAGE(PG8_SA(1, 0), cA + kstep, voffA); PG8_STAGE(PG8_SB(1, 1), cB + hstep + kstep, voffB);
;   PG8_WAIT_V(6); PG8_BAR;
.LBB0_1192:
	v_and_b32_e32 v17, 48, v16
	v_lshlrev_b32_e32 v18, 6, v16
	s_movk_i32 s4, 0x3c0
	v_lshlrev_b32_e32 v16, 2, v16
	s_lshl_b32 s42, s2, 6
	s_lshl_b32 s2, s2, 13
	v_and_or_b32 v17, v18, s4, v17
	v_and_b32_e32 v16, 32, v16
	v_bitop3_b32 v18, v17, s2, v16 bitop3:0xde
	s_lshl_b32 s2, s3, 5
	s_and_b32 s43, s2, 0x60
	s_lshl_b32 s2, s43, 7
	s_add_u32 s12, s9, 0x5f20000
	s_addc_u32 s13, s24, 0
	s_add_u32 s14, s9, 0x5f60000
	s_addc_u32 s15, s24, 0
	s_add_i32 m0, s38, 0x18000
	v_lshl_add_u64 v[6:7], v[6:7], 0, s[0:1]
	s_waitcnt vmcnt(4)
	s_barrier
	global_load_lds_dwordx4 v[6:7], off
	v_lshl_add_u64 v[4:5], v[4:5], 0, s[0:1]
	s_add_i32 m0, s38, 0x1a000
	s_add_i32 s44, s38, 0x8000
	s_add_i32 s45, s38, 0xa000
	v_bitop3_b32 v162, s2, v17, v16 bitop3:0xf6
	global_load_lds_dwordx4 v[4:5], off
	v_lshl_add_u64 v[2:3], v[2:3], 0, s[0:1]
	s_mov_b32 m0, s44
	s_add_u32 s2, s20, 0x18080
	global_load_lds_dwordx4 v[2:3], off
	v_lshl_add_u64 v[0:1], v[0:1], 0, s[0:1]
	s_mov_b32 m0, s45
	s_addc_u32 s3, s21, 0
	global_load_lds_dwordx4 v[0:1], off
	s_add_i32 m0, s38, 0x1c000
	v_lshl_add_u64 v[0:1], s[2:3], 0, v[130:131]
	global_load_lds_dwordx4 v[0:1], off
	v_lshl_add_u64 v[0:1], s[2:3], 0, v[134:135]
	s_add_i32 m0, s38, 0x1e000
	s_movk_i32 s4, 0x180
	global_load_lds_dwordx4 v[0:1], off
	v_lshrrev_b32_e32 v1, 1, v8
	v_mul_lo_u32 v0, v10, s4
	s_movk_i32 s5, 0x1800
	v_mad_u64_u32 v[0:1], s[2:3], v1, s5, v[0:1]
	v_or_b32_e32 v0, v0, v9
	v_add_lshl_u32 v144, v0, v11, 1
	v_lshrrev_b32_e32 v1, 1, v12
	v_mul_lo_u32 v0, v14, s4
	v_mad_u64_u32 v[0:1], s[2:3], v1, s5, v[0:1]
	s_waitcnt vmcnt(6)
	s_mov_b64 s[22:23], 0x18080
	v_or_b32_e32 v0, v0, v13
	s_add_u32 s16, s9, 0x12da8100
	v_lshl_add_u64 v[136:137], v[144:145], 0, s[22:23]
	v_add_lshl_u32 v144, v0, v15, 1
	s_addc_u32 s17, s24, 0
	v_lshl_add_u64 v[138:139], v[144:145], 0, s[22:23]
	s_mov_b32 s51, 0
	v_add_u32_e32 v163, 0, v18
	s_barrier
	s_barrier
	s_branch .LBB0_1195

; #define PG8_STAGE(bufoff, gbase, voff) do { _Pragma("unroll") for (int _i = 0; _i < 2; ++_i) \
;     __builtin_amdgcn_global_load_lds((const unsigned*)((const char*)(gbase) + (voff)[_i]), (LAS unsigned*)(lds + (bufoff) + ldsw + _i * 8192), 16, 0, 0); } while (0)
; #define PG8_LDA(dst, b, h) do { _Pragma("unroll") for (int m = 0; m < 4; ++m) _Pragma("unroll") for (int k = 0; k < 2; ++k) dst[m][k] = *(const LAS bf16x8*)(lds + PG8_SA(b, h) + aoff + m * 2048 + k * 1024); } while (0)
; #define PG8_LDB(dst, b, h) do { _Pragma("unroll") for (int n = 0; n < 2; ++n) _Pragma("unroll") for (int k = 0; k < 2; ++k) dst[n][k] = *(const LAS bf16x8*)(lds + PG8_SB(b, h) + boff + n * 2048 + k * 1024); } while (0)
; #define PG8_MMA(ai, bj, At, Bt) do { __builtin_amdgcn_s_setprio(1); _Pragma("unroll") for (int m = 0; m < 4; ++m) _Pragma("unroll") for (int n = 0; n < 2; ++n) _Pragma("unroll") for (int k = 0; k < 2; ++k) \
;     acc[ai][bj][m][n] = __builtin_amdgcn_mfma_f32_16x16x32_bf16(Bt[n][k], At[m][k], acc[ai][bj][m][n], 0, 0, 0); __builtin_amdgcn_s_setprio(0); } while (0)
; #define PG8_WAIT_V(n) asm volatile("s_waitcnt vmcnt(" #n ")" ::: "memory")
; #define PG8_WAIT_L(n) asm volatile("s_waitcnt lgkmcnt(" #n ")" ::: "memory")
; #define PG8_BAR __builtin_amdgcn_s_barrier()
; #define PG8_SCHED __builtin_amdgcn_sched_barrier(0)
; template <class Epi, class Sched>
; DI void gemm_phase(LAS unsigned char* lds, const Gemm g, const Sched& S, const Epi& E) {
;     ...
;       PG8_LDB(B0, 0, 0); PG8_SCHED; PG8_LDA(At, 0, 0); PG8_STAGE(PG8_SA(1, 1), a1 + hstep, voffA);
;       PG8_WAIT_L(8); PG8_BAR; PG8_WAIT_L(0); PG8_MMA(0, 0, At, B0); PG8_BAR; PG8_SCHED;
;       PG8_LDB(B1, 0, 1); PG8_STAGE(PG8_SB(0, 0), b2, voffB);
;       PG8_BAR; PG8_WAIT_L(0); PG8_MMA(0, 1, At, B1); PG8_BAR;
;       PG8_LDA(At, 0, 1); PG8_STAGE(PG8_SA(0, 0), a2, voffA);
;       PG8_BAR; PG8_WAIT_L(0); PG8_MMA(1, 0, At, B0); PG8_BAR; PG8_SCHED;
;       PG8_STAGE(PG8_SB(0, 1), b2 + hstep, voffB);
;       PG8_WAIT_V(6); PG8_BAR; PG8_MMA(1, 1, At, B1); PG8_BAR;
.LBB0_1202:
	ds_read_b128 v[140:143], v224
	ds_read_b128 v[146:149], v224 offset:1024
	ds_read_b128 v[150:153], v224 offset:2048
	ds_read_b128 v[154:157], v224 offset:3072
	ds_read_b128 v[158:161], v163
	ds_read_b128 v[164:167], v163 offset:1024
	ds_read_b128 v[168:171], v163 offset:2048
	ds_read_b128 v[172:175], v163 offset:3072
	ds_read_b128 v[176:179], v163 offset:4096
	ds_read_b128 v[196:199], v163 offset:5120
	ds_read_b128 v[200:203], v163 offset:6144
	ds_read_b128 v[204:207], v163 offset:7168
	ds_read_b128 v[208:211], v225
	ds_read_b128 v[212:215], v225 offset:1024
	ds_read_b128 v[216:219], v225 offset:2048
	ds_read_b128 v[220:223], v225 offset:3072
	s_add_u32 s20, s18, 0x100
	s_addc_u32 s21, s19, 0
	s_add_i32 s55, 0, 0x10000
	s_cmp_eq_u32 s54, 2
	s_cselect_b32 s29, s3, s21
	s_cselect_b32 s28, s2, s20
	s_cselect_b32 s23, s5, s53
	s_cselect_b32 s22, s4, s52
	s_add_i32 m0, s38, 0xc000
	s_nop 0
	global_load_lds_dwordx4 v136, s[18:19]
	s_add_i32 m0, s38, 0xe000
	s_nop 0
	global_load_lds_dwordx4 v138, s[18:19]
	s_waitcnt vmcnt(8)
	s_waitcnt lgkmcnt(0)
	s_barrier
	v_mfma_f32_16x16x32_bf16 v[124:127], v[140:143], v[158:161], v[124:127]
	v_mfma_f32_16x16x32_bf16 v[120:123], v[150:153], v[158:161], v[120:123]
	v_mfma_f32_16x16x32_bf16 v[108:111], v[140:143], v[168:171], v[108:111]
	v_mfma_f32_16x16x32_bf16 v[104:107], v[150:153], v[168:171], v[104:107]
	v_mfma_f32_16x16x32_bf16 v[92:95], v[140:143], v[176:179], v[92:95]
	v_mfma_f32_16x16x32_bf16 v[88:91], v[150:153], v[176:179], v[88:91]
	v_mfma_f32_16x16x32_bf16 v[76:79], v[140:143], v[200:203], v[76:79]
	v_mfma_f32_16x16x32_bf16 v[72:75], v[150:153], v[200:203], v[72:75]
	v_mfma_f32_16x16x32_bf16 v[124:127], v[146:149], v[164:167], v[124:127]
	v_mfma_f32_16x16x32_bf16 v[120:123], v[154:157], v[164:167], v[120:123]
	v_mfma_f32_16x16x32_bf16 v[108:111], v[146:149], v[172:175], v[108:111]
	v_mfma_f32_16x16x32_bf16 v[104:107], v[154:157], v[172:175], v[104:107]
	v_mfma_f32_16x16x32_bf16 v[92:95], v[146:149], v[196:199], v[92:95]
	v_mfma_f32_16x16x32_bf16 v[88:91], v[154:157], v[196:199], v[88:91]
	v_mfma_f32_16x16x32_bf16 v[76:79], v[146:149], v[204:207], v[76:79]
	v_mfma_f32_16x16x32_bf16 v[72:75], v[154:157], v[204:207], v[72:75]
	v_mfma_f32_16x16x32_bf16 v[116:119], v[208:211], v[158:161], v[116:119]
	v_mfma_f32_16x16x32_bf16 v[112:115], v[216:219], v[158:161], v[112:115]
	v_mfma_f32_16x16x32_bf16 v[100:103], v[208:211], v[168:171], v[100:103]
	v_mfma_f32_16x16x32_bf16 v[96:99], v[216:219], v[168:171], v[96:99]
	v_mfma_f32_16x16x32_bf16 v[84:87], v[208:211], v[176:179], v[84:87]
	v_mfma_f32_16x16x32_bf16 v[80:83], v[216:219], v[176:179], v[80:83]
	v_mfma_f32_16x16x32_bf16 v[68:71], v[208:211], v[200:203], v[68:71]
	v_mfma_f32_16x16x32_bf16 v[64:67], v[216:219], v[200:203], v[64:67]
	v_mfma_f32_16x16x32_bf16 v[116:119], v[212:215], v[164:167], v[116:119]
	v_mfma_f32_16x16x32_bf16 v[112:115], v[220:223], v[164:167], v[112:115]
	v_mfma_f32_16x16x32_bf16 v[100:103], v[212:215], v[172:175], v[100:103]
	v_mfma_f32_16x16x32_bf16 v[96:99], v[220:223], v[172:175], v[96:99]
	v_mfma_f32_16x16x32_bf16 v[84:87], v[212:215], v[196:199], v[84:87]
	v_mfma_f32_16x16x32_bf16 v[80:83], v[220:223], v[196:199], v[80:83]
	v_mfma_f32_16x16x32_bf16 v[68:71], v[212:215], v[204:207], v[68:71]
	v_mfma_f32_16x16x32_bf16 v[64:67], v[220:223], v[204:207], v[64:67]
	s_barrier
	ds_read_b128 v[158:161], v163 offset:16384
	ds_read_b128 v[164:167], v163 offset:17408
	ds_read_b128 v[168:171], v163 offset:18432
	ds_read_b128 v[172:175], v163 offset:19456
	ds_read_b128 v[176:179], v163 offset:20480
	ds_read_b128 v[196:199], v163 offset:21504
	ds_read_b128 v[200:203], v163 offset:22528
	ds_read_b128 v[204:207], v163 offset:23552
	s_add_i32 s56, 0, 0x14000
	s_add_i32 s18, s55, s35
	s_add_u32 vcc_lo, s22, s0
	s_addc_u32 vcc_hi, s23, s1
	s_mov_b32 m0, s18
	s_nop 0
	global_load_lds_dwordx4 v130, s[22:23]
	s_add_i32 m0, s18, 0x2000
	s_nop 0
	global_load_lds_dwordx4 v134, s[22:23]
	s_mov_b32 m0, s38
	s_add_u32 s100, s28, s0
	s_addc_u32 s101, s29, s1
	global_load_lds_dwordx4 v128, s[28:29]
	s_mov_b32 m0, s39
	s_nop 0
	global_load_lds_dwordx4 v132, s[28:29]
	s_add_u32 s18, s22, 0x18000
	s_addc_u32 s19, s23, 0
	s_add_i32 s55, s56, s35
	s_mov_b32 m0, s55
	s_nop 0
	global_load_lds_dwordx4 v130, s[18:19]
	s_add_i32 m0, s55, 0x2000
	s_nop 0
	global_load_lds_dwordx4 v134, s[18:19]
	s_add_i32 s55, 0, 0x18000
	s_waitcnt vmcnt(8)
	s_waitcnt lgkmcnt(0)
	s_barrier
	v_mfma_f32_16x16x32_bf16 v[60:63], v[140:143], v[158:161], v[60:63]
	v_mfma_f32_16x16x32_bf16 v[56:59], v[150:153], v[158:161], v[56:59]
	v_mfma_f32_16x16x32_bf16 v[44:47], v[140:143], v[168:171], v[44:47]
	v_mfma_f32_16x16x32_bf16 v[40:43], v[150:153], v[168:171], v[40:43]
	v_mfma_f32_16x16x32_bf16 v[28:31], v[140:143], v[176:179], v[28:31]
	v_mfma_f32_16x16x32_bf16 v[24:27], v[150:153], v[176:179], v[24:27]
	v_mfma_f32_16x16x32_bf16 v[12:15], v[140:143], v[200:203], v[12:15]
	v_mfma_f32_16x16x32_bf16 v[8:11], v[150:153], v[200:203], v[8:11]
	v_mfma_f32_16x16x32_bf16 v[60:63], v[146:149], v[164:167], v[60:63]
	v_mfma_f32_16x16x32_bf16 v[56:59], v[154:157], v[164:167], v[56:59]
	v_mfma_f32_16x16x32_bf16 v[44:47], v[146:149], v[172:175], v[44:47]
	v_mfma_f32_16x16x32_bf16 v[40:43], v[154:157], v[172:175], v[40:43]
	v_mfma_f32_16x16x32_bf16 v[28:31], v[146:149], v[196:199], v[28:31]
	v_mfma_f32_16x16x32_bf16 v[24:27], v[154:157], v[196:199], v[24:27]
	v_mfma_f32_16x16x32_bf16 v[12:15], v[146:149], v[204:207], v[12:15]
	v_mfma_f32_16x16x32_bf16 v[8:11], v[154:157], v[204:207], v[8:11]
	v_mfma_f32_16x16x32_bf16 v[52:55], v[208:211], v[158:161], v[52:55]
	v_mfma_f32_16x16x32_bf16 v[48:51], v[216:219], v[158:161], v[48:51]
	v_mfma_f32_16x16x32_bf16 v[36:39], v[208:211], v[168:171], v[36:39]
	v_mfma_f32_16x16x32_bf16 v[32:35], v[216:219], v[168:171], v[32:35]
	v_mfma_f32_16x16x32_bf16 v[20:23], v[208:211], v[176:179], v[20:23]
	v_mfma_f32_16x16x32_bf16 v[16:19], v[216:219], v[176:179], v[16:19]
	v_mfma_f32_16x16x32_bf16 v[4:7], v[208:211], v[200:203], v[4:7]
	v_mfma_f32_16x16x32_bf16 v[0:3], v[216:219], v[200:203], v[0:3]
	v_mfma_f32_16x16x32_bf16 v[52:55], v[212:215], v[164:167], v[52:55]
	v_mfma_f32_16x16x32_bf16 v[48:51], v[220:223], v[164:167], v[48:51]
	v_mfma_f32_16x16x32_bf16 v[36:39], v[212:215], v[172:175], v[36:39]
	v_mfma_f32_16x16x32_bf16 v[32:35], v[220:223], v[172:175], v[32:35]
	v_mfma_f32_16x16x32_bf16 v[20:23], v[212:215], v[196:199], v[20:23]
	v_mfma_f32_16x16x32_bf16 v[16:19], v[220:223], v[196:199], v[16:19]
	v_mfma_f32_16x16x32_bf16 v[4:7], v[212:215], v[204:207], v[4:7]
	v_mfma_f32_16x16x32_bf16 v[0:3], v[220:223], v[204:207], v[0:3]
	s_barrier
; #define PG8_STAGE(bufoff, gbase, voff) do { _Pragma("unroll") for (int _i = 0; _i < 2; ++_i) \
;     __builtin_amdgcn_global_load_lds((const unsigned*)((const char*)(gbase) + (voff)[_i]), (LAS unsigned*)(lds + (bufoff) + ldsw + _i * 8192), 16, 0, 0); } while (0)
; #define PG8_LDA(dst, b, h) do { _Pragma("unroll") for (int m = 0; m < 4; ++m) _Pragma("unroll") for (int k = 0; k < 2; ++k) dst[m][k] = *(const LAS bf16x8*)(lds + PG8_SA(b, h) + aoff + m * 2048 + k * 1024); } while (0)
; #define PG8_LDB(dst, b, h) do { _Pragma("unroll") for (int n = 0; n < 2; ++n) _Pragma("unroll") for (int k = 0; k < 2; ++k) dst[n][k] = *(const LAS bf16x8*)(lds + PG8_SB(b, h) + boff + n * 2048 + k * 1024); } while (0)
; #define PG8_MMA(ai, bj, At, Bt) do { __builtin_amdgcn_s_setprio(1); _Pragma("unroll") for (int m = 0; m < 4; ++m) _Pragma("unroll") for (int n = 0; n < 2; ++n) _Pragma("unroll") for (int k = 0; k < 2; ++k) \
;     acc[ai][bj][m][n] = __builtin_amdgcn_mfma_f32_16x16x32_bf16(Bt[n][k], At[m][k], acc[ai][bj][m][n], 0, 0, 0); __builtin_amdgcn_s_setprio(0); } while (0)
; #define PG8_WAIT_L(n) asm volatile("s_waitcnt lgkmcnt(" #n ")" ::: "memory")
; #define PG8_BAR __builtin_amdgcn_s_barrier()
; #define PG8_SCHED __builtin_amdgcn_sched_barrier(0)
; template <class Epi, class Sched>
; DI void gemm_phase(LAS unsigned char* lds, const Gemm g, const Sched& S, const Epi& E) {
;     ...
;       PG8_LDB(B0, 1, 0); PG8_SCHED; PG8_LDA(At, 1, 0); PG8_STAGE(PG8_SA(0, 1), a2 + hstep, voffA);
;       PG8_WAIT_L(8); PG8_BAR; PG8_WAIT_L(0); PG8_MMA(0, 0, At, B0); PG8_BAR; PG8_SCHED;
;       PG8_LDB(B1, 1, 1); PG8_STAGE(PG8_SB(1, 0), b3, voffB);
;       PG8_BAR; PG8_WAIT_L(0); PG8_MMA(0, 1, At, B1); PG8_BAR;
;       PG8_LDA(At, 1, 1); PG8_STAGE(PG8_SA(1, 0), a3, voffA);
;       PG8_BAR; PG8_WAIT_L(0); PG8_MMA(1, 0, At, B0); PG8_BAR; PG8_SCHED;
	ds_read_b128 v[140:143], v226
	ds_read_b128 v[146:149], v226 offset:1024
	ds_read_b128 v[150:153], v226 offset:2048
	ds_read_b128 v[154:157], v226 offset:3072
	ds_read_b128 v[158:161], v163 offset:32768
	ds_read_b128 v[164:167], v163 offset:33792
	ds_read_b128 v[168:171], v163 offset:34816
	ds_read_b128 v[172:175], v163 offset:35840
	ds_read_b128 v[176:179], v163 offset:36864
	ds_read_b128 v[196:199], v163 offset:37888
	ds_read_b128 v[200:203], v163 offset:38912
	ds_read_b128 v[204:207], v163 offset:39936
	ds_read_b128 v[208:211], v227
	ds_read_b128 v[212:215], v227 offset:1024
	ds_read_b128 v[216:219], v227 offset:2048
	ds_read_b128 v[220:223], v227 offset:3072
	s_add_u32 s18, s28, 0x18000
	s_addc_u32 s19, s29, 0
	s_mov_b32 m0, s40
	s_nop 0
	global_load_lds_dwordx4 v128, s[18:19]
	s_mov_b32 m0, s41
	s_nop 0
	global_load_lds_dwordx4 v132, s[18:19]
	s_waitcnt vmcnt(8)
	s_waitcnt lgkmcnt(0)
	s_barrier
	v_mfma_f32_16x16x32_bf16 v[124:127], v[140:143], v[158:161], v[124:127]
	v_mfma_f32_16x16x32_bf16 v[120:123], v[150:153], v[158:161], v[120:123]
	v_mfma_f32_16x16x32_bf16 v[108:111], v[140:143], v[168:171], v[108:111]
	v_mfma_f32_16x16x32_bf16 v[104:107], v[150:153], v[168:171], v[104:107]
	v_mfma_f32_16x16x32_bf16 v[92:95], v[140:143], v[176:179], v[92:95]
	v_mfma_f32_16x16x32_bf16 v[88:91], v[150:153], v[176:179], v[88:91]
	v_mfma_f32_16x16x32_bf16 v[76:79], v[140:143], v[200:203], v[76:79]
	v_mfma_f32_16x16x32_bf16 v[72:75], v[150:153], v[200:203], v[72:75]
	v_mfma_f32_16x16x32_bf16 v[124:127], v[146:149], v[164:167], v[124:127]
	v_mfma_f32_16x16x32_bf16 v[120:123], v[154:157], v[164:167], v[120:123]
	v_mfma_f32_16x16x32_bf16 v[108:111], v[146:149], v[172:175], v[108:111]
	v_mfma_f32_16x16x32_bf16 v[104:107], v[154:157], v[172:175], v[104:107]
	v_mfma_f32_16x16x32_bf16 v[92:95], v[146:149], v[196:199], v[92:95]
	v_mfma_f32_16x16x32_bf16 v[88:91], v[154:157], v[196:199], v[88:91]
	v_mfma_f32_16x16x32_bf16 v[76:79], v[146:149], v[204:207], v[76:79]
	v_mfma_f32_16x16x32_bf16 v[72:75], v[154:157], v[204:207], v[72:75]
	v_mfma_f32_16x16x32_bf16 v[116:119], v[208:211], v[158:161], v[116:119]
	v_mfma_f32_16x16x32_bf16 v[112:115], v[216:219], v[158:161], v[112:115]
	v_mfma_f32_16x16x32_bf16 v[100:103], v[208:211], v[168:171], v[100:103]
	v_mfma_f32_16x16x32_bf16 v[96:99], v[216:219], v[168:171], v[96:99]
	v_mfma_f32_16x16x32_bf16 v[84:87], v[208:211], v[176:179], v[84:87]
	v_mfma_f32_16x16x32_bf16 v[80:83], v[216:219], v[176:179], v[80:83]
	v_mfma_f32_16x16x32_bf16 v[68:71], v[208:211], v[200:203], v[68:71]
	v_mfma_f32_16x16x32_bf16 v[64:67], v[216:219], v[200:203], v[64:67]
	v_mfma_f32_16x16x32_bf16 v[116:119], v[212:215], v[164:167], v[116:119]
	v_mfma_f32_16x16x32_bf16 v[112:115], v[220:223], v[164:167], v[112:115]
	v_mfma_f32_16x16x32_bf16 v[100:103], v[212:215], v[172:175], v[100:103]
	v_mfma_f32_16x16x32_bf16 v[96:99], v[220:223], v[172:175], v[96:99]
	v_mfma_f32_16x16x32_bf16 v[84:87], v[212:215], v[196:199], v[84:87]
	v_mfma_f32_16x16x32_bf16 v[80:83], v[220:223], v[196:199], v[80:83]
	v_mfma_f32_16x16x32_bf16 v[68:71], v[212:215], v[204:207], v[68:71]
	v_mfma_f32_16x16x32_bf16 v[64:67], v[220:223], v[204:207], v[64:67]
	s_barrier
	ds_read_b128 v[158:161], v163 offset:49152
	ds_read_b128 v[164:167], v163 offset:50176
	ds_read_b128 v[168:171], v163 offset:51200
	ds_read_b128 v[172:175], v163 offset:52224
	ds_read_b128 v[176:179], v163 offset:53248
	ds_read_b128 v[196:199], v163 offset:54272
	ds_read_b128 v[200:203], v163 offset:55296
	ds_read_b128 v[204:207], v163 offset:56320
	s_add_i32 s28, 0, 0x1c000
	s_add_i32 s18, s55, s35
	s_mov_b32 m0, s18
	s_nop 0
	global_load_lds_dwordx4 v130, vcc
	s_add_i32 m0, s18, 0x2000
	s_nop 0
	global_load_lds_dwordx4 v134, vcc
	s_mov_b32 m0, s44
	s_nop 0
	global_load_lds_dwordx4 v128, s[100:101]
	s_mov_b32 m0, s45
	s_nop 0
	global_load_lds_dwordx4 v132, s[100:101]
	s_add_u32 s18, s22, 0x18080
	s_addc_u32 s19, s23, 0
	s_add_i32 s22, s28, s35
	s_mov_b32 m0, s22
	s_nop 0
	global_load_lds_dwordx4 v130, s[18:19]
	s_add_i32 m0, s22, 0x2000
	s_nop 0
	global_load_lds_dwordx4 v134, s[18:19]
	s_add_i32 s54, s54, 2
	s_add_u32 s52, s52, 0x100
	s_addc_u32 s53, s53, 0
	s_cmp_gt_u32 s54, 3
	s_mov_b64 s[18:19], s[20:21]
	s_waitcnt vmcnt(8)
	s_waitcnt lgkmcnt(0)
	s_barrier
; #define PG8_STAGE(bufoff, gbase, voff) do { _Pragma("unroll") for (int _i = 0; _i < 2; ++_i) \
;     __builtin_amdgcn_global_load_lds((const unsigned*)((const char*)(gbase) + (voff)[_i]), (LAS unsigned*)(lds + (bufoff) + ldsw + _i * 8192), 16, 0, 0); } while (0)
; #define PG8_MMA(ai, bj, At, Bt) do { __builtin_amdgcn_s_setprio(1); _Pragma("unroll") for (int m = 0; m < 4; ++m) _Pragma("unroll") for (int n = 0; n < 2; ++n) _Pragma("unroll") for (int k = 0; k < 2; ++k) \
;     acc[ai][bj][m][n] = __builtin_amdgcn_mfma_f32_16x16x32_bf16(Bt[n][k], At[m][k], acc[ai][bj][m][n], 0, 0, 0); __builtin_amdgcn_s_setprio(0); } while (0)
; #define PG8_WAIT_V(n) asm volatile("s_waitcnt vmcnt(" #n ")" ::: "memory")
; #define PG8_WAIT_L(n) asm volatile("s_waitcnt lgkmcnt(" #n ")" ::: "memory")
; #define PG8_BAR __builtin_amdgcn_s_barrier()
; #define PG8_SCHED __builtin_amdgcn_sched_barrier(0)
; template <class Epi, class Sched>
; DI void gemm_phase(LAS unsigned char* lds, const Gemm g, const Sched& S, const Epi& E) {
;     ...
;       PG8_BAR; PG8_WAIT_L(0); PG8_MMA(1, 0, At, B0); PG8_BAR; PG8_SCHED;
;       PG8_STAGE(PG8_SB(1, 1), b3 + hstep, voffB);
;       PG8_WAIT_V(6); PG8_BAR; PG8_MMA(1, 1, At, B1); PG8_BAR;
;     }
; DI void rope_perm(f32x4& a0, f32x4& a1, int fq, int lane, const float* tcos, const float* tsin, int pos) {
;   f32x4 p0, p1;
; #pragma unroll
;   for (int e = 0; e < 4; ++e) { p0[e] = shx(a0[e], 32, lane); p1[e] = shx(a1[e], 32, lane); }
;   const int jb = 8 * (fq & 1);
;   const f32x4 c0 = *(const f32x4*)(tcos + pos * 16 + jb), c1 = *(const f32x4*)(tcos + pos * 16 + jb + 4);
;   const f32x4 s0 = *(const f32x4*)(tsin + pos * 16 + jb), s1 = *(const f32x4*)(tsin + pos * 16 + jb + 4);
;   if (fq < 2) { a0 = a0 * c0 - p0 * s0; a1 = a1 * c1 - p1 * s1; }
;   else        { a0 = a0 * c0 + p0 * s0; a1 = a1 * c1 + p1 * s1; }
; }
	v_mfma_f32_16x16x32_bf16 v[60:63], v[140:143], v[158:161], v[60:63]
	v_mfma_f32_16x16x32_bf16 v[56:59], v[150:153], v[158:161], v[56:59]
	v_mfma_f32_16x16x32_bf16 v[44:47], v[140:143], v[168:171], v[44:47]
	v_mfma_f32_16x16x32_bf16 v[40:43], v[150:153], v[168:171], v[40:43]
	v_mfma_f32_16x16x32_bf16 v[28:31], v[140:143], v[176:179], v[28:31]
	v_mfma_f32_16x16x32_bf16 v[24:27], v[150:153], v[176:179], v[24:27]
	v_mfma_f32_16x16x32_bf16 v[12:15], v[140:143], v[200:203], v[12:15]
	v_mfma_f32_16x16x32_bf16 v[8:11], v[150:153], v[200:203], v[8:11]
	v_mfma_f32_16x16x32_bf16 v[60:63], v[146:149], v[164:167], v[60:63]
	v_mfma_f32_16x16x32_bf16 v[56:59], v[154:157], v[164:167], v[56:59]
	v_mfma_f32_16x16x32_bf16 v[44:47], v[146:149], v[172:175], v[44:47]
	v_mfma_f32_16x16x32_bf16 v[40:43], v[154:157], v[172:175], v[40:43]
	v_mfma_f32_16x16x32_bf16 v[28:31], v[146:149], v[196:199], v[28:31]
	v_mfma_f32_16x16x32_bf16 v[24:27], v[154:157], v[196:199], v[24:27]
	v_mfma_f32_16x16x32_bf16 v[12:15], v[146:149], v[204:207], v[12:15]
	v_mfma_f32_16x16x32_bf16 v[8:11], v[154:157], v[204:207], v[8:11]
	v_mfma_f32_16x16x32_bf16 v[52:55], v[208:211], v[158:161], v[52:55]
	v_mfma_f32_16x16x32_bf16 v[48:51], v[216:219], v[158:161], v[48:51]
	v_mfma_f32_16x16x32_bf16 v[36:39], v[208:211], v[168:171], v[36:39]
	v_mfma_f32_16x16x32_bf16 v[32:35], v[216:219], v[168:171], v[32:35]
	v_mfma_f32_16x16x32_bf16 v[20:23], v[208:211], v[176:179], v[20:23]
	v_mfma_f32_16x16x32_bf16 v[16:19], v[216:219], v[176:179], v[16:19]
	v_mfma_f32_16x16x32_bf16 v[4:7], v[208:211], v[200:203], v[4:7]
	v_mfma_f32_16x16x32_bf16 v[0:3], v[216:219], v[200:203], v[0:3]
	v_mfma_f32_16x16x32_bf16 v[52:55], v[212:215], v[164:167], v[52:55]
	v_mfma_f32_16x16x32_bf16 v[48:51], v[220:223], v[164:167], v[48:51]
	v_mfma_f32_16x16x32_bf16 v[36:39], v[212:215], v[172:175], v[36:39]
	v_mfma_f32_16x16x32_bf16 v[32:35], v[220:223], v[172:175], v[32:35]
	v_mfma_f32_16x16x32_bf16 v[20:23], v[212:215], v[196:199], v[20:23]
	v_mfma_f32_16x16x32_bf16 v[16:19], v[220:223], v[196:199], v[16:19]
	v_mfma_f32_16x16x32_bf16 v[4:7], v[212:215], v[204:207], v[4:7]
	v_mfma_f32_16x16x32_bf16 v[0:3], v[220:223], v[204:207], v[0:3]
	s_barrier
	s_cbranch_scc0 .LBB0_1202
	v_mov_b32_e32 v140, v182
	s_lshl_b32 s19, s51, 10
	s_lshl_b32 s18, s49, 8
	s_or_b32 s18, s18, s43
	v_and_or_b32 v167, v140, 15, s42
	v_lshlrev_b32_e32 v141, 2, v140
	s_movk_i32 s20, 0x80
	s_add_i32 s19, s19, 0
	v_bitop3_b32 v164, v141, s20, v190 bitop3:0x6c
	v_lshl_add_u32 v141, v167, 2, s19
	s_mul_hi_i32 s19, s18, 0x2aaaaaab
	v_add_u32_e32 v166, 0x20000, v141
	s_lshr_b32 s20, s19, 31
	s_lshr_b32 s19, s19, 4
	s_lshl_b32 s50, s50, 8
	ds_read_b32 v144, v166
	s_add_i32 s19, s19, s20
	v_add_u32_e32 v165, s50, v167
	s_mulk_i32 s19, 0x60
	v_bfe_u32 v168, v140, 4, 2
	v_lshrrev_b32_e32 v140, 1, v140
	v_lshlrev_b32_e32 v141, 4, v165
	s_sub_i32 s19, s18, s19
	v_and_b32_e32 v140, 8, v140
	v_and_b32_e32 v141, 0xfcf0, v141
	s_cmp_eq_u32 s19, 64
	v_cmp_lt_u32_e64 s[78:79], 1, v168
	s_cselect_b64 s[20:21], -1, 0
	s_cmp_lg_u32 s19, 64
	v_lshlrev_b32_e32 v142, 2, v141
	v_lshlrev_b32_e32 v140, 2, v140
	s_cbranch_scc1 .LBB0_1209
	v_mov_b32_e32 v143, v145
	v_lshl_add_u64 v[146:147], s[12:13], 0, v[142:143]
	v_mov_b32_e32 v141, v145
	v_lshl_add_u64 v[152:153], s[14:15], 0, v[142:143]
	v_lshl_add_u64 v[146:147], v[146:147], 0, v[140:141]
	v_lshl_add_u64 v[152:153], v[152:153], 0, v[140:141]
	global_load_dwordx4 v[148:151], v[146:147], off
	global_load_dwordx4 v[154:157], v[152:153], off
	global_load_dwordx4 v[170:173], v[152:153], off offset:16
	global_load_dwordx4 v[174:177], v[146:147], off offset:16
	ds_bpermute_b32 v152, v164, v124
	ds_bpermute_b32 v160, v164, v120
	ds_bpermute_b32 v153, v164, v125
	ds_bpermute_b32 v161, v164, v121
	ds_bpermute_b32 v158, v164, v126
	ds_bpermute_b32 v178, v164, v122
	ds_bpermute_b32 v159, v164, v127
	ds_bpermute_b32 v179, v164, v123
	s_waitcnt vmcnt(0) lgkmcnt(0)
	v_pk_mul_f32 v[154:155], v[154:155], v[152:153]
	v_pk_mul_f32 v[146:147], v[126:127], v[150:151]
	v_pk_mul_f32 v[150:151], v[124:125], v[148:149]
	v_pk_mul_f32 v[158:159], v[156:157], v[158:159]
	v_pk_mul_f32 v[148:149], v[170:171], v[160:161]
	v_pk_mul_f32 v[152:153], v[172:173], v[178:179]
	v_pk_mul_f32 v[156:157], v[122:123], v[176:177]
	v_pk_mul_f32 v[160:161], v[120:121], v[174:175]
	s_and_saveexec_b64 s[22:23], s[78:79]
	s_xor_b64 s[22:23], exec, s[22:23]
	v_pk_add_f32 v[126:127], v[146:147], v[158:159]
	v_pk_add_f32 v[124:125], v[150:151], v[154:155]
	v_pk_add_f32 v[122:123], v[156:157], v[152:153]
	v_pk_add_f32 v[120:121], v[160:161], v[148:149]
	s_andn2_saveexec_b64 s[22:23], s[22:23]
	v_sub_f32_e32 v127, v147, v159
	v_sub_f32_e32 v126, v146, v158
	v_sub_f32_e32 v125, v151, v155
	v_sub_f32_e32 v124, v150, v154
	v_sub_f32_e32 v123, v157, v153
	v_sub_f32_e32 v122, v156, v152
	v_sub_f32_e32 v121, v161, v149
	v_sub_f32_e32 v120, v160, v148
	s_or_b64 exec, exec, s[22:23]

; #define PG8_STAGE(bufoff, gbase, voff) do { _Pragma("unroll") for (int _i = 0; _i < 2; ++_i) \
;     __builtin_amdgcn_global_load_lds((const unsigned*)((const char*)(gbase) + (voff)[_i]), (LAS unsigned*)(lds + (bufoff) + ldsw + _i * 8192), 16, 0, 0); } while (0)
; #define PG8_WAIT_V(n) asm volatile("s_waitcnt vmcnt(" #n ")" ::: "memory")
; #define PG8_BAR __builtin_amdgcn_s_barrier()
; template <class Epi, class Sched>
; DI void gemm_phase(LAS unsigned char* lds, const Gemm g, const Sched& S, const Epi& E) {
;     ...
;   for (int i = 0; i < 2; ++i) { int R, C; stage_rc(tid * 16 + i * 8192, R, C); const int Rb = Epi::PERM ? ((R & ~31) + perm32(R & 31)) : R;
;     voffA[i] = (unsigned)(R * K + C) * 2u; voffB[i] = (unsigned)(Rb * K + C) * 2u; }
;   const size_t kstep = (size_t)(BK * 2);
;   const size_t hstep = (size_t)HALF * K * 2;
;   const size_t tstep = 2 * hstep;
;   const unsigned ldsw = (unsigned)wid * 1024u;
;   const int aoff = lds_byte(wr * 64 + fr, fq * 8), boff = lds_byte(wc * 32 + fr, fq * 8);
;     ...
;   Unit cur, nxt; int ui = 0;
;   if (!S.next(0, cur)) return;
;   f32x4 acc[2][2][4][2];
; #pragma unroll
;   for (int a = 0; a < 2; ++a)
; #pragma unroll
;     for (int b = 0; b < 2; ++b)
; #pragma unroll
;       for (int m = 0; m < 4; ++m)
; #pragma unroll
;         for (int n = 0; n < 2; ++n) acc[a][b][m][n] = (f32x4){0.f, 0.f, 0.f, 0.f};
;   bf16x8 At[4][2], B0[2][2], B1[2][2];
;   const char* cA = (const char*)g.A + (size_t)cur.pm * tstep; const char* cB = (const char*)g.Bt + (size_t)cur.pn * tstep;
;   PG8_STAGE(PG8_SB(0, 0), cB, voffB); PG8_STAGE(PG8_SA(0, 0), cA, voffA); PG8_STAGE(PG8_SB(0, 1), cB + hstep, voffB); PG8_STAGE(PG8_SA(0, 1), cA + hstep, voffA);
;   if (wr == 1) PG8_BAR;
;   PG8_WAIT_V(4); PG8_BAR;
;   PG8_STAGE(PG8_SB(1, 0), cB + kstep, voffB); PG8_STAGE(PG8_SA(1, 0), cA + kstep, voffA); PG8_STAGE(PG8_SB(1, 1), cB + hstep + kstep, voffB);
;   PG8_WAIT_V(6); PG8_BAR;
.LBB0_1337:
	s_and_b32 s3, s4, 3
	s_lshl_b32 s60, s5, 6
	v_and_b32_e32 v1, 48, v0
	s_lshl_b32 s4, s5, 13
	v_lshlrev_b32_e32 v10, 6, v0
	s_movk_i32 s5, 0x3c0
	v_lshlrev_b32_e32 v0, 2, v0
	v_mov_b32_e32 v131, v145
	v_and_or_b32 v1, v10, s5, v1
	v_and_b32_e32 v0, 32, v0
	v_lshl_add_u64 v[2:3], s[22:23], 0, v[130:131]
	v_mov_b32_e32 v135, v145
	v_bitop3_b32 v10, v1, s4, v0 bitop3:0xde
	s_lshl_b32 s4, s3, 12
	v_lshl_add_u64 v[4:5], s[22:23], 0, v[134:135]
	v_mov_b32_e32 v129, v145
	v_bitop3_b32 v142, v1, s4, v0 bitop3:0xde
	s_add_i32 m0, s56, 0x18000
	v_lshl_add_u64 v[0:1], v[2:3], 0, s[0:1]
	v_lshl_add_u64 v[6:7], s[28:29], 0, v[128:129]
	v_mov_b32_e32 v133, v145
	s_lshl_b32 s61, s3, 5
	s_waitcnt vmcnt(4)
	s_barrier
	global_load_lds_dwordx4 v[0:1], off
	v_lshl_add_u64 v[0:1], v[4:5], 0, s[0:1]
	s_add_i32 m0, s56, 0x1a000
	s_add_i32 s62, s56, 0x8000
	s_add_i32 s63, s56, 0xa000
	v_lshl_add_u64 v[8:9], s[28:29], 0, v[132:133]
	global_load_lds_dwordx4 v[0:1], off
	v_lshl_add_u64 v[0:1], v[6:7], 0, s[0:1]
	s_mov_b32 m0, s62
	s_add_u32 s4, s22, 0x10080
	global_load_lds_dwordx4 v[0:1], off
	v_lshl_add_u64 v[0:1], v[8:9], 0, s[0:1]
	s_mov_b32 m0, s63
	s_addc_u32 s5, s23, 0
	global_load_lds_dwordx4 v[0:1], off
	s_add_i32 m0, s56, 0x1c000
	v_lshl_add_u64 v[0:1], s[4:5], 0, v[130:131]
	global_load_lds_dwordx4 v[0:1], off
	v_lshl_add_u64 v[0:1], s[4:5], 0, v[134:135]
	s_add_i32 m0, s56, 0x1e000
	s_cmp_gt_u32 s3, 1
	global_load_lds_dwordx4 v[0:1], off
	s_waitcnt vmcnt(6)
	s_cselect_b64 s[4:5], -1, 0
	s_add_u32 s10, s9, 0x15da8100
	s_addc_u32 s11, s24, 0
	s_mov_b32 s3, 0
	v_add_u32_e32 v143, 0, v10
	s_barrier
	s_barrier
	s_branch .LBB0_1339

; #define PG8_STAGE(bufoff, gbase, voff) do { _Pragma("unroll") for (int _i = 0; _i < 2; ++_i) \
;     __builtin_amdgcn_global_load_lds((const unsigned*)((const char*)(gbase) + (voff)[_i]), (LAS unsigned*)(lds + (bufoff) + ldsw + _i * 8192), 16, 0, 0); } while (0)
; #define PG8_LDA(dst, b, h) do { _Pragma("unroll") for (int m = 0; m < 4; ++m) _Pragma("unroll") for (int k = 0; k < 2; ++k) dst[m][k] = *(const LAS bf16x8*)(lds + PG8_SA(b, h) + aoff + m * 2048 + k * 1024); } while (0)
; #define PG8_LDB(dst, b, h) do { _Pragma("unroll") for (int n = 0; n < 2; ++n) _Pragma("unroll") for (int k = 0; k < 2; ++k) dst[n][k] = *(const LAS bf16x8*)(lds + PG8_SB(b, h) + boff + n * 2048 + k * 1024); } while (0)
; #define PG8_MMA(ai, bj, At, Bt) do { __builtin_amdgcn_s_setprio(1); _Pragma("unroll") for (int m = 0; m < 4; ++m) _Pragma("unroll") for (int n = 0; n < 2; ++n) _Pragma("unroll") for (int k = 0; k < 2; ++k) \
;     acc[ai][bj][m][n] = __builtin_amdgcn_mfma_f32_16x16x32_bf16(Bt[n][k], At[m][k], acc[ai][bj][m][n], 0, 0, 0); __builtin_amdgcn_s_setprio(0); } while (0)
; #define PG8_WAIT_V(n) asm volatile("s_waitcnt vmcnt(" #n ")" ::: "memory")
; #define PG8_WAIT_L(n) asm volatile("s_waitcnt lgkmcnt(" #n ")" ::: "memory")
; #define PG8_BAR __builtin_amdgcn_s_barrier()
; #define PG8_SCHED __builtin_amdgcn_sched_barrier(0)
; template <class Epi, class Sched>
; DI void gemm_phase(LAS unsigned char* lds, const Gemm g, const Sched& S, const Epi& E) {
;     ...
;     for (int t = 0; t < nt; t += 2) {
;       const bool last = (t == nt - 2);
;       const char* a1 = cA + (size_t)(t + 1) * kstep;
;       const char* a2 = last ? nA : cA + (size_t)(t + 2) * kstep; const char* b2 = last ? nB : cB + (size_t)(t + 2) * kstep;
;       const char* a3 = a2 + kstep; const char* b3 = b2 + kstep;
;       PG8_LDB(B0, 0, 0); PG8_SCHED; PG8_LDA(At, 0, 0); PG8_STAGE(PG8_SA(1, 1), a1 + hstep, voffA);
;       PG8_WAIT_L(8); PG8_BAR; PG8_WAIT_L(0); PG8_MMA(0, 0, At, B0); PG8_BAR; PG8_SCHED;
;       PG8_LDB(B1, 0, 1); PG8_STAGE(PG8_SB(0, 0), b2, voffB);
;       PG8_BAR; PG8_WAIT_L(0); PG8_MMA(0, 1, At, B1); PG8_BAR;
;       PG8_LDA(At, 0, 1); PG8_STAGE(PG8_SA(0, 0), a2, voffA);
;       PG8_BAR; PG8_WAIT_L(0); PG8_MMA(1, 0, At, B0); PG8_BAR; PG8_SCHED;
;       PG8_STAGE(PG8_SB(0, 1), b2 + hstep, voffB);
;       PG8_WAIT_V(6); PG8_BAR; PG8_MMA(1, 1, At, B1); PG8_BAR;
.LBB0_1346:
	ds_read_b128 v[136:139], v220
	ds_read_b128 v[146:149], v220 offset:1024
	ds_read_b128 v[150:153], v220 offset:2048
	ds_read_b128 v[154:157], v220 offset:3072
	ds_read_b128 v[158:161], v143
	ds_read_b128 v[162:165], v143 offset:1024
	ds_read_b128 v[166:169], v143 offset:2048
	ds_read_b128 v[170:173], v143 offset:3072
	ds_read_b128 v[174:177], v143 offset:4096
	ds_read_b128 v[178:181], v143 offset:5120
	ds_read_b128 v[196:199], v143 offset:6144
	ds_read_b128 v[200:203], v143 offset:7168
	ds_read_b128 v[204:207], v221
	ds_read_b128 v[208:211], v221 offset:1024
	ds_read_b128 v[212:215], v221 offset:2048
	ds_read_b128 v[216:219], v221 offset:3072
	s_add_u32 s48, s28, s40
	s_addc_u32 s49, s29, s41
	s_add_u32 s44, s48, 0x100
	s_addc_u32 s45, s49, 0
	s_and_b64 s[42:43], s[36:37], exec
	s_cselect_b32 s45, s15, s45
	s_cselect_b32 s44, s21, s44
	s_add_u32 s40, s22, s40
	s_addc_u32 s41, s23, s41
	s_add_u32 s40, s40, 0x100
	s_addc_u32 s41, s41, 0
	s_add_i32 s70, 0, 0x10000
	s_and_b64 s[36:37], s[36:37], exec
	s_cselect_b32 s47, s13, s41
	s_cselect_b32 s46, s24, s40
	s_add_u32 s48, s48, 0x10080
	s_addc_u32 s49, s49, 0
	s_add_i32 s74, s70, s51
	s_add_i32 m0, s56, 0xc000
	s_add_i32 s75, s56, 0xe000
	s_add_i32 s73, 0, 0x14000
	s_add_i32 s72, s74, 0x2000
	s_add_u32 s42, s46, 0x10000
	s_addc_u32 s43, s47, 0
	s_add_i32 s69, s73, s51
	s_add_i32 s68, s69, 0x2000
	s_add_i32 s67, 0, 0x18000
	s_add_u32 s40, s44, 0x10000
	s_addc_u32 s41, s45, 0
	s_add_i32 s66, s67, s51
	s_add_i32 s65, 0, 0x1c000
	s_add_i32 s64, s66, 0x2000
	s_add_u32 s36, s46, 0x10080
	s_addc_u32 s37, s47, 0
	s_add_i32 s71, s65, s51
	s_add_i32 s70, s71, 0x2000
	global_load_lds_dwordx4 v128, s[48:49]
	s_mov_b32 m0, s75
	s_nop 0
	global_load_lds_dwordx4 v132, s[48:49]
	s_waitcnt vmcnt(8)
	s_waitcnt lgkmcnt(0)
	s_barrier
	v_mfma_f32_16x16x32_bf16 v[124:127], v[136:139], v[158:161], v[124:127]
	v_mfma_f32_16x16x32_bf16 v[120:123], v[150:153], v[158:161], v[120:123]
	v_mfma_f32_16x16x32_bf16 v[108:111], v[136:139], v[166:169], v[108:111]
	v_mfma_f32_16x16x32_bf16 v[104:107], v[150:153], v[166:169], v[104:107]
	v_mfma_f32_16x16x32_bf16 v[92:95], v[136:139], v[174:177], v[92:95]
	v_mfma_f32_16x16x32_bf16 v[88:91], v[150:153], v[174:177], v[88:91]
	v_mfma_f32_16x16x32_bf16 v[76:79], v[136:139], v[196:199], v[76:79]
	v_mfma_f32_16x16x32_bf16 v[72:75], v[150:153], v[196:199], v[72:75]
	v_mfma_f32_16x16x32_bf16 v[124:127], v[146:149], v[162:165], v[124:127]
	v_mfma_f32_16x16x32_bf16 v[120:123], v[154:157], v[162:165], v[120:123]
	v_mfma_f32_16x16x32_bf16 v[108:111], v[146:149], v[170:173], v[108:111]
	v_mfma_f32_16x16x32_bf16 v[104:107], v[154:157], v[170:173], v[104:107]
	v_mfma_f32_16x16x32_bf16 v[92:95], v[146:149], v[178:181], v[92:95]
	v_mfma_f32_16x16x32_bf16 v[88:91], v[154:157], v[178:181], v[88:91]
	v_mfma_f32_16x16x32_bf16 v[76:79], v[146:149], v[200:203], v[76:79]
	v_mfma_f32_16x16x32_bf16 v[72:75], v[154:157], v[200:203], v[72:75]
	v_mfma_f32_16x16x32_bf16 v[116:119], v[204:207], v[158:161], v[116:119]
	v_mfma_f32_16x16x32_bf16 v[112:115], v[212:215], v[158:161], v[112:115]
	v_mfma_f32_16x16x32_bf16 v[100:103], v[204:207], v[166:169], v[100:103]
	v_mfma_f32_16x16x32_bf16 v[96:99], v[212:215], v[166:169], v[96:99]
	v_mfma_f32_16x16x32_bf16 v[84:87], v[204:207], v[174:177], v[84:87]
	v_mfma_f32_16x16x32_bf16 v[80:83], v[212:215], v[174:177], v[80:83]
	v_mfma_f32_16x16x32_bf16 v[68:71], v[204:207], v[196:199], v[68:71]
	v_mfma_f32_16x16x32_bf16 v[64:67], v[212:215], v[196:199], v[64:67]
	v_mfma_f32_16x16x32_bf16 v[116:119], v[208:211], v[162:165], v[116:119]
	v_mfma_f32_16x16x32_bf16 v[112:115], v[216:219], v[162:165], v[112:115]
	v_mfma_f32_16x16x32_bf16 v[100:103], v[208:211], v[170:173], v[100:103]
	v_mfma_f32_16x16x32_bf16 v[96:99], v[216:219], v[170:173], v[96:99]
	v_mfma_f32_16x16x32_bf16 v[84:87], v[208:211], v[178:181], v[84:87]
	v_mfma_f32_16x16x32_bf16 v[80:83], v[216:219], v[178:181], v[80:83]
	v_mfma_f32_16x16x32_bf16 v[68:71], v[208:211], v[200:203], v[68:71]
	v_mfma_f32_16x16x32_bf16 v[64:67], v[216:219], v[200:203], v[64:67]
	s_barrier
	ds_read_b128 v[158:161], v143 offset:16384
	ds_read_b128 v[162:165], v143 offset:17408
	ds_read_b128 v[166:169], v143 offset:18432
	ds_read_b128 v[170:173], v143 offset:19456
	ds_read_b128 v[174:177], v143 offset:20480
	ds_read_b128 v[178:181], v143 offset:21504
	ds_read_b128 v[196:199], v143 offset:22528
	ds_read_b128 v[200:203], v143 offset:23552
	s_mov_b32 m0, s74
	s_add_u32 vcc_lo, s46, s0
	s_addc_u32 vcc_hi, s47, s1
	global_load_lds_dwordx4 v130, s[46:47]
	s_mov_b32 m0, s72
	s_nop 0
	global_load_lds_dwordx4 v134, s[46:47]
	s_mov_b32 m0, s56
	s_add_u32 s100, s44, s0
	s_addc_u32 s101, s45, s1
	global_load_lds_dwordx4 v128, s[44:45]
	s_mov_b32 m0, s57
	s_nop 0
	global_load_lds_dwordx4 v132, s[44:45]
	s_mov_b32 m0, s69
	s_nop 0
	global_load_lds_dwordx4 v130, s[42:43]
	s_mov_b32 m0, s68
	s_nop 0
	global_load_lds_dwordx4 v134, s[42:43]
	s_waitcnt vmcnt(8)
	s_waitcnt lgkmcnt(0)
	s_barrier
; #define PG8_STAGE(bufoff, gbase, voff) do { _Pragma("unroll") for (int _i = 0; _i < 2; ++_i) \
;     __builtin_amdgcn_global_load_lds((const unsigned*)((const char*)(gbase) + (voff)[_i]), (LAS unsigned*)(lds + (bufoff) + ldsw + _i * 8192), 16, 0, 0); } while (0)
; #define PG8_LDA(dst, b, h) do { _Pragma("unroll") for (int m = 0; m < 4; ++m) _Pragma("unroll") for (int k = 0; k < 2; ++k) dst[m][k] = *(const LAS bf16x8*)(lds + PG8_SA(b, h) + aoff + m * 2048 + k * 1024); } while (0)
; #define PG8_LDB(dst, b, h) do { _Pragma("unroll") for (int n = 0; n < 2; ++n) _Pragma("unroll") for (int k = 0; k < 2; ++k) dst[n][k] = *(const LAS bf16x8*)(lds + PG8_SB(b, h) + boff + n * 2048 + k * 1024); } while (0)
; #define PG8_MMA(ai, bj, At, Bt) do { __builtin_amdgcn_s_setprio(1); _Pragma("unroll") for (int m = 0; m < 4; ++m) _Pragma("unroll") for (int n = 0; n < 2; ++n) _Pragma("unroll") for (int k = 0; k < 2; ++k) \
;     acc[ai][bj][m][n] = __builtin_amdgcn_mfma_f32_16x16x32_bf16(Bt[n][k], At[m][k], acc[ai][bj][m][n], 0, 0, 0); __builtin_amdgcn_s_setprio(0); } while (0)
; #define PG8_WAIT_V(n) asm volatile("s_waitcnt vmcnt(" #n ")" ::: "memory")
; #define PG8_WAIT_L(n) asm volatile("s_waitcnt lgkmcnt(" #n ")" ::: "memory")
; #define PG8_BAR __builtin_amdgcn_s_barrier()
; #define PG8_SCHED __builtin_amdgcn_sched_barrier(0)
; template <class Epi, class Sched>
; DI void gemm_phase(LAS unsigned char* lds, const Gemm g, const Sched& S, const Epi& E) {
;     ...
;       PG8_BAR; PG8_WAIT_L(0); PG8_MMA(1, 0, At, B0); PG8_BAR; PG8_SCHED;
;       PG8_STAGE(PG8_SB(0, 1), b2 + hstep, voffB);
;       PG8_WAIT_V(6); PG8_BAR; PG8_MMA(1, 1, At, B1); PG8_BAR;
;       PG8_LDB(B0, 1, 0); PG8_SCHED; PG8_LDA(At, 1, 0); PG8_STAGE(PG8_SA(0, 1), a2 + hstep, voffA);
;       PG8_WAIT_L(8); PG8_BAR; PG8_WAIT_L(0); PG8_MMA(0, 0, At, B0); PG8_BAR; PG8_SCHED;
;       PG8_LDB(B1, 1, 1); PG8_STAGE(PG8_SB(1, 0), b3, voffB);
;       PG8_BAR; PG8_WAIT_L(0); PG8_MMA(0, 1, At, B1); PG8_BAR;
;       PG8_LDA(At, 1, 1); PG8_STAGE(PG8_SA(1, 0), a3, voffA);
;       PG8_BAR; PG8_WAIT_L(0); PG8_MMA(1, 0, At, B0); PG8_BAR; PG8_SCHED;
	v_mfma_f32_16x16x32_bf16 v[60:63], v[136:139], v[158:161], v[60:63]
	v_mfma_f32_16x16x32_bf16 v[56:59], v[150:153], v[158:161], v[56:59]
	v_mfma_f32_16x16x32_bf16 v[44:47], v[136:139], v[166:169], v[44:47]
	v_mfma_f32_16x16x32_bf16 v[40:43], v[150:153], v[166:169], v[40:43]
	v_mfma_f32_16x16x32_bf16 v[28:31], v[136:139], v[174:177], v[28:31]
	v_mfma_f32_16x16x32_bf16 v[24:27], v[150:153], v[174:177], v[24:27]
	v_mfma_f32_16x16x32_bf16 v[12:15], v[136:139], v[196:199], v[12:15]
	v_mfma_f32_16x16x32_bf16 v[8:11], v[150:153], v[196:199], v[8:11]
	v_mfma_f32_16x16x32_bf16 v[60:63], v[146:149], v[162:165], v[60:63]
	v_mfma_f32_16x16x32_bf16 v[56:59], v[154:157], v[162:165], v[56:59]
	v_mfma_f32_16x16x32_bf16 v[44:47], v[146:149], v[170:173], v[44:47]
	v_mfma_f32_16x16x32_bf16 v[40:43], v[154:157], v[170:173], v[40:43]
	v_mfma_f32_16x16x32_bf16 v[28:31], v[146:149], v[178:181], v[28:31]
	v_mfma_f32_16x16x32_bf16 v[24:27], v[154:157], v[178:181], v[24:27]
	v_mfma_f32_16x16x32_bf16 v[12:15], v[146:149], v[200:203], v[12:15]
	v_mfma_f32_16x16x32_bf16 v[8:11], v[154:157], v[200:203], v[8:11]
	v_mfma_f32_16x16x32_bf16 v[52:55], v[204:207], v[158:161], v[52:55]
	v_mfma_f32_16x16x32_bf16 v[48:51], v[212:215], v[158:161], v[48:51]
	v_mfma_f32_16x16x32_bf16 v[36:39], v[204:207], v[166:169], v[36:39]
	v_mfma_f32_16x16x32_bf16 v[32:35], v[212:215], v[166:169], v[32:35]
	v_mfma_f32_16x16x32_bf16 v[20:23], v[204:207], v[174:177], v[20:23]
	v_mfma_f32_16x16x32_bf16 v[16:19], v[212:215], v[174:177], v[16:19]
	v_mfma_f32_16x16x32_bf16 v[4:7], v[204:207], v[196:199], v[4:7]
	v_mfma_f32_16x16x32_bf16 v[0:3], v[212:215], v[196:199], v[0:3]
	v_mfma_f32_16x16x32_bf16 v[52:55], v[208:211], v[162:165], v[52:55]
	v_mfma_f32_16x16x32_bf16 v[48:51], v[216:219], v[162:165], v[48:51]
	v_mfma_f32_16x16x32_bf16 v[36:39], v[208:211], v[170:173], v[36:39]
	v_mfma_f32_16x16x32_bf16 v[32:35], v[216:219], v[170:173], v[32:35]
	v_mfma_f32_16x16x32_bf16 v[20:23], v[208:211], v[178:181], v[20:23]
	v_mfma_f32_16x16x32_bf16 v[16:19], v[216:219], v[178:181], v[16:19]
	v_mfma_f32_16x16x32_bf16 v[4:7], v[208:211], v[200:203], v[4:7]
	v_mfma_f32_16x16x32_bf16 v[0:3], v[216:219], v[200:203], v[0:3]
	s_barrier
	ds_read_b128 v[136:139], v222
	ds_read_b128 v[146:149], v222 offset:1024
	ds_read_b128 v[150:153], v222 offset:2048
	ds_read_b128 v[154:157], v222 offset:3072
	ds_read_b128 v[158:161], v143 offset:32768
	ds_read_b128 v[162:165], v143 offset:33792
	ds_read_b128 v[166:169], v143 offset:34816
	ds_read_b128 v[170:173], v143 offset:35840
	ds_read_b128 v[174:177], v143 offset:36864
	ds_read_b128 v[178:181], v143 offset:37888
	ds_read_b128 v[196:199], v143 offset:38912
	ds_read_b128 v[200:203], v143 offset:39936
	ds_read_b128 v[204:207], v223
	ds_read_b128 v[208:211], v223 offset:1024
	ds_read_b128 v[212:215], v223 offset:2048
	ds_read_b128 v[216:219], v223 offset:3072
	s_mov_b32 m0, s58
	s_nop 0
	global_load_lds_dwordx4 v128, s[40:41]
	s_mov_b32 m0, s59
	s_nop 0
	global_load_lds_dwordx4 v132, s[40:41]
	s_waitcnt vmcnt(8)
	s_waitcnt lgkmcnt(0)
	s_barrier
	v_mfma_f32_16x16x32_bf16 v[124:127], v[136:139], v[158:161], v[124:127]
	v_mfma_f32_16x16x32_bf16 v[120:123], v[150:153], v[158:161], v[120:123]
	v_mfma_f32_16x16x32_bf16 v[108:111], v[136:139], v[166:169], v[108:111]
	v_mfma_f32_16x16x32_bf16 v[104:107], v[150:153], v[166:169], v[104:107]
	v_mfma_f32_16x16x32_bf16 v[92:95], v[136:139], v[174:177], v[92:95]
	v_mfma_f32_16x16x32_bf16 v[88:91], v[150:153], v[174:177], v[88:91]
	v_mfma_f32_16x16x32_bf16 v[76:79], v[136:139], v[196:199], v[76:79]
	v_mfma_f32_16x16x32_bf16 v[72:75], v[150:153], v[196:199], v[72:75]
	v_mfma_f32_16x16x32_bf16 v[124:127], v[146:149], v[162:165], v[124:127]
	v_mfma_f32_16x16x32_bf16 v[120:123], v[154:157], v[162:165], v[120:123]
	v_mfma_f32_16x16x32_bf16 v[108:111], v[146:149], v[170:173], v[108:111]
	v_mfma_f32_16x16x32_bf16 v[104:107], v[154:157], v[170:173], v[104:107]
	v_mfma_f32_16x16x32_bf16 v[92:95], v[146:149], v[178:181], v[92:95]
	v_mfma_f32_16x16x32_bf16 v[88:91], v[154:157], v[178:181], v[88:91]
	v_mfma_f32_16x16x32_bf16 v[76:79], v[146:149], v[200:203], v[76:79]
	v_mfma_f32_16x16x32_bf16 v[72:75], v[154:157], v[200:203], v[72:75]
	v_mfma_f32_16x16x32_bf16 v[116:119], v[204:207], v[158:161], v[116:119]
	v_mfma_f32_16x16x32_bf16 v[112:115], v[212:215], v[158:161], v[112:115]
	v_mfma_f32_16x16x32_bf16 v[100:103], v[204:207], v[166:169], v[100:103]
	v_mfma_f32_16x16x32_bf16 v[96:99], v[212:215], v[166:169], v[96:99]
	v_mfma_f32_16x16x32_bf16 v[84:87], v[204:207], v[174:177], v[84:87]
	v_mfma_f32_16x16x32_bf16 v[80:83], v[212:215], v[174:177], v[80:83]
	v_mfma_f32_16x16x32_bf16 v[68:71], v[204:207], v[196:199], v[68:71]
	v_mfma_f32_16x16x32_bf16 v[64:67], v[212:215], v[196:199], v[64:67]
	v_mfma_f32_16x16x32_bf16 v[116:119], v[208:211], v[162:165], v[116:119]
	v_mfma_f32_16x16x32_bf16 v[112:115], v[216:219], v[162:165], v[112:115]
	v_mfma_f32_16x16x32_bf16 v[100:103], v[208:211], v[170:173], v[100:103]
	v_mfma_f32_16x16x32_bf16 v[96:99], v[216:219], v[170:173], v[96:99]
	v_mfma_f32_16x16x32_bf16 v[84:87], v[208:211], v[178:181], v[84:87]
	v_mfma_f32_16x16x32_bf16 v[80:83], v[216:219], v[178:181], v[80:83]
	v_mfma_f32_16x16x32_bf16 v[68:71], v[208:211], v[200:203], v[68:71]
	v_mfma_f32_16x16x32_bf16 v[64:67], v[216:219], v[200:203], v[64:67]
	s_barrier
; #define PG8_STAGE(bufoff, gbase, voff) do { _Pragma("unroll") for (int _i = 0; _i < 2; ++_i) \
;     __builtin_amdgcn_global_load_lds((const unsigned*)((const char*)(gbase) + (voff)[_i]), (LAS unsigned*)(lds + (bufoff) + ldsw + _i * 8192), 16, 0, 0); } while (0)
; #define PG8_LDA(dst, b, h) do { _Pragma("unroll") for (int m = 0; m < 4; ++m) _Pragma("unroll") for (int k = 0; k < 2; ++k) dst[m][k] = *(const LAS bf16x8*)(lds + PG8_SA(b, h) + aoff + m * 2048 + k * 1024); } while (0)
; #define PG8_MMA(ai, bj, At, Bt) do { __builtin_amdgcn_s_setprio(1); _Pragma("unroll") for (int m = 0; m < 4; ++m) _Pragma("unroll") for (int n = 0; n < 2; ++n) _Pragma("unroll") for (int k = 0; k < 2; ++k) \
;     acc[ai][bj][m][n] = __builtin_amdgcn_mfma_f32_16x16x32_bf16(Bt[n][k], At[m][k], acc[ai][bj][m][n], 0, 0, 0); __builtin_amdgcn_s_setprio(0); } while (0)
; #define PG8_WAIT_V(n) asm volatile("s_waitcnt vmcnt(" #n ")" ::: "memory")
; #define PG8_WAIT_L(n) asm volatile("s_waitcnt lgkmcnt(" #n ")" ::: "memory")
; #define PG8_BAR __builtin_amdgcn_s_barrier()
; #define PG8_SCHED __builtin_amdgcn_sched_barrier(0)
; template <class Epi, class Sched>
; DI void gemm_phase(LAS unsigned char* lds, const Gemm g, const Sched& S, const Epi& E) {
;     ...
;       PG8_LDA(At, 1, 1); PG8_STAGE(PG8_SA(1, 0), a3, voffA);
;       PG8_BAR; PG8_WAIT_L(0); PG8_MMA(1, 0, At, B0); PG8_BAR; PG8_SCHED;
;       PG8_STAGE(PG8_SB(1, 1), b3 + hstep, voffB);
;       PG8_WAIT_V(6); PG8_BAR; PG8_MMA(1, 1, At, B1); PG8_BAR;
;     }
;     E(acc, cur, wr, wc, fr, fq);
;   DI void operator()(const f32x4 (&acc)[2][2][4][2], const pg8::Unit& u, int wr, int wc, int fr_, int fq_) const {
;     ...
;         if (EPI != EPI_RESID) rinv = rinv_tab[slot * 256 + rl];
;     ...
;             } else if (EPI == EPI_UKV) {
;               if (n == 0) {
;                 const int gb = u.pn * 256 + bj * 128 + wc * 32;
;                 const int hd = gb >> 7, within = (gb & 127) + 8 * fq;
;                 const f32x4 v1 = acc[ai][bj][m][1];
;                 if (within < 64) st_bf8((u16*)(big + E_KNOPE) + (size_t)token * 512 + hd * 64 + within, v, v1, rinv);
;                 else st_bf8((u16*)(big + E_VMLAT) + (size_t)token * 512 + hd * 64 + (within - 64), v, v1, rinv);
;               }
	ds_read_b128 v[158:161], v143 offset:49152
	ds_read_b128 v[162:165], v143 offset:50176
	ds_read_b128 v[166:169], v143 offset:51200
	ds_read_b128 v[170:173], v143 offset:52224
	ds_read_b128 v[174:177], v143 offset:53248
	ds_read_b128 v[178:181], v143 offset:54272
	ds_read_b128 v[196:199], v143 offset:55296
	ds_read_b128 v[200:203], v143 offset:56320
	s_mov_b32 m0, s66
	s_nop 0
	global_load_lds_dwordx4 v130, vcc
	s_mov_b32 m0, s64
	s_nop 0
	global_load_lds_dwordx4 v134, vcc
	s_mov_b32 m0, s62
	s_nop 0
	global_load_lds_dwordx4 v128, s[100:101]
	s_mov_b32 m0, s63
	s_nop 0
	global_load_lds_dwordx4 v132, s[100:101]
	s_mov_b32 m0, s71
	s_nop 0
	global_load_lds_dwordx4 v130, s[36:37]
	s_mov_b32 m0, s70
	s_nop 0
	global_load_lds_dwordx4 v134, s[36:37]
	s_andn2_b64 vcc, exec, s[34:35]
	s_mov_b64 s[36:37], -1
	s_mov_b64 s[34:35], 0
	s_mov_b64 s[40:41], 0x100
	s_waitcnt vmcnt(8)
	s_waitcnt lgkmcnt(0)
	s_barrier
	v_mfma_f32_16x16x32_bf16 v[60:63], v[136:139], v[158:161], v[60:63]
	v_mfma_f32_16x16x32_bf16 v[56:59], v[150:153], v[158:161], v[56:59]
	v_mfma_f32_16x16x32_bf16 v[44:47], v[136:139], v[166:169], v[44:47]
	v_mfma_f32_16x16x32_bf16 v[40:43], v[150:153], v[166:169], v[40:43]
	v_mfma_f32_16x16x32_bf16 v[28:31], v[136:139], v[174:177], v[28:31]
	v_mfma_f32_16x16x32_bf16 v[24:27], v[150:153], v[174:177], v[24:27]
	v_mfma_f32_16x16x32_bf16 v[12:15], v[136:139], v[196:199], v[12:15]
	v_mfma_f32_16x16x32_bf16 v[8:11], v[150:153], v[196:199], v[8:11]
	v_mfma_f32_16x16x32_bf16 v[60:63], v[146:149], v[162:165], v[60:63]
	v_mfma_f32_16x16x32_bf16 v[56:59], v[154:157], v[162:165], v[56:59]
	v_mfma_f32_16x16x32_bf16 v[44:47], v[146:149], v[170:173], v[44:47]
	v_mfma_f32_16x16x32_bf16 v[40:43], v[154:157], v[170:173], v[40:43]
	v_mfma_f32_16x16x32_bf16 v[28:31], v[146:149], v[178:181], v[28:31]
	v_mfma_f32_16x16x32_bf16 v[24:27], v[154:157], v[178:181], v[24:27]
	v_mfma_f32_16x16x32_bf16 v[12:15], v[146:149], v[200:203], v[12:15]
	v_mfma_f32_16x16x32_bf16 v[8:11], v[154:157], v[200:203], v[8:11]
	v_mfma_f32_16x16x32_bf16 v[52:55], v[204:207], v[158:161], v[52:55]
	v_mfma_f32_16x16x32_bf16 v[48:51], v[212:215], v[158:161], v[48:51]
	v_mfma_f32_16x16x32_bf16 v[36:39], v[204:207], v[166:169], v[36:39]
	v_mfma_f32_16x16x32_bf16 v[32:35], v[212:215], v[166:169], v[32:35]
	v_mfma_f32_16x16x32_bf16 v[20:23], v[204:207], v[174:177], v[20:23]
	v_mfma_f32_16x16x32_bf16 v[16:19], v[212:215], v[174:177], v[16:19]
	v_mfma_f32_16x16x32_bf16 v[4:7], v[204:207], v[196:199], v[4:7]
	v_mfma_f32_16x16x32_bf16 v[0:3], v[212:215], v[196:199], v[0:3]
	v_mfma_f32_16x16x32_bf16 v[52:55], v[208:211], v[162:165], v[52:55]
	v_mfma_f32_16x16x32_bf16 v[48:51], v[216:219], v[162:165], v[48:51]
	v_mfma_f32_16x16x32_bf16 v[36:39], v[208:211], v[170:173], v[36:39]
	v_mfma_f32_16x16x32_bf16 v[32:35], v[216:219], v[170:173], v[32:35]
	v_mfma_f32_16x16x32_bf16 v[20:23], v[208:211], v[178:181], v[20:23]
	v_mfma_f32_16x16x32_bf16 v[16:19], v[216:219], v[178:181], v[16:19]
	v_mfma_f32_16x16x32_bf16 v[4:7], v[208:211], v[200:203], v[4:7]
	v_mfma_f32_16x16x32_bf16 v[0:3], v[216:219], v[200:203], v[0:3]
	s_barrier
	s_cbranch_vccz .LBB0_1346
	v_mov_b32_e32 v136, v182
	s_lshl_b32 s3, s3, 10
	s_add_i32 s3, s3, 0
	v_and_or_b32 v147, v136, 15, s60
	v_lshl_add_u32 v137, v147, 2, s3
	v_add_u32_e32 v146, 0x20000, v137
	ds_read_b32 v138, v146
	s_lshl_b32 s13, s20, 8
	v_lshrrev_b32_e32 v136, 1, v136
	v_and_or_b32 v139, v136, 24, s61
	v_add_u32_e32 v136, s13, v147
	v_ashrrev_i32_e32 v137, 31, v136
	s_waitcnt lgkmcnt(0)
	v_pk_mul_f32 v[124:125], v[124:125], v[138:139] op_sel_hi:[1,0]
	v_pk_mul_f32 v[126:127], v[126:127], v[138:139] op_sel_hi:[1,0]
	v_pk_mul_f32 v[120:121], v[120:121], v[138:139] op_sel_hi:[1,0]
	v_lshlrev_b64 v[140:141], 10, v[136:137]
	s_lshl_b32 s20, s2, 7
	v_cvt_pk_bf16_f32 v124, v124, v125
	v_cvt_pk_bf16_f32 v125, v126, v127
	v_cvt_pk_bf16_f32 v126, v120, v121
	v_pk_mul_f32 v[120:121], v[122:123], v[138:139] op_sel_hi:[1,0]
	s_ashr_i32 s21, s20, 31
	v_cvt_pk_bf16_f32 v127, v120, v121
	v_lshl_add_u64 v[120:121], s[6:7], 0, v[140:141]
	s_mov_b64 s[2:3], -1
	s_and_b64 vcc, exec, s[4:5]
	v_lshl_add_u64 v[120:121], s[20:21], 1, v[120:121]
	v_lshlrev_b32_e32 v144, 1, v139
	s_cbranch_vccz .LBB0_1349
	v_lshl_add_u64 v[122:123], v[120:121], 0, v[144:145]
	v_add_co_u32_e32 v122, vcc, 0xd9ff000, v122
	s_mov_b64 s[2:3], 0
	s_nop 0
	v_addc_co_u32_e32 v123, vcc, 0, v123, vcc
	global_store_dwordx4 v[122:123], v[124:127], off offset:3968

; #define PG8_STAGE(bufoff, gbase, voff) do { _Pragma("unroll") for (int _i = 0; _i < 2; ++_i) \
;     __builtin_amdgcn_global_load_lds((const unsigned*)((const char*)(gbase) + (voff)[_i]), (LAS unsigned*)(lds + (bufoff) + ldsw + _i * 8192), 16, 0, 0); } while (0)
; #define PG8_WAIT_V(n) asm volatile("s_waitcnt vmcnt(" #n ")" ::: "memory")
; #define PG8_BAR __builtin_amdgcn_s_barrier()
; template <class Epi, class Sched>
; DI void gemm_phase(LAS unsigned char* lds, const Gemm g, const Sched& S, const Epi& E) {
;     ...
;   Unit cur, nxt; int ui = 0;
;   if (!S.next(0, cur)) return;
;   f32x4 acc[2][2][4][2];
; #pragma unroll
;   for (int a = 0; a < 2; ++a)
; #pragma unroll
;     for (int b = 0; b < 2; ++b)
; #pragma unroll
;       for (int m = 0; m < 4; ++m)
; #pragma unroll
;         for (int n = 0; n < 2; ++n) acc[a][b][m][n] = (f32x4){0.f, 0.f, 0.f, 0.f};
;   bf16x8 At[4][2], B0[2][2], B1[2][2];
;   const char* cA = (const char*)g.A + (size_t)cur.pm * tstep; const char* cB = (const char*)g.Bt + (size_t)cur.pn * tstep;
;   PG8_STAGE(PG8_SB(0, 0), cB, voffB); PG8_STAGE(PG8_SA(0, 0), cA, voffA); PG8_STAGE(PG8_SB(0, 1), cB + hstep, voffB); PG8_STAGE(PG8_SA(0, 1), cA + hstep, voffA);
;   if (wr == 1) PG8_BAR;
;   PG8_WAIT_V(4); PG8_BAR;
;   PG8_STAGE(PG8_SB(1, 0), cB + kstep, voffB); PG8_STAGE(PG8_SA(1, 0), cA + kstep, voffA); PG8_STAGE(PG8_SB(1, 1), cB + hstep + kstep, voffB);
;   PG8_WAIT_V(6); PG8_BAR;
.LBB0_1635:
	v_readlane_b32 s48, v241, 13
	v_readlane_b32 s49, v241, 14
	s_lshl_b64 s[6:7], s[6:7], 2
	s_mov_b64 s[16:17], s[48:49]
	s_add_u32 s6, s16, s6
	s_addc_u32 s7, s17, s7
	v_readlane_b32 s10, v237, 11
	s_cmp_eq_u32 s10, 0
	s_cselect_b32 s7, s7, 0
	s_cselect_b32 s6, s6, 0
	s_add_u32 s10, s12, 0x61a4100
	s_addc_u32 s11, s13, 0
	s_add_u32 s12, s12, 0x1a3a8100
	s_addc_u32 s13, s13, 0
	s_and_b32 s46, s15, 3
	v_and_b32_e32 v15, 48, v14
	v_lshlrev_b32_e32 v16, 6, v14
	s_movk_i32 s15, 0x3c0
	v_lshlrev_b32_e32 v14, 2, v14
	v_readlane_b32 s50, v241, 15
	s_lshl_b32 s47, s14, 6
	s_lshl_b32 s14, s14, 13
	v_and_or_b32 v15, v16, s15, v15
	v_and_b32_e32 v14, 32, v14
	s_add_i32 m0, s41, 0x18000
	v_lshl_add_u64 v[6:7], v[6:7], 0, s[0:1]
	v_bitop3_b32 v16, v15, s14, v14 bitop3:0xde
	s_lshl_b32 s48, s46, 5
	s_lshl_b32 s14, s46, 12
	s_waitcnt vmcnt(4)
	s_barrier
	global_load_lds_dwordx4 v[6:7], off
	v_lshl_add_u64 v[4:5], v[4:5], 0, s[0:1]
	s_add_i32 m0, s41, 0x1a000
	s_add_i32 s49, s41, 0x8000
	s_add_i32 s50, s41, 0xa000
	v_bitop3_b32 v158, v15, s14, v14 bitop3:0xde
	global_load_lds_dwordx4 v[4:5], off
	v_lshl_add_u64 v[2:3], v[2:3], 0, s[0:1]
	s_mov_b32 m0, s49
	s_add_u32 s14, s4, 0x40080
	global_load_lds_dwordx4 v[2:3], off
	v_lshl_add_u64 v[0:1], v[0:1], 0, s[0:1]
	s_mov_b32 m0, s50
	s_addc_u32 s15, s5, 0
	global_load_lds_dwordx4 v[0:1], off
	s_add_i32 m0, s41, 0x1c000
	v_lshl_add_u64 v[0:1], s[14:15], 0, v[144:145]
	global_load_lds_dwordx4 v[0:1], off
	v_lshl_add_u64 v[0:1], s[14:15], 0, v[136:137]
	s_add_i32 m0, s41, 0x1e000
	s_cmp_lg_u64 s[6:7], 0
	global_load_lds_dwordx4 v[0:1], off
	v_lshlrev_b32_e32 v0, 14, v12
	v_and_b32_e32 v0, 0xffff8000, v0
	v_lshl_add_u32 v0, v11, 11, v0
	v_and_b32_e32 v1, 1, v12
	v_lshl_or_b32 v0, v1, 6, v0
	v_lshl_add_u32 v142, v13, 1, v0
	v_lshlrev_b32_e32 v0, 14, v8
	v_and_b32_e32 v0, 0xffff8000, v0
	s_waitcnt vmcnt(6)
	v_lshl_add_u32 v0, v9, 11, v0
	v_and_b32_e32 v1, 1, v8
	v_lshl_or_b32 v0, v1, 6, v0
	v_readlane_b32 s16, v240, 53
	s_mov_b32 s45, 0
	s_cselect_b64 s[14:15], -1, 0
	v_mov_b32_e32 v143, v145
	v_lshl_add_u32 v146, v10, 1, v0
	v_mov_b32_e32 v147, v145
	v_add_u32_e32 v159, 0, v16
	v_readlane_b32 s24, v240, 46
	s_mov_b32 s34, s16
	v_readlane_b32 s51, v241, 16
	v_readlane_b32 s52, v241, 17
	v_readlane_b32 s53, v241, 18
	v_readlane_b32 s54, v241, 19
	v_readlane_b32 s55, v241, 20
	v_readlane_b32 s56, v241, 21
	v_readlane_b32 s57, v241, 22
	v_readlane_b32 s58, v241, 23
	v_readlane_b32 s59, v241, 24
	v_readlane_b32 s60, v241, 25
	v_readlane_b32 s61, v241, 26
	v_readlane_b32 s62, v241, 27
	v_readlane_b32 s63, v241, 28
	s_barrier
	s_barrier
	v_readlane_b32 s17, v240, 54
	s_branch .LBB0_1637

; #define PG8_STAGE(bufoff, gbase, voff) do { _Pragma("unroll") for (int _i = 0; _i < 2; ++_i) \
;     __builtin_amdgcn_global_load_lds((const unsigned*)((const char*)(gbase) + (voff)[_i]), (LAS unsigned*)(lds + (bufoff) + ldsw + _i * 8192), 16, 0, 0); } while (0)
; #define PG8_LDA(dst, b, h) do { _Pragma("unroll") for (int m = 0; m < 4; ++m) _Pragma("unroll") for (int k = 0; k < 2; ++k) dst[m][k] = *(const LAS bf16x8*)(lds + PG8_SA(b, h) + aoff + m * 2048 + k * 1024); } while (0)
; #define PG8_LDB(dst, b, h) do { _Pragma("unroll") for (int n = 0; n < 2; ++n) _Pragma("unroll") for (int k = 0; k < 2; ++k) dst[n][k] = *(const LAS bf16x8*)(lds + PG8_SB(b, h) + boff + n * 2048 + k * 1024); } while (0)
; #define PG8_MMA(ai, bj, At, Bt) do { __builtin_amdgcn_s_setprio(1); _Pragma("unroll") for (int m = 0; m < 4; ++m) _Pragma("unroll") for (int n = 0; n < 2; ++n) _Pragma("unroll") for (int k = 0; k < 2; ++k) \
;     acc[ai][bj][m][n] = __builtin_amdgcn_mfma_f32_16x16x32_bf16(Bt[n][k], At[m][k], acc[ai][bj][m][n], 0, 0, 0); __builtin_amdgcn_s_setprio(0); } while (0)
; #define PG8_WAIT_V(n) asm volatile("s_waitcnt vmcnt(" #n ")" ::: "memory")
; #define PG8_WAIT_L(n) asm volatile("s_waitcnt lgkmcnt(" #n ")" ::: "memory")
; #define PG8_BAR __builtin_amdgcn_s_barrier()
; #define PG8_SCHED __builtin_amdgcn_sched_barrier(0)
; template <class Epi, class Sched>
; DI void gemm_phase(LAS unsigned char* lds, const Gemm g, const Sched& S, const Epi& E) {
;     ...
;     for (int t = 0; t < nt; t += 2) {
;       const bool last = (t == nt - 2);
;       const char* a1 = cA + (size_t)(t + 1) * kstep;
;       const char* a2 = last ? nA : cA + (size_t)(t + 2) * kstep; const char* b2 = last ? nB : cB + (size_t)(t + 2) * kstep;
;       const char* a3 = a2 + kstep; const char* b3 = b2 + kstep;
;       PG8_LDB(B0, 0, 0); PG8_SCHED; PG8_LDA(At, 0, 0); PG8_STAGE(PG8_SA(1, 1), a1 + hstep, voffA);
;       PG8_WAIT_L(8); PG8_BAR; PG8_WAIT_L(0); PG8_MMA(0, 0, At, B0); PG8_BAR; PG8_SCHED;
;       PG8_LDB(B1, 0, 1); PG8_STAGE(PG8_SB(0, 0), b2, voffB);
;       PG8_BAR; PG8_WAIT_L(0); PG8_MMA(0, 1, At, B1); PG8_BAR;
;       PG8_LDA(At, 0, 1); PG8_STAGE(PG8_SA(0, 0), a2, voffA);
;       PG8_BAR; PG8_WAIT_L(0); PG8_MMA(1, 0, At, B0); PG8_BAR; PG8_SCHED;
;       PG8_STAGE(PG8_SB(0, 1), b2 + hstep, voffB);
;       PG8_WAIT_V(6); PG8_BAR; PG8_MMA(1, 1, At, B1); PG8_BAR;
.LBB0_1644:
	ds_read_b128 v[128:131], v224
	ds_read_b128 v[132:135], v224 offset:1024
	ds_read_b128 v[148:151], v224 offset:2048
	ds_read_b128 v[152:155], v224 offset:3072
	ds_read_b128 v[160:163], v159
	ds_read_b128 v[164:167], v159 offset:1024
	ds_read_b128 v[168:171], v159 offset:2048
	ds_read_b128 v[172:175], v159 offset:3072
	ds_read_b128 v[176:179], v159 offset:4096
	ds_read_b128 v[196:199], v159 offset:5120
	ds_read_b128 v[200:203], v159 offset:6144
	ds_read_b128 v[204:207], v159 offset:7168
	ds_read_b128 v[208:211], v225
	ds_read_b128 v[212:215], v225 offset:1024
	ds_read_b128 v[216:219], v225 offset:2048
	ds_read_b128 v[220:223], v225 offset:3072
	s_add_u32 s4, s2, 0xfffc0080
	s_addc_u32 s5, s3, -1
	s_add_i32 s55, 0, 0x10000
	s_cmp_eq_u32 s54, 12
	s_cselect_b32 s29, s19, s5
	s_cselect_b32 s28, s35, s4
	s_cselect_b32 s5, s17, s53
	s_cselect_b32 s4, s51, s52
	s_add_i32 m0, s41, 0xc000
	s_nop 0
	global_load_lds_dwordx4 v142, s[2:3]
	s_add_i32 m0, s41, 0xe000
	s_nop 0
	global_load_lds_dwordx4 v146, s[2:3]
	s_waitcnt vmcnt(8)
	s_waitcnt lgkmcnt(0)
	s_barrier
	v_mfma_f32_16x16x32_bf16 v[124:127], v[128:131], v[160:163], v[124:127]
	v_mfma_f32_16x16x32_bf16 v[120:123], v[148:151], v[160:163], v[120:123]
	v_mfma_f32_16x16x32_bf16 v[108:111], v[128:131], v[168:171], v[108:111]
	v_mfma_f32_16x16x32_bf16 v[104:107], v[148:151], v[168:171], v[104:107]
	v_mfma_f32_16x16x32_bf16 v[92:95], v[128:131], v[176:179], v[92:95]
	v_mfma_f32_16x16x32_bf16 v[88:91], v[148:151], v[176:179], v[88:91]
	v_mfma_f32_16x16x32_bf16 v[76:79], v[128:131], v[200:203], v[76:79]
	v_mfma_f32_16x16x32_bf16 v[72:75], v[148:151], v[200:203], v[72:75]
	v_mfma_f32_16x16x32_bf16 v[124:127], v[132:135], v[164:167], v[124:127]
	v_mfma_f32_16x16x32_bf16 v[120:123], v[152:155], v[164:167], v[120:123]
	v_mfma_f32_16x16x32_bf16 v[108:111], v[132:135], v[172:175], v[108:111]
	v_mfma_f32_16x16x32_bf16 v[104:107], v[152:155], v[172:175], v[104:107]
	v_mfma_f32_16x16x32_bf16 v[92:95], v[132:135], v[196:199], v[92:95]
	v_mfma_f32_16x16x32_bf16 v[88:91], v[152:155], v[196:199], v[88:91]
	v_mfma_f32_16x16x32_bf16 v[76:79], v[132:135], v[204:207], v[76:79]
	v_mfma_f32_16x16x32_bf16 v[72:75], v[152:155], v[204:207], v[72:75]
	v_mfma_f32_16x16x32_bf16 v[116:119], v[208:211], v[160:163], v[116:119]
	v_mfma_f32_16x16x32_bf16 v[112:115], v[216:219], v[160:163], v[112:115]
	v_mfma_f32_16x16x32_bf16 v[100:103], v[208:211], v[168:171], v[100:103]
	v_mfma_f32_16x16x32_bf16 v[96:99], v[216:219], v[168:171], v[96:99]
	v_mfma_f32_16x16x32_bf16 v[84:87], v[208:211], v[176:179], v[84:87]
	v_mfma_f32_16x16x32_bf16 v[80:83], v[216:219], v[176:179], v[80:83]
	v_mfma_f32_16x16x32_bf16 v[68:71], v[208:211], v[200:203], v[68:71]
	v_mfma_f32_16x16x32_bf16 v[64:67], v[216:219], v[200:203], v[64:67]
	v_mfma_f32_16x16x32_bf16 v[116:119], v[212:215], v[164:167], v[116:119]
	v_mfma_f32_16x16x32_bf16 v[112:115], v[220:223], v[164:167], v[112:115]
	v_mfma_f32_16x16x32_bf16 v[100:103], v[212:215], v[172:175], v[100:103]
	v_mfma_f32_16x16x32_bf16 v[96:99], v[220:223], v[172:175], v[96:99]
	v_mfma_f32_16x16x32_bf16 v[84:87], v[212:215], v[196:199], v[84:87]
	v_mfma_f32_16x16x32_bf16 v[80:83], v[220:223], v[196:199], v[80:83]
	v_mfma_f32_16x16x32_bf16 v[68:71], v[212:215], v[204:207], v[68:71]
	v_mfma_f32_16x16x32_bf16 v[64:67], v[220:223], v[204:207], v[64:67]
	s_barrier
	ds_read_b128 v[160:163], v159 offset:16384
	ds_read_b128 v[164:167], v159 offset:17408
	ds_read_b128 v[168:171], v159 offset:18432
	ds_read_b128 v[172:175], v159 offset:19456
	ds_read_b128 v[176:179], v159 offset:20480
	ds_read_b128 v[196:199], v159 offset:21504
	ds_read_b128 v[200:203], v159 offset:22528
	ds_read_b128 v[204:207], v159 offset:23552
	s_add_i32 s58, 0, 0x14000
	s_add_i32 s55, s55, s40
	s_add_u32 vcc_lo, s4, s0
	s_addc_u32 vcc_hi, s5, s1
	s_mov_b32 m0, s55
	s_nop 0
	global_load_lds_dwordx4 v144, s[4:5]
	s_add_i32 m0, s55, 0x2000
	s_nop 0
	global_load_lds_dwordx4 v136, s[4:5]
	s_mov_b32 m0, s41
	s_add_u32 s100, s28, s0
	s_addc_u32 s101, s29, s1
	global_load_lds_dwordx4 v140, s[28:29]
	s_mov_b32 m0, s42
	s_nop 0
	global_load_lds_dwordx4 v138, s[28:29]
	s_add_u32 s56, s4, 0x40000
	s_addc_u32 s57, s5, 0
	s_add_i32 s55, s58, s40
	s_mov_b32 m0, s55
	s_nop 0
	global_load_lds_dwordx4 v144, s[56:57]
	s_add_i32 m0, s55, 0x2000
	s_nop 0
	global_load_lds_dwordx4 v136, s[56:57]
	s_add_i32 s55, 0, 0x18000
	s_waitcnt vmcnt(8)
	s_waitcnt lgkmcnt(0)
	s_barrier
	v_mfma_f32_16x16x32_bf16 v[60:63], v[128:131], v[160:163], v[60:63]
	v_mfma_f32_16x16x32_bf16 v[56:59], v[148:151], v[160:163], v[56:59]
	v_mfma_f32_16x16x32_bf16 v[44:47], v[128:131], v[168:171], v[44:47]
	v_mfma_f32_16x16x32_bf16 v[40:43], v[148:151], v[168:171], v[40:43]
	v_mfma_f32_16x16x32_bf16 v[28:31], v[128:131], v[176:179], v[28:31]
	v_mfma_f32_16x16x32_bf16 v[24:27], v[148:151], v[176:179], v[24:27]
	v_mfma_f32_16x16x32_bf16 v[12:15], v[128:131], v[200:203], v[12:15]
	v_mfma_f32_16x16x32_bf16 v[8:11], v[148:151], v[200:203], v[8:11]
	v_mfma_f32_16x16x32_bf16 v[60:63], v[132:135], v[164:167], v[60:63]
	v_mfma_f32_16x16x32_bf16 v[56:59], v[152:155], v[164:167], v[56:59]
	v_mfma_f32_16x16x32_bf16 v[44:47], v[132:135], v[172:175], v[44:47]
	v_mfma_f32_16x16x32_bf16 v[40:43], v[152:155], v[172:175], v[40:43]
	v_mfma_f32_16x16x32_bf16 v[28:31], v[132:135], v[196:199], v[28:31]
	v_mfma_f32_16x16x32_bf16 v[24:27], v[152:155], v[196:199], v[24:27]
	v_mfma_f32_16x16x32_bf16 v[12:15], v[132:135], v[204:207], v[12:15]
	v_mfma_f32_16x16x32_bf16 v[8:11], v[152:155], v[204:207], v[8:11]
	v_mfma_f32_16x16x32_bf16 v[52:55], v[208:211], v[160:163], v[52:55]
	v_mfma_f32_16x16x32_bf16 v[48:51], v[216:219], v[160:163], v[48:51]
	v_mfma_f32_16x16x32_bf16 v[36:39], v[208:211], v[168:171], v[36:39]
	v_mfma_f32_16x16x32_bf16 v[32:35], v[216:219], v[168:171], v[32:35]
	v_mfma_f32_16x16x32_bf16 v[20:23], v[208:211], v[176:179], v[20:23]
	v_mfma_f32_16x16x32_bf16 v[16:19], v[216:219], v[176:179], v[16:19]
	v_mfma_f32_16x16x32_bf16 v[4:7], v[208:211], v[200:203], v[4:7]
	v_mfma_f32_16x16x32_bf16 v[0:3], v[216:219], v[200:203], v[0:3]
	v_mfma_f32_16x16x32_bf16 v[52:55], v[212:215], v[164:167], v[52:55]
	v_mfma_f32_16x16x32_bf16 v[48:51], v[220:223], v[164:167], v[48:51]
	v_mfma_f32_16x16x32_bf16 v[36:39], v[212:215], v[172:175], v[36:39]
	v_mfma_f32_16x16x32_bf16 v[32:35], v[220:223], v[172:175], v[32:35]
	v_mfma_f32_16x16x32_bf16 v[20:23], v[212:215], v[196:199], v[20:23]
	v_mfma_f32_16x16x32_bf16 v[16:19], v[220:223], v[196:199], v[16:19]
	v_mfma_f32_16x16x32_bf16 v[4:7], v[212:215], v[204:207], v[4:7]
	v_mfma_f32_16x16x32_bf16 v[0:3], v[220:223], v[204:207], v[0:3]
	s_barrier
; #define PG8_STAGE(bufoff, gbase, voff) do { _Pragma("unroll") for (int _i = 0; _i < 2; ++_i) \
;     __builtin_amdgcn_global_load_lds((const unsigned*)((const char*)(gbase) + (voff)[_i]), (LAS unsigned*)(lds + (bufoff) + ldsw + _i * 8192), 16, 0, 0); } while (0)
; #define PG8_LDA(dst, b, h) do { _Pragma("unroll") for (int m = 0; m < 4; ++m) _Pragma("unroll") for (int k = 0; k < 2; ++k) dst[m][k] = *(const LAS bf16x8*)(lds + PG8_SA(b, h) + aoff + m * 2048 + k * 1024); } while (0)
; #define PG8_LDB(dst, b, h) do { _Pragma("unroll") for (int n = 0; n < 2; ++n) _Pragma("unroll") for (int k = 0; k < 2; ++k) dst[n][k] = *(const LAS bf16x8*)(lds + PG8_SB(b, h) + boff + n * 2048 + k * 1024); } while (0)
; #define PG8_MMA(ai, bj, At, Bt) do { __builtin_amdgcn_s_setprio(1); _Pragma("unroll") for (int m = 0; m < 4; ++m) _Pragma("unroll") for (int n = 0; n < 2; ++n) _Pragma("unroll") for (int k = 0; k < 2; ++k) \
;     acc[ai][bj][m][n] = __builtin_amdgcn_mfma_f32_16x16x32_bf16(Bt[n][k], At[m][k], acc[ai][bj][m][n], 0, 0, 0); __builtin_amdgcn_s_setprio(0); } while (0)
; #define PG8_WAIT_L(n) asm volatile("s_waitcnt lgkmcnt(" #n ")" ::: "memory")
; #define PG8_BAR __builtin_amdgcn_s_barrier()
; #define PG8_SCHED __builtin_amdgcn_sched_barrier(0)
; template <class Epi, class Sched>
; DI void gemm_phase(LAS unsigned char* lds, const Gemm g, const Sched& S, const Epi& E) {
;     ...
;       PG8_LDB(B0, 1, 0); PG8_SCHED; PG8_LDA(At, 1, 0); PG8_STAGE(PG8_SA(0, 1), a2 + hstep, voffA);
;       PG8_WAIT_L(8); PG8_BAR; PG8_WAIT_L(0); PG8_MMA(0, 0, At, B0); PG8_BAR; PG8_SCHED;
;       PG8_LDB(B1, 1, 1); PG8_STAGE(PG8_SB(1, 0), b3, voffB);
;       PG8_BAR; PG8_WAIT_L(0); PG8_MMA(0, 1, At, B1); PG8_BAR;
	ds_read_b128 v[128:131], v226
	ds_read_b128 v[132:135], v226 offset:1024
	ds_read_b128 v[148:151], v226 offset:2048
	ds_read_b128 v[152:155], v226 offset:3072
	ds_read_b128 v[160:163], v159 offset:32768
	ds_read_b128 v[164:167], v159 offset:33792
	ds_read_b128 v[168:171], v159 offset:34816
	ds_read_b128 v[172:175], v159 offset:35840
	ds_read_b128 v[176:179], v159 offset:36864
	ds_read_b128 v[196:199], v159 offset:37888
	ds_read_b128 v[200:203], v159 offset:38912
	ds_read_b128 v[204:207], v159 offset:39936
	ds_read_b128 v[208:211], v227
	ds_read_b128 v[212:215], v227 offset:1024
	ds_read_b128 v[216:219], v227 offset:2048
	ds_read_b128 v[220:223], v227 offset:3072
	s_add_u32 s28, s28, 0x40000
	s_addc_u32 s29, s29, 0
	s_mov_b32 m0, s43
	s_nop 0
	global_load_lds_dwordx4 v140, s[28:29]
	s_mov_b32 m0, s44
	s_nop 0
	global_load_lds_dwordx4 v138, s[28:29]
	s_waitcnt vmcnt(8)
	s_waitcnt lgkmcnt(0)
	s_barrier
	v_mfma_f32_16x16x32_bf16 v[124:127], v[128:131], v[160:163], v[124:127]
	v_mfma_f32_16x16x32_bf16 v[120:123], v[148:151], v[160:163], v[120:123]
	v_mfma_f32_16x16x32_bf16 v[108:111], v[128:131], v[168:171], v[108:111]
	v_mfma_f32_16x16x32_bf16 v[104:107], v[148:151], v[168:171], v[104:107]
	v_mfma_f32_16x16x32_bf16 v[92:95], v[128:131], v[176:179], v[92:95]
	v_mfma_f32_16x16x32_bf16 v[88:91], v[148:151], v[176:179], v[88:91]
	v_mfma_f32_16x16x32_bf16 v[76:79], v[128:131], v[200:203], v[76:79]
	v_mfma_f32_16x16x32_bf16 v[72:75], v[148:151], v[200:203], v[72:75]
	v_mfma_f32_16x16x32_bf16 v[124:127], v[132:135], v[164:167], v[124:127]
	v_mfma_f32_16x16x32_bf16 v[120:123], v[152:155], v[164:167], v[120:123]
	v_mfma_f32_16x16x32_bf16 v[108:111], v[132:135], v[172:175], v[108:111]
	v_mfma_f32_16x16x32_bf16 v[104:107], v[152:155], v[172:175], v[104:107]
	v_mfma_f32_16x16x32_bf16 v[92:95], v[132:135], v[196:199], v[92:95]
	v_mfma_f32_16x16x32_bf16 v[88:91], v[152:155], v[196:199], v[88:91]
	v_mfma_f32_16x16x32_bf16 v[76:79], v[132:135], v[204:207], v[76:79]
	v_mfma_f32_16x16x32_bf16 v[72:75], v[152:155], v[204:207], v[72:75]
	v_mfma_f32_16x16x32_bf16 v[116:119], v[208:211], v[160:163], v[116:119]
	v_mfma_f32_16x16x32_bf16 v[112:115], v[216:219], v[160:163], v[112:115]
	v_mfma_f32_16x16x32_bf16 v[100:103], v[208:211], v[168:171], v[100:103]
	v_mfma_f32_16x16x32_bf16 v[96:99], v[216:219], v[168:171], v[96:99]
	v_mfma_f32_16x16x32_bf16 v[84:87], v[208:211], v[176:179], v[84:87]
	v_mfma_f32_16x16x32_bf16 v[80:83], v[216:219], v[176:179], v[80:83]
	v_mfma_f32_16x16x32_bf16 v[68:71], v[208:211], v[200:203], v[68:71]
	v_mfma_f32_16x16x32_bf16 v[64:67], v[216:219], v[200:203], v[64:67]
	v_mfma_f32_16x16x32_bf16 v[116:119], v[212:215], v[164:167], v[116:119]
	v_mfma_f32_16x16x32_bf16 v[112:115], v[220:223], v[164:167], v[112:115]
	v_mfma_f32_16x16x32_bf16 v[100:103], v[212:215], v[172:175], v[100:103]
	v_mfma_f32_16x16x32_bf16 v[96:99], v[220:223], v[172:175], v[96:99]
	v_mfma_f32_16x16x32_bf16 v[84:87], v[212:215], v[196:199], v[84:87]
	v_mfma_f32_16x16x32_bf16 v[80:83], v[220:223], v[196:199], v[80:83]
	v_mfma_f32_16x16x32_bf16 v[68:71], v[212:215], v[204:207], v[68:71]
	v_mfma_f32_16x16x32_bf16 v[64:67], v[220:223], v[204:207], v[64:67]
	s_barrier
; #define PG8_STAGE(bufoff, gbase, voff) do { _Pragma("unroll") for (int _i = 0; _i < 2; ++_i) \
;     __builtin_amdgcn_global_load_lds((const unsigned*)((const char*)(gbase) + (voff)[_i]), (LAS unsigned*)(lds + (bufoff) + ldsw + _i * 8192), 16, 0, 0); } while (0)
; #define PG8_LDA(dst, b, h) do { _Pragma("unroll") for (int m = 0; m < 4; ++m) _Pragma("unroll") for (int k = 0; k < 2; ++k) dst[m][k] = *(const LAS bf16x8*)(lds + PG8_SA(b, h) + aoff + m * 2048 + k * 1024); } while (0)
; #define PG8_MMA(ai, bj, At, Bt) do { __builtin_amdgcn_s_setprio(1); _Pragma("unroll") for (int m = 0; m < 4; ++m) _Pragma("unroll") for (int n = 0; n < 2; ++n) _Pragma("unroll") for (int k = 0; k < 2; ++k) \
;     acc[ai][bj][m][n] = __builtin_amdgcn_mfma_f32_16x16x32_bf16(Bt[n][k], At[m][k], acc[ai][bj][m][n], 0, 0, 0); __builtin_amdgcn_s_setprio(0); } while (0)
; #define PG8_WAIT_V(n) asm volatile("s_waitcnt vmcnt(" #n ")" ::: "memory")
; #define PG8_WAIT_L(n) asm volatile("s_waitcnt lgkmcnt(" #n ")" ::: "memory")
; #define PG8_BAR __builtin_amdgcn_s_barrier()
; #define PG8_SCHED __builtin_amdgcn_sched_barrier(0)
; template <class Epi, class Sched>
; DI void gemm_phase(LAS unsigned char* lds, const Gemm g, const Sched& S, const Epi& E) {
;     ...
;       PG8_LDA(At, 1, 1); PG8_STAGE(PG8_SA(1, 0), a3, voffA);
;       PG8_BAR; PG8_WAIT_L(0); PG8_MMA(1, 0, At, B0); PG8_BAR; PG8_SCHED;
;       PG8_STAGE(PG8_SB(1, 1), b3 + hstep, voffB);
;       PG8_WAIT_V(6); PG8_BAR; PG8_MMA(1, 1, At, B1); PG8_BAR;
;     }
;     E(acc, cur, wr, wc, fr, fq);
;   DI void operator()(const f32x4 (&acc)[2][2][4][2], const pg8::Unit& u, int wr, int wc, int fr_, int fq_) const {
;     ...
;             } else if (EPI == EPI_RESID) {
;               if (n == 0) {
;                 const int f8 = u.pn * 256 + bj * 128 + wc * 32 + 8 * fq;
;                 const f32x4 v1 = acc[ai][bj][m][1];
;                 f32x4 r0, r1;
;                 if (rsrc) {
;                   r0 = *(const f32x4*)(rsrc + (size_t)token * 1024 + f8); r1 = *(const f32x4*)(rsrc + (size_t)token * 1024 + f8 + 4);
	ds_read_b128 v[160:163], v159 offset:49152
	ds_read_b128 v[164:167], v159 offset:50176
	ds_read_b128 v[168:171], v159 offset:51200
	ds_read_b128 v[172:175], v159 offset:52224
	ds_read_b128 v[176:179], v159 offset:53248
	ds_read_b128 v[196:199], v159 offset:54272
	ds_read_b128 v[200:203], v159 offset:55296
	ds_read_b128 v[204:207], v159 offset:56320
	s_add_i32 s28, 0, 0x1c000
	s_add_i32 s29, s55, s40
	s_mov_b32 m0, s29
	s_nop 0
	global_load_lds_dwordx4 v144, vcc
	s_add_i32 m0, s29, 0x2000
	s_nop 0
	global_load_lds_dwordx4 v136, vcc
	s_mov_b32 m0, s49
	s_nop 0
	global_load_lds_dwordx4 v140, s[100:101]
	s_mov_b32 m0, s50
	s_nop 0
	global_load_lds_dwordx4 v138, s[100:101]
	s_add_u32 s4, s4, 0x40080
	s_addc_u32 s5, s5, 0
	s_add_i32 s28, s28, s40
	s_mov_b32 m0, s28
	s_nop 0
	global_load_lds_dwordx4 v144, s[4:5]
	s_add_i32 m0, s28, 0x2000
	s_nop 0
	global_load_lds_dwordx4 v136, s[4:5]
	s_add_i32 s54, s54, 2
	s_add_u32 s2, s2, 0x100
	s_addc_u32 s3, s3, 0
	s_add_u32 s52, s52, 0x100
	s_addc_u32 s53, s53, 0
	s_cmp_gt_u32 s54, 13
	s_waitcnt vmcnt(8)
	s_waitcnt lgkmcnt(0)
	s_barrier
	v_mfma_f32_16x16x32_bf16 v[60:63], v[128:131], v[160:163], v[60:63]
	v_mfma_f32_16x16x32_bf16 v[56:59], v[148:151], v[160:163], v[56:59]
	v_mfma_f32_16x16x32_bf16 v[44:47], v[128:131], v[168:171], v[44:47]
	v_mfma_f32_16x16x32_bf16 v[40:43], v[148:151], v[168:171], v[40:43]
	v_mfma_f32_16x16x32_bf16 v[28:31], v[128:131], v[176:179], v[28:31]
	v_mfma_f32_16x16x32_bf16 v[24:27], v[148:151], v[176:179], v[24:27]
	v_mfma_f32_16x16x32_bf16 v[12:15], v[128:131], v[200:203], v[12:15]
	v_mfma_f32_16x16x32_bf16 v[8:11], v[148:151], v[200:203], v[8:11]
	v_mfma_f32_16x16x32_bf16 v[60:63], v[132:135], v[164:167], v[60:63]
	v_mfma_f32_16x16x32_bf16 v[56:59], v[152:155], v[164:167], v[56:59]
	v_mfma_f32_16x16x32_bf16 v[44:47], v[132:135], v[172:175], v[44:47]
	v_mfma_f32_16x16x32_bf16 v[40:43], v[152:155], v[172:175], v[40:43]
	v_mfma_f32_16x16x32_bf16 v[28:31], v[132:135], v[196:199], v[28:31]
	v_mfma_f32_16x16x32_bf16 v[24:27], v[152:155], v[196:199], v[24:27]
	v_mfma_f32_16x16x32_bf16 v[12:15], v[132:135], v[204:207], v[12:15]
	v_mfma_f32_16x16x32_bf16 v[8:11], v[152:155], v[204:207], v[8:11]
	v_mfma_f32_16x16x32_bf16 v[52:55], v[208:211], v[160:163], v[52:55]
	v_mfma_f32_16x16x32_bf16 v[48:51], v[216:219], v[160:163], v[48:51]
	v_mfma_f32_16x16x32_bf16 v[36:39], v[208:211], v[168:171], v[36:39]
	v_mfma_f32_16x16x32_bf16 v[32:35], v[216:219], v[168:171], v[32:35]
	v_mfma_f32_16x16x32_bf16 v[20:23], v[208:211], v[176:179], v[20:23]
	v_mfma_f32_16x16x32_bf16 v[16:19], v[216:219], v[176:179], v[16:19]
	v_mfma_f32_16x16x32_bf16 v[4:7], v[208:211], v[200:203], v[4:7]
	v_mfma_f32_16x16x32_bf16 v[0:3], v[216:219], v[200:203], v[0:3]
	v_mfma_f32_16x16x32_bf16 v[52:55], v[212:215], v[164:167], v[52:55]
	v_mfma_f32_16x16x32_bf16 v[48:51], v[220:223], v[164:167], v[48:51]
	v_mfma_f32_16x16x32_bf16 v[36:39], v[212:215], v[172:175], v[36:39]
	v_mfma_f32_16x16x32_bf16 v[32:35], v[220:223], v[172:175], v[32:35]
	v_mfma_f32_16x16x32_bf16 v[20:23], v[212:215], v[196:199], v[20:23]
	v_mfma_f32_16x16x32_bf16 v[16:19], v[220:223], v[196:199], v[16:19]
	v_mfma_f32_16x16x32_bf16 v[4:7], v[212:215], v[204:207], v[4:7]
	v_mfma_f32_16x16x32_bf16 v[0:3], v[220:223], v[204:207], v[0:3]
	s_barrier
	s_cbranch_scc0 .LBB0_1644
	s_lshl_b32 s2, s34, 8
	v_mov_b32_e32 v161, v182
	s_add_i32 s2, s2, s47
	v_cndmask_b32_e64 v130, 0, 1, s[14:15]
	v_and_or_b32 v150, v161, 15, s2
	s_lshl_b32 s2, s24, 8
	v_bfe_u32 v160, v161, 4, 2
	s_or_b32 s2, s2, s48
	v_ashrrev_i32_e32 v151, 31, v150
	v_lshl_or_b32 v148, v160, 3, s2
	v_lshlrev_b64 v[128:129], 12, v[150:151]
	v_ashrrev_i32_e32 v149, 31, v148
	v_lshl_add_u64 v[128:129], s[6:7], 0, v[128:129]
	v_cmp_ne_u32_e64 s[2:3], 1, v130
	s_andn2_b64 vcc, exec, s[14:15]
	v_lshl_add_u64 v[154:155], v[148:149], 2, v[128:129]
	s_cbranch_vccnz .LBB0_1647
	global_load_dwordx4 v[132:135], v[154:155], off offset:16
	global_load_dwordx4 v[128:131], v[154:155], off
	s_mov_b64 s[4:5], 0
	s_branch .LBB0_1648

; #define PG8_STAGE(bufoff, gbase, voff) do { _Pragma("unroll") for (int _i = 0; _i < 2; ++_i) \
;     __builtin_amdgcn_global_load_lds((const unsigned*)((const char*)(gbase) + (voff)[_i]), (LAS unsigned*)(lds + (bufoff) + ldsw + _i * 8192), 16, 0, 0); } while (0)
; #define PG8_WAIT_V(n) asm volatile("s_waitcnt vmcnt(" #n ")" ::: "memory")
; #define PG8_BAR __builtin_amdgcn_s_barrier()
; template <class Epi, class Sched>
; DI void gemm_phase(LAS unsigned char* lds, const Gemm g, const Sched& S, const Epi& E) {
;     ...
;   Unit cur, nxt; int ui = 0;
;   if (!S.next(0, cur)) return;
;   f32x4 acc[2][2][4][2];
; #pragma unroll
;   for (int a = 0; a < 2; ++a)
; #pragma unroll
;     for (int b = 0; b < 2; ++b)
; #pragma unroll
;       for (int m = 0; m < 4; ++m)
; #pragma unroll
;         for (int n = 0; n < 2; ++n) acc[a][b][m][n] = (f32x4){0.f, 0.f, 0.f, 0.f};
;   bf16x8 At[4][2], B0[2][2], B1[2][2];
;   const char* cA = (const char*)g.A + (size_t)cur.pm * tstep; const char* cB = (const char*)g.Bt + (size_t)cur.pn * tstep;
;   PG8_STAGE(PG8_SB(0, 0), cB, voffB); PG8_STAGE(PG8_SA(0, 0), cA, voffA); PG8_STAGE(PG8_SB(0, 1), cB + hstep, voffB); PG8_STAGE(PG8_SA(0, 1), cA + hstep, voffA);
;   if (wr == 1) PG8_BAR;
;   PG8_WAIT_V(4); PG8_BAR;
;   PG8_STAGE(PG8_SB(1, 0), cB + kstep, voffB); PG8_STAGE(PG8_SA(1, 0), cA + kstep, voffA); PG8_STAGE(PG8_SB(1, 1), cB + hstep + kstep, voffB);
;   PG8_WAIT_V(6); PG8_BAR;
.LBB0_1821:
	s_lshl_b32 s2, s2, 5
	v_and_b32_e32 v15, 48, v14
	v_lshlrev_b32_e32 v16, 6, v14
	s_movk_i32 s4, 0x3c0
	v_lshlrev_b32_e32 v14, 2, v14
	s_and_b32 s10, s2, 0x60
	s_lshl_b32 s39, s3, 6
	s_lshl_b32 s3, s3, 13
	v_and_or_b32 v15, v16, s4, v15
	v_and_b32_e32 v14, 32, v14
	s_lshl_b32 s2, s10, 7
	v_bitop3_b32 v142, s2, v15, v14 bitop3:0xf6
	s_add_u32 s2, s6, 0xa3a8100
	v_bitop3_b32 v16, v15, s3, v14 bitop3:0xde
	s_addc_u32 s3, s7, 0
	s_add_i32 m0, s29, 0x18000
	v_lshl_add_u64 v[6:7], v[6:7], 0, s[0:1]
	s_waitcnt vmcnt(4)
	s_barrier
	global_load_lds_dwordx4 v[6:7], off
	v_lshl_add_u64 v[4:5], v[4:5], 0, s[0:1]
	s_add_i32 m0, s29, 0x1a000
	s_add_i32 s40, s29, 0x8000
	s_add_i32 s41, s29, 0xa000
	global_load_lds_dwordx4 v[4:5], off
	v_lshl_add_u64 v[2:3], v[2:3], 0, s[0:1]
	s_mov_b32 m0, s40
	s_add_u32 s4, s16, 0x40080
	global_load_lds_dwordx4 v[2:3], off
	v_lshl_add_u64 v[0:1], v[0:1], 0, s[0:1]
	s_mov_b32 m0, s41
	s_addc_u32 s5, s17, 0
	global_load_lds_dwordx4 v[0:1], off
	s_add_i32 m0, s29, 0x1c000
	v_lshl_add_u64 v[0:1], s[4:5], 0, v[132:133]
	global_load_lds_dwordx4 v[0:1], off
	v_lshl_add_u64 v[0:1], s[4:5], 0, v[128:129]
	s_add_i32 m0, s29, 0x1e000
	v_readlane_b32 s4, v240, 49
	global_load_lds_dwordx4 v[0:1], off
	v_lshlrev_b32_e32 v0, 14, v12
	v_and_b32_e32 v0, 0xffff8000, v0
	v_lshl_add_u32 v0, v11, 11, v0
	v_and_b32_e32 v1, 1, v12
	v_lshl_or_b32 v0, v1, 6, v0
	v_lshl_add_u32 v136, v13, 1, v0
	v_lshlrev_b32_e32 v0, 14, v8
	v_and_b32_e32 v0, 0xffff8000, v0
	s_waitcnt vmcnt(6)
	v_lshl_add_u32 v0, v9, 11, v0
	v_and_b32_e32 v1, 1, v8
	v_lshl_or_b32 v0, v1, 6, v0
	v_mov_b32_e32 v137, v145
	v_lshl_add_u32 v138, v10, 1, v0
	v_mov_b32_e32 v139, v145
	s_mov_b32 s43, 0
	v_add_u32_e32 v143, 0, v16
	s_lshl_b32 s24, s10, 1
	v_readlane_b32 s45, v240, 43
	s_mov_b32 s44, s4
	s_barrier
	s_barrier
	v_readlane_b32 s5, v240, 50

; #define PG8_STAGE(bufoff, gbase, voff) do { _Pragma("unroll") for (int _i = 0; _i < 2; ++_i) \
;     __builtin_amdgcn_global_load_lds((const unsigned*)((const char*)(gbase) + (voff)[_i]), (LAS unsigned*)(lds + (bufoff) + ldsw + _i * 8192), 16, 0, 0); } while (0)
; #define PG8_LDA(dst, b, h) do { _Pragma("unroll") for (int m = 0; m < 4; ++m) _Pragma("unroll") for (int k = 0; k < 2; ++k) dst[m][k] = *(const LAS bf16x8*)(lds + PG8_SA(b, h) + aoff + m * 2048 + k * 1024); } while (0)
; #define PG8_LDB(dst, b, h) do { _Pragma("unroll") for (int n = 0; n < 2; ++n) _Pragma("unroll") for (int k = 0; k < 2; ++k) dst[n][k] = *(const LAS bf16x8*)(lds + PG8_SB(b, h) + boff + n * 2048 + k * 1024); } while (0)
; #define PG8_MMA(ai, bj, At, Bt) do { __builtin_amdgcn_s_setprio(1); _Pragma("unroll") for (int m = 0; m < 4; ++m) _Pragma("unroll") for (int n = 0; n < 2; ++n) _Pragma("unroll") for (int k = 0; k < 2; ++k) \
;     acc[ai][bj][m][n] = __builtin_amdgcn_mfma_f32_16x16x32_bf16(Bt[n][k], At[m][k], acc[ai][bj][m][n], 0, 0, 0); __builtin_amdgcn_s_setprio(0); } while (0)
; #define PG8_WAIT_V(n) asm volatile("s_waitcnt vmcnt(" #n ")" ::: "memory")
; #define PG8_WAIT_L(n) asm volatile("s_waitcnt lgkmcnt(" #n ")" ::: "memory")
; #define PG8_BAR __builtin_amdgcn_s_barrier()
; #define PG8_SCHED __builtin_amdgcn_sched_barrier(0)
; template <class Epi, class Sched>
; DI void gemm_phase(LAS unsigned char* lds, const Gemm g, const Sched& S, const Epi& E) {
;     ...
;     for (int t = 0; t < nt; t += 2) {
;       const bool last = (t == nt - 2);
;       const char* a1 = cA + (size_t)(t + 1) * kstep;
;       const char* a2 = last ? nA : cA + (size_t)(t + 2) * kstep; const char* b2 = last ? nB : cB + (size_t)(t + 2) * kstep;
;       const char* a3 = a2 + kstep; const char* b3 = b2 + kstep;
;       PG8_LDB(B0, 0, 0); PG8_SCHED; PG8_LDA(At, 0, 0); PG8_STAGE(PG8_SA(1, 1), a1 + hstep, voffA);
;       PG8_WAIT_L(8); PG8_BAR; PG8_WAIT_L(0); PG8_MMA(0, 0, At, B0); PG8_BAR; PG8_SCHED;
;       PG8_LDB(B1, 0, 1); PG8_STAGE(PG8_SB(0, 0), b2, voffB);
;       PG8_BAR; PG8_WAIT_L(0); PG8_MMA(0, 1, At, B1); PG8_BAR;
;       PG8_LDA(At, 0, 1); PG8_STAGE(PG8_SA(0, 0), a2, voffA);
;       PG8_BAR; PG8_WAIT_L(0); PG8_MMA(1, 0, At, B0); PG8_BAR; PG8_SCHED;
;       PG8_STAGE(PG8_SB(0, 1), b2 + hstep, voffB);
;       PG8_WAIT_V(6); PG8_BAR; PG8_MMA(1, 1, At, B1); PG8_BAR;
.LBB0_1829:
	ds_read_b128 v[146:149], v224
	ds_read_b128 v[150:153], v224 offset:1024
	ds_read_b128 v[154:157], v224 offset:2048
	ds_read_b128 v[158:161], v224 offset:3072
	ds_read_b128 v[162:165], v143
	ds_read_b128 v[166:169], v143 offset:1024
	ds_read_b128 v[170:173], v143 offset:2048
	ds_read_b128 v[174:177], v143 offset:3072
	ds_read_b128 v[178:181], v143 offset:4096
	ds_read_b128 v[196:199], v143 offset:5120
	ds_read_b128 v[200:203], v143 offset:6144
	ds_read_b128 v[204:207], v143 offset:7168
	ds_read_b128 v[208:211], v225
	ds_read_b128 v[212:215], v225 offset:1024
	ds_read_b128 v[216:219], v225 offset:2048
	ds_read_b128 v[220:223], v225 offset:3072
	s_add_u32 s16, s14, 0xfffc0080
	s_addc_u32 s17, s15, -1
	s_add_i32 s51, 0, 0x10000
	s_cmp_eq_u32 s50, 12
	s_cselect_b32 s19, s7, s17
	s_cselect_b32 s18, s46, s16
	s_cselect_b32 s17, s5, s49
	s_cselect_b32 s16, s47, s48
	s_add_i32 m0, s29, 0xc000
	s_nop 0
	global_load_lds_dwordx4 v136, s[14:15]
	s_add_i32 m0, s29, 0xe000
	s_nop 0
	global_load_lds_dwordx4 v138, s[14:15]
	s_waitcnt vmcnt(8)
	s_waitcnt lgkmcnt(0)
	s_barrier
	v_mfma_f32_16x16x32_bf16 v[124:127], v[146:149], v[162:165], v[124:127]
	v_mfma_f32_16x16x32_bf16 v[120:123], v[154:157], v[162:165], v[120:123]
	v_mfma_f32_16x16x32_bf16 v[112:115], v[146:149], v[170:173], v[112:115]
	v_mfma_f32_16x16x32_bf16 v[104:107], v[154:157], v[170:173], v[104:107]
	v_mfma_f32_16x16x32_bf16 v[92:95], v[146:149], v[178:181], v[92:95]
	v_mfma_f32_16x16x32_bf16 v[88:91], v[154:157], v[178:181], v[88:91]
	v_mfma_f32_16x16x32_bf16 v[80:83], v[146:149], v[200:203], v[80:83]
	v_mfma_f32_16x16x32_bf16 v[72:75], v[154:157], v[200:203], v[72:75]
	v_mfma_f32_16x16x32_bf16 v[124:127], v[150:153], v[166:169], v[124:127]
	v_mfma_f32_16x16x32_bf16 v[120:123], v[158:161], v[166:169], v[120:123]
	v_mfma_f32_16x16x32_bf16 v[112:115], v[150:153], v[174:177], v[112:115]
	v_mfma_f32_16x16x32_bf16 v[104:107], v[158:161], v[174:177], v[104:107]
	v_mfma_f32_16x16x32_bf16 v[92:95], v[150:153], v[196:199], v[92:95]
	v_mfma_f32_16x16x32_bf16 v[88:91], v[158:161], v[196:199], v[88:91]
	v_mfma_f32_16x16x32_bf16 v[80:83], v[150:153], v[204:207], v[80:83]
	v_mfma_f32_16x16x32_bf16 v[72:75], v[158:161], v[204:207], v[72:75]
	v_mfma_f32_16x16x32_bf16 v[116:119], v[208:211], v[162:165], v[116:119]
	v_mfma_f32_16x16x32_bf16 v[108:111], v[216:219], v[162:165], v[108:111]
	v_mfma_f32_16x16x32_bf16 v[100:103], v[208:211], v[170:173], v[100:103]
	v_mfma_f32_16x16x32_bf16 v[96:99], v[216:219], v[170:173], v[96:99]
	v_mfma_f32_16x16x32_bf16 v[84:87], v[208:211], v[178:181], v[84:87]
	v_mfma_f32_16x16x32_bf16 v[76:79], v[216:219], v[178:181], v[76:79]
	v_mfma_f32_16x16x32_bf16 v[68:71], v[208:211], v[200:203], v[68:71]
	v_mfma_f32_16x16x32_bf16 v[64:67], v[216:219], v[200:203], v[64:67]
	v_mfma_f32_16x16x32_bf16 v[116:119], v[212:215], v[166:169], v[116:119]
	v_mfma_f32_16x16x32_bf16 v[108:111], v[220:223], v[166:169], v[108:111]
	v_mfma_f32_16x16x32_bf16 v[100:103], v[212:215], v[174:177], v[100:103]
	v_mfma_f32_16x16x32_bf16 v[96:99], v[220:223], v[174:177], v[96:99]
	v_mfma_f32_16x16x32_bf16 v[84:87], v[212:215], v[196:199], v[84:87]
	v_mfma_f32_16x16x32_bf16 v[76:79], v[220:223], v[196:199], v[76:79]
	v_mfma_f32_16x16x32_bf16 v[68:71], v[212:215], v[204:207], v[68:71]
	v_mfma_f32_16x16x32_bf16 v[64:67], v[220:223], v[204:207], v[64:67]
	s_barrier
	ds_read_b128 v[162:165], v143 offset:16384
	ds_read_b128 v[166:169], v143 offset:17408
	ds_read_b128 v[170:173], v143 offset:18432
	ds_read_b128 v[174:177], v143 offset:19456
	ds_read_b128 v[178:181], v143 offset:20480
	ds_read_b128 v[196:199], v143 offset:21504
	ds_read_b128 v[200:203], v143 offset:22528
	ds_read_b128 v[204:207], v143 offset:23552
	s_add_i32 s54, 0, 0x14000
	s_add_i32 s51, s51, s20
	s_add_u32 vcc_lo, s16, s0
	s_addc_u32 vcc_hi, s17, s1
	s_mov_b32 m0, s51
	s_nop 0
	global_load_lds_dwordx4 v132, s[16:17]
	s_add_i32 m0, s51, 0x2000
	s_nop 0
	global_load_lds_dwordx4 v128, s[16:17]
	s_mov_b32 m0, s29
	s_add_u32 s100, s18, s0
	s_addc_u32 s101, s19, s1
	global_load_lds_dwordx4 v134, s[18:19]
	s_mov_b32 m0, s34
	s_nop 0
	global_load_lds_dwordx4 v130, s[18:19]
	s_add_u32 s52, s16, 0x40000
	s_addc_u32 s53, s17, 0
	s_add_i32 s51, s54, s20
	s_mov_b32 m0, s51
	s_nop 0
	global_load_lds_dwordx4 v132, s[52:53]
	s_add_i32 m0, s51, 0x2000
	s_nop 0
	global_load_lds_dwordx4 v128, s[52:53]
	s_add_i32 s51, 0, 0x18000
	s_waitcnt vmcnt(8)
	s_waitcnt lgkmcnt(0)
	s_barrier
	v_mfma_f32_16x16x32_bf16 v[60:63], v[146:149], v[162:165], v[60:63]
	v_mfma_f32_16x16x32_bf16 v[56:59], v[154:157], v[162:165], v[56:59]
	v_mfma_f32_16x16x32_bf16 v[48:51], v[146:149], v[170:173], v[48:51]
	v_mfma_f32_16x16x32_bf16 v[40:43], v[154:157], v[170:173], v[40:43]
	v_mfma_f32_16x16x32_bf16 v[28:31], v[146:149], v[178:181], v[28:31]
	v_mfma_f32_16x16x32_bf16 v[24:27], v[154:157], v[178:181], v[24:27]
	v_mfma_f32_16x16x32_bf16 v[16:19], v[146:149], v[200:203], v[16:19]
	v_mfma_f32_16x16x32_bf16 v[8:11], v[154:157], v[200:203], v[8:11]
	v_mfma_f32_16x16x32_bf16 v[60:63], v[150:153], v[166:169], v[60:63]
	v_mfma_f32_16x16x32_bf16 v[56:59], v[158:161], v[166:169], v[56:59]
	v_mfma_f32_16x16x32_bf16 v[48:51], v[150:153], v[174:177], v[48:51]
	v_mfma_f32_16x16x32_bf16 v[40:43], v[158:161], v[174:177], v[40:43]
	v_mfma_f32_16x16x32_bf16 v[28:31], v[150:153], v[196:199], v[28:31]
	v_mfma_f32_16x16x32_bf16 v[24:27], v[158:161], v[196:199], v[24:27]
	v_mfma_f32_16x16x32_bf16 v[16:19], v[150:153], v[204:207], v[16:19]
	v_mfma_f32_16x16x32_bf16 v[8:11], v[158:161], v[204:207], v[8:11]
	v_mfma_f32_16x16x32_bf16 v[52:55], v[208:211], v[162:165], v[52:55]
	v_mfma_f32_16x16x32_bf16 v[44:47], v[216:219], v[162:165], v[44:47]
	v_mfma_f32_16x16x32_bf16 v[36:39], v[208:211], v[170:173], v[36:39]
	v_mfma_f32_16x16x32_bf16 v[32:35], v[216:219], v[170:173], v[32:35]
	v_mfma_f32_16x16x32_bf16 v[20:23], v[208:211], v[178:181], v[20:23]
	v_mfma_f32_16x16x32_bf16 v[12:15], v[216:219], v[178:181], v[12:15]
	v_mfma_f32_16x16x32_bf16 v[4:7], v[208:211], v[200:203], v[4:7]
	v_mfma_f32_16x16x32_bf16 v[0:3], v[216:219], v[200:203], v[0:3]
	v_mfma_f32_16x16x32_bf16 v[52:55], v[212:215], v[166:169], v[52:55]
	v_mfma_f32_16x16x32_bf16 v[44:47], v[220:223], v[166:169], v[44:47]
	v_mfma_f32_16x16x32_bf16 v[36:39], v[212:215], v[174:177], v[36:39]
	v_mfma_f32_16x16x32_bf16 v[32:35], v[220:223], v[174:177], v[32:35]
	v_mfma_f32_16x16x32_bf16 v[20:23], v[212:215], v[196:199], v[20:23]
	v_mfma_f32_16x16x32_bf16 v[12:15], v[220:223], v[196:199], v[12:15]
	v_mfma_f32_16x16x32_bf16 v[4:7], v[212:215], v[204:207], v[4:7]
	v_mfma_f32_16x16x32_bf16 v[0:3], v[220:223], v[204:207], v[0:3]
	s_barrier
; #define PG8_STAGE(bufoff, gbase, voff) do { _Pragma("unroll") for (int _i = 0; _i < 2; ++_i) \
;     __builtin_amdgcn_global_load_lds((const unsigned*)((const char*)(gbase) + (voff)[_i]), (LAS unsigned*)(lds + (bufoff) + ldsw + _i * 8192), 16, 0, 0); } while (0)
; #define PG8_LDA(dst, b, h) do { _Pragma("unroll") for (int m = 0; m < 4; ++m) _Pragma("unroll") for (int k = 0; k < 2; ++k) dst[m][k] = *(const LAS bf16x8*)(lds + PG8_SA(b, h) + aoff + m * 2048 + k * 1024); } while (0)
; #define PG8_LDB(dst, b, h) do { _Pragma("unroll") for (int n = 0; n < 2; ++n) _Pragma("unroll") for (int k = 0; k < 2; ++k) dst[n][k] = *(const LAS bf16x8*)(lds + PG8_SB(b, h) + boff + n * 2048 + k * 1024); } while (0)
; #define PG8_MMA(ai, bj, At, Bt) do { __builtin_amdgcn_s_setprio(1); _Pragma("unroll") for (int m = 0; m < 4; ++m) _Pragma("unroll") for (int n = 0; n < 2; ++n) _Pragma("unroll") for (int k = 0; k < 2; ++k) \
;     acc[ai][bj][m][n] = __builtin_amdgcn_mfma_f32_16x16x32_bf16(Bt[n][k], At[m][k], acc[ai][bj][m][n], 0, 0, 0); __builtin_amdgcn_s_setprio(0); } while (0)
; #define PG8_WAIT_V(n) asm volatile("s_waitcnt vmcnt(" #n ")" ::: "memory")
; #define PG8_WAIT_L(n) asm volatile("s_waitcnt lgkmcnt(" #n ")" ::: "memory")
; #define PG8_BAR __builtin_amdgcn_s_barrier()
; #define PG8_SCHED __builtin_amdgcn_sched_barrier(0)
; template <class Epi, class Sched>
; DI void gemm_phase(LAS unsigned char* lds, const Gemm g, const Sched& S, const Epi& E) {
;     ...
;       PG8_LDB(B0, 1, 0); PG8_SCHED; PG8_LDA(At, 1, 0); PG8_STAGE(PG8_SA(0, 1), a2 + hstep, voffA);
;       PG8_WAIT_L(8); PG8_BAR; PG8_WAIT_L(0); PG8_MMA(0, 0, At, B0); PG8_BAR; PG8_SCHED;
;       PG8_LDB(B1, 1, 1); PG8_STAGE(PG8_SB(1, 0), b3, voffB);
;       PG8_BAR; PG8_WAIT_L(0); PG8_MMA(0, 1, At, B1); PG8_BAR;
;       PG8_LDA(At, 1, 1); PG8_STAGE(PG8_SA(1, 0), a3, voffA);
;       PG8_BAR; PG8_WAIT_L(0); PG8_MMA(1, 0, At, B0); PG8_BAR; PG8_SCHED;
;       PG8_STAGE(PG8_SB(1, 1), b3 + hstep, voffB);
;       PG8_WAIT_V(6); PG8_BAR; PG8_MMA(1, 1, At, B1); PG8_BAR;
	ds_read_b128 v[146:149], v226
	ds_read_b128 v[150:153], v226 offset:1024
	ds_read_b128 v[154:157], v226 offset:2048
	ds_read_b128 v[158:161], v226 offset:3072
	ds_read_b128 v[162:165], v143 offset:32768
	ds_read_b128 v[166:169], v143 offset:33792
	ds_read_b128 v[170:173], v143 offset:34816
	ds_read_b128 v[174:177], v143 offset:35840
	ds_read_b128 v[178:181], v143 offset:36864
	ds_read_b128 v[196:199], v143 offset:37888
	ds_read_b128 v[200:203], v143 offset:38912
	ds_read_b128 v[204:207], v143 offset:39936
	ds_read_b128 v[208:211], v227
	ds_read_b128 v[212:215], v227 offset:1024
	ds_read_b128 v[216:219], v227 offset:2048
	ds_read_b128 v[220:223], v227 offset:3072
	s_add_u32 s18, s18, 0x40000
	s_addc_u32 s19, s19, 0
	s_mov_b32 m0, s35
	s_nop 0
	global_load_lds_dwordx4 v134, s[18:19]
	s_mov_b32 m0, s38
	s_nop 0
	global_load_lds_dwordx4 v130, s[18:19]
	s_waitcnt vmcnt(8)
	s_waitcnt lgkmcnt(0)
	s_barrier
	v_mfma_f32_16x16x32_bf16 v[124:127], v[146:149], v[162:165], v[124:127]
	v_mfma_f32_16x16x32_bf16 v[120:123], v[154:157], v[162:165], v[120:123]
	v_mfma_f32_16x16x32_bf16 v[112:115], v[146:149], v[170:173], v[112:115]
	v_mfma_f32_16x16x32_bf16 v[104:107], v[154:157], v[170:173], v[104:107]
	v_mfma_f32_16x16x32_bf16 v[92:95], v[146:149], v[178:181], v[92:95]
	v_mfma_f32_16x16x32_bf16 v[88:91], v[154:157], v[178:181], v[88:91]
	v_mfma_f32_16x16x32_bf16 v[80:83], v[146:149], v[200:203], v[80:83]
	v_mfma_f32_16x16x32_bf16 v[72:75], v[154:157], v[200:203], v[72:75]
	v_mfma_f32_16x16x32_bf16 v[124:127], v[150:153], v[166:169], v[124:127]
	v_mfma_f32_16x16x32_bf16 v[120:123], v[158:161], v[166:169], v[120:123]
	v_mfma_f32_16x16x32_bf16 v[112:115], v[150:153], v[174:177], v[112:115]
	v_mfma_f32_16x16x32_bf16 v[104:107], v[158:161], v[174:177], v[104:107]
	v_mfma_f32_16x16x32_bf16 v[92:95], v[150:153], v[196:199], v[92:95]
	v_mfma_f32_16x16x32_bf16 v[88:91], v[158:161], v[196:199], v[88:91]
	v_mfma_f32_16x16x32_bf16 v[80:83], v[150:153], v[204:207], v[80:83]
	v_mfma_f32_16x16x32_bf16 v[72:75], v[158:161], v[204:207], v[72:75]
	v_mfma_f32_16x16x32_bf16 v[116:119], v[208:211], v[162:165], v[116:119]
	v_mfma_f32_16x16x32_bf16 v[108:111], v[216:219], v[162:165], v[108:111]
	v_mfma_f32_16x16x32_bf16 v[100:103], v[208:211], v[170:173], v[100:103]
	v_mfma_f32_16x16x32_bf16 v[96:99], v[216:219], v[170:173], v[96:99]
	v_mfma_f32_16x16x32_bf16 v[84:87], v[208:211], v[178:181], v[84:87]
	v_mfma_f32_16x16x32_bf16 v[76:79], v[216:219], v[178:181], v[76:79]
	v_mfma_f32_16x16x32_bf16 v[68:71], v[208:211], v[200:203], v[68:71]
	v_mfma_f32_16x16x32_bf16 v[64:67], v[216:219], v[200:203], v[64:67]
	v_mfma_f32_16x16x32_bf16 v[116:119], v[212:215], v[166:169], v[116:119]
	v_mfma_f32_16x16x32_bf16 v[108:111], v[220:223], v[166:169], v[108:111]
	v_mfma_f32_16x16x32_bf16 v[100:103], v[212:215], v[174:177], v[100:103]
	v_mfma_f32_16x16x32_bf16 v[96:99], v[220:223], v[174:177], v[96:99]
	v_mfma_f32_16x16x32_bf16 v[84:87], v[212:215], v[196:199], v[84:87]
	v_mfma_f32_16x16x32_bf16 v[76:79], v[220:223], v[196:199], v[76:79]
	v_mfma_f32_16x16x32_bf16 v[68:71], v[212:215], v[204:207], v[68:71]
	v_mfma_f32_16x16x32_bf16 v[64:67], v[220:223], v[204:207], v[64:67]
	s_barrier
	ds_read_b128 v[162:165], v143 offset:49152
	ds_read_b128 v[166:169], v143 offset:50176
	ds_read_b128 v[170:173], v143 offset:51200
	ds_read_b128 v[174:177], v143 offset:52224
	ds_read_b128 v[178:181], v143 offset:53248
	ds_read_b128 v[196:199], v143 offset:54272
	ds_read_b128 v[200:203], v143 offset:55296
	ds_read_b128 v[204:207], v143 offset:56320
	s_add_i32 s18, 0, 0x1c000
	s_add_i32 s19, s51, s20
	s_mov_b32 m0, s19
	s_nop 0
	global_load_lds_dwordx4 v132, vcc
	s_add_i32 m0, s19, 0x2000
	s_nop 0
	global_load_lds_dwordx4 v128, vcc
	s_mov_b32 m0, s40
	s_nop 0
	global_load_lds_dwordx4 v134, s[100:101]
	s_mov_b32 m0, s41
	s_nop 0
	global_load_lds_dwordx4 v130, s[100:101]
	s_add_u32 s16, s16, 0x40080
	s_addc_u32 s17, s17, 0
	s_add_i32 s18, s18, s20
	s_mov_b32 m0, s18
	s_nop 0
	global_load_lds_dwordx4 v132, s[16:17]
	s_add_i32 m0, s18, 0x2000
	s_nop 0
	global_load_lds_dwordx4 v128, s[16:17]
	s_add_i32 s50, s50, 2
	s_add_u32 s14, s14, 0x100
	s_addc_u32 s15, s15, 0
	s_add_u32 s48, s48, 0x100
	s_addc_u32 s49, s49, 0
	s_cmp_gt_u32 s50, 13
	s_waitcnt vmcnt(8)
	s_waitcnt lgkmcnt(0)
	s_barrier
	v_mfma_f32_16x16x32_bf16 v[60:63], v[146:149], v[162:165], v[60:63]
	v_mfma_f32_16x16x32_bf16 v[56:59], v[154:157], v[162:165], v[56:59]
	v_mfma_f32_16x16x32_bf16 v[48:51], v[146:149], v[170:173], v[48:51]
	v_mfma_f32_16x16x32_bf16 v[40:43], v[154:157], v[170:173], v[40:43]
	v_mfma_f32_16x16x32_bf16 v[28:31], v[146:149], v[178:181], v[28:31]
	v_mfma_f32_16x16x32_bf16 v[24:27], v[154:157], v[178:181], v[24:27]
	v_mfma_f32_16x16x32_bf16 v[16:19], v[146:149], v[200:203], v[16:19]
	v_mfma_f32_16x16x32_bf16 v[8:11], v[154:157], v[200:203], v[8:11]
	v_mfma_f32_16x16x32_bf16 v[60:63], v[150:153], v[166:169], v[60:63]
	v_mfma_f32_16x16x32_bf16 v[56:59], v[158:161], v[166:169], v[56:59]
	v_mfma_f32_16x16x32_bf16 v[48:51], v[150:153], v[174:177], v[48:51]
	v_mfma_f32_16x16x32_bf16 v[40:43], v[158:161], v[174:177], v[40:43]
	v_mfma_f32_16x16x32_bf16 v[28:31], v[150:153], v[196:199], v[28:31]
	v_mfma_f32_16x16x32_bf16 v[24:27], v[158:161], v[196:199], v[24:27]
	v_mfma_f32_16x16x32_bf16 v[16:19], v[150:153], v[204:207], v[16:19]
	v_mfma_f32_16x16x32_bf16 v[8:11], v[158:161], v[204:207], v[8:11]
	v_mfma_f32_16x16x32_bf16 v[52:55], v[208:211], v[162:165], v[52:55]
	v_mfma_f32_16x16x32_bf16 v[44:47], v[216:219], v[162:165], v[44:47]
	v_mfma_f32_16x16x32_bf16 v[36:39], v[208:211], v[170:173], v[36:39]
	v_mfma_f32_16x16x32_bf16 v[32:35], v[216:219], v[170:173], v[32:35]
	v_mfma_f32_16x16x32_bf16 v[20:23], v[208:211], v[178:181], v[20:23]
	v_mfma_f32_16x16x32_bf16 v[12:15], v[216:219], v[178:181], v[12:15]
	v_mfma_f32_16x16x32_bf16 v[4:7], v[208:211], v[200:203], v[4:7]
	v_mfma_f32_16x16x32_bf16 v[0:3], v[216:219], v[200:203], v[0:3]
	v_mfma_f32_16x16x32_bf16 v[52:55], v[212:215], v[166:169], v[52:55]
	v_mfma_f32_16x16x32_bf16 v[44:47], v[220:223], v[166:169], v[44:47]
	v_mfma_f32_16x16x32_bf16 v[36:39], v[212:215], v[174:177], v[36:39]
	v_mfma_f32_16x16x32_bf16 v[32:35], v[220:223], v[174:177], v[32:35]
	v_mfma_f32_16x16x32_bf16 v[20:23], v[212:215], v[196:199], v[20:23]
	v_mfma_f32_16x16x32_bf16 v[12:15], v[220:223], v[196:199], v[12:15]
	v_mfma_f32_16x16x32_bf16 v[4:7], v[212:215], v[204:207], v[4:7]
	v_mfma_f32_16x16x32_bf16 v[0:3], v[220:223], v[204:207], v[0:3]
	s_barrier
; DI int get_tid() { int t = threadIdx.x; asm volatile("" : "+v"(t)); return t; }
;   DI void operator()(const f32x4 (&acc)[2][2][4][2], const pg8::Unit& u, int wr, int wc, int fr_, int fq_) const {
;     const int t_ = get_tid();
;     const int fr = t_ & 15, fq = (t_ >> 4) & 3;
;     const int slot = round; round = round + 1;
; #pragma unroll
;     for (int ai = 0; ai < 2; ++ai)
; #pragma unroll
;       for (int m = 0; m < 4; ++m) {
;         const int rl = ai * 128 + wr * 64 + m * 16 + fr;
;         const int token = u.pm * 256 + rl;
;         float rinv = 1.f;
;         if (EPI != EPI_RESID) rinv = rinv_tab[slot * 256 + rl];
;     ...
;             } else {
;               if (n == 0) {
;                 const f32x4 v1 = acc[ai][bj][m][1];
;                 u32x4 o4;
;                 { const float t0 = fmaxf(v[0], 0.f) * rinv, t1 = fmaxf(v[1], 0.f) * rinv, t2 = fmaxf(v[2], 0.f) * rinv, t3 = fmaxf(v[3], 0.f) * rinv;
;                   o4.x = pack2(t0 * t0, t1 * t1); o4.y = pack2(t2 * t2, t3 * t3); }
;                 { const float t0 = fmaxf(v1[0], 0.f) * rinv, t1 = fmaxf(v1[1], 0.f) * rinv, t2 = fmaxf(v1[2], 0.f) * rinv, t3 = fmaxf(v1[3], 0.f) * rinv;
;                   o4.z = pack2(t0 * t0, t1 * t1); o4.w = pack2(t2 * t2, t3 * t3); }
;                 *(u32x4*)((u16*)big + (size_t)token * 4096 + u.pn * 256 + bj * 128 + wc * 32 + 8 * fq) = o4;
;               }
	s_cbranch_scc0 .LBB0_1829
	v_mov_b32_e32 v144, v182
	s_lshl_b32 s5, s43, 10
	s_add_i32 s5, s5, 0
	v_and_or_b32 v141, v144, 15, s39
	v_lshl_add_u32 v140, s44, 8, v141
	v_lshl_add_u32 v141, v141, 2, s5
	v_add_u32_e32 v146, 0x20000, v141
	ds_read2_b32 v[148:149], v146 offset1:16
	v_max_f32_e32 v124, 0, v124
	v_max_f32_e32 v125, 0, v125
	v_max_f32_e32 v126, 0, v126
	v_max_f32_e32 v127, 0, v127
	v_max_f32_e32 v120, 0, v120
	v_max_f32_e32 v121, 0, v121
	s_waitcnt lgkmcnt(0)
	v_pk_mul_f32 v[124:125], v[124:125], v[148:149] op_sel_hi:[1,0]
	v_pk_mul_f32 v[126:127], v[126:127], v[148:149] op_sel_hi:[1,0]
	v_pk_mul_f32 v[120:121], v[120:121], v[148:149] op_sel_hi:[1,0]
	v_pk_mul_f32 v[124:125], v[124:125], v[124:125]
	v_pk_mul_f32 v[126:127], v[126:127], v[126:127]
	v_max_f32_e32 v122, 0, v122
	v_max_f32_e32 v123, 0, v123
	v_pk_mul_f32 v[120:121], v[120:121], v[120:121]
	v_max_f32_e32 v116, 0, v116
	v_max_f32_e32 v117, 0, v117
	v_max_f32_e32 v118, 0, v118
	v_max_f32_e32 v119, 0, v119
	v_max_f32_e32 v108, 0, v108
	v_max_f32_e32 v109, 0, v109
	s_lshl_b32 s14, s45, 8
	v_ashrrev_i32_e32 v141, 31, v140
	v_cvt_pk_bf16_f32 v124, v124, v125
	v_cvt_pk_bf16_f32 v125, v126, v127
	v_cvt_pk_bf16_f32 v126, v120, v121
	v_pk_mul_f32 v[120:121], v[122:123], v[148:149] op_sel_hi:[1,0]
	v_pk_mul_f32 v[116:117], v[116:117], v[148:149] op_sel_hi:[1,0]
	v_pk_mul_f32 v[118:119], v[118:119], v[148:149] op_sel_hi:[1,0]
	v_pk_mul_f32 v[108:109], v[108:109], v[148:149] op_sel_hi:[1,0]
	s_ashr_i32 s15, s14, 31
	v_lshlrev_b64 v[150:151], 13, v[140:141]
	v_pk_mul_f32 v[120:121], v[120:121], v[120:121]
	v_pk_mul_f32 v[116:117], v[116:117], v[116:117]
	v_pk_mul_f32 v[118:119], v[118:119], v[118:119]
	v_max_f32_e32 v110, 0, v110
	v_max_f32_e32 v111, 0, v111
	v_pk_mul_f32 v[108:109], v[108:109], v[108:109]
	v_cvt_pk_bf16_f32 v127, v120, v121
	v_lshl_add_u64 v[120:121], s[2:3], 0, v[150:151]
	s_lshl_b64 s[14:15], s[14:15], 1
	v_cvt_pk_bf16_f32 v116, v116, v117
	v_cvt_pk_bf16_f32 v117, v118, v119
	v_cvt_pk_bf16_f32 v118, v108, v109
	v_pk_mul_f32 v[108:109], v[110:111], v[148:149] op_sel_hi:[1,0]
	v_lshl_add_u64 v[120:121], v[120:121], 0, s[14:15]
	v_pk_mul_f32 v[108:109], v[108:109], v[108:109]
	v_lshl_add_u64 v[120:121], v[120:121], 0, s[24:25]
	v_and_b32_e32 v144, 48, v144
	v_cvt_pk_bf16_f32 v119, v108, v109
	v_add_u32_e32 v108, 16, v140
	v_lshl_add_u64 v[120:121], v[120:121], 0, v[144:145]
	v_ashrrev_i32_e32 v109, 31, v108
	global_store_dwordx4 v[120:121], v[116:119], off offset:256
	v_max_f32_e32 v100, 0, v100
	v_max_f32_e32 v101, 0, v101
	v_lshlrev_b64 v[116:117], 13, v[108:109]
	v_max_f32_e32 v108, v112, v112
	v_mov_b32_e32 v112, v149
	v_max_f32_e32 v102, 0, v102
	v_max_f32_e32 v103, 0, v103
	v_max_f32_e32 v96, 0, v96
	v_max_f32_e32 v97, 0, v97
	v_pk_mul_f32 v[100:101], v[100:101], v[112:113] op_sel_hi:[1,0]
	v_pk_mul_f32 v[102:103], v[102:103], v[112:113] op_sel_hi:[1,0]
	v_pk_mul_f32 v[96:97], v[96:97], v[112:113] op_sel_hi:[1,0]
	v_pk_mul_f32 v[100:101], v[100:101], v[100:101]
	v_pk_mul_f32 v[102:103], v[102:103], v[102:103]
	v_max_f32_e32 v98, 0, v98
	v_max_f32_e32 v99, 0, v99
	v_pk_mul_f32 v[96:97], v[96:97], v[96:97]
	v_cvt_pk_bf16_f32 v100, v100, v101
	v_cvt_pk_bf16_f32 v101, v102, v103
	v_cvt_pk_bf16_f32 v102, v96, v97
	v_pk_mul_f32 v[96:97], v[98:99], v[112:113] op_sel_hi:[1,0]
	ds_read2_b32 v[98:99], v146 offset0:32 offset1:48
	v_max_f32_e32 v92, 0, v92
	v_max_f32_e32 v93, 0, v93
	v_max_f32_e32 v94, 0, v94
	v_max_f32_e32 v95, 0, v95
	v_max_f32_e32 v88, 0, v88
	v_max_f32_e32 v89, 0, v89
	v_pk_mul_f32 v[96:97], v[96:97], v[96:97]
	s_waitcnt lgkmcnt(0)
	v_pk_mul_f32 v[92:93], v[92:93], v[98:99] op_sel_hi:[1,0]
	v_pk_mul_f32 v[94:95], v[94:95], v[98:99] op_sel_hi:[1,0]
	v_pk_mul_f32 v[88:89], v[88:89], v[98:99] op_sel_hi:[1,0]
	v_cvt_pk_bf16_f32 v103, v96, v97
	v_add_u32_e32 v96, 32, v140
	v_pk_mul_f32 v[92:93], v[92:93], v[92:93]
	v_pk_mul_f32 v[94:95], v[94:95], v[94:95]
	v_max_f32_e32 v90, 0, v90
	v_max_f32_e32 v91, 0, v91
	v_pk_mul_f32 v[88:89], v[88:89], v[88:89]
	v_max_f32_e32 v84, 0, v84
	v_max_f32_e32 v85, 0, v85
	v_max_f32_e32 v86, 0, v86
	v_max_f32_e32 v87, 0, v87
	v_max_f32_e32 v76, 0, v76
	v_max_f32_e32 v77, 0, v77
	v_ashrrev_i32_e32 v97, 31, v96
	v_cvt_pk_bf16_f32 v92, v92, v93
	v_cvt_pk_bf16_f32 v93, v94, v95
	v_cvt_pk_bf16_f32 v94, v88, v89
	v_pk_mul_f32 v[88:89], v[90:91], v[98:99] op_sel_hi:[1,0]
	v_pk_mul_f32 v[84:85], v[84:85], v[98:99] op_sel_hi:[1,0]
	v_pk_mul_f32 v[86:87], v[86:87], v[98:99] op_sel_hi:[1,0]
	v_pk_mul_f32 v[76:77], v[76:77], v[98:99] op_sel_hi:[1,0]
	v_lshlrev_b64 v[96:97], 13, v[96:97]
	v_pk_mul_f32 v[88:89], v[88:89], v[88:89]
	v_pk_mul_f32 v[84:85], v[84:85], v[84:85]
	v_pk_mul_f32 v[86:87], v[86:87], v[86:87]
	v_max_f32_e32 v78, 0, v78
	v_max_f32_e32 v79, 0, v79
	v_pk_mul_f32 v[76:77], v[76:77], v[76:77]
	v_cvt_pk_bf16_f32 v95, v88, v89
	v_lshl_add_u64 v[88:89], s[2:3], 0, v[96:97]
	v_cvt_pk_bf16_f32 v84, v84, v85
	v_cvt_pk_bf16_f32 v85, v86, v87
	v_cvt_pk_bf16_f32 v86, v76, v77
	v_pk_mul_f32 v[76:77], v[78:79], v[98:99] op_sel_hi:[1,0]
	v_lshl_add_u64 v[88:89], v[88:89], 0, s[14:15]
	v_pk_mul_f32 v[76:77], v[76:77], v[76:77]
	v_lshl_add_u64 v[88:89], v[88:89], 0, s[24:25]
	v_cvt_pk_bf16_f32 v87, v76, v77
	v_add_u32_e32 v76, 48, v140
	v_lshl_add_u64 v[88:89], v[88:89], 0, v[144:145]
	v_ashrrev_i32_e32 v77, 31, v76
	global_store_dwordx4 v[88:89], v[84:87], off offset:256
	v_max_f32_e32 v68, 0, v68
	v_max_f32_e32 v69, 0, v69
	v_lshlrev_b64 v[84:85], 13, v[76:77]
	v_max_f32_e32 v76, v80, v80
	v_mov_b32_e32 v80, v99
	v_max_f32_e32 v70, 0, v70
	v_max_f32_e32 v71, 0, v71
	v_max_f32_e32 v64, 0, v64
	v_max_f32_e32 v65, 0, v65
	v_pk_mul_f32 v[68:69], v[68:69], v[80:81] op_sel_hi:[1,0]
	v_pk_mul_f32 v[70:71], v[70:71], v[80:81] op_sel_hi:[1,0]
	v_pk_mul_f32 v[64:65], v[64:65], v[80:81] op_sel_hi:[1,0]
	v_pk_mul_f32 v[68:69], v[68:69], v[68:69]
	v_pk_mul_f32 v[70:71], v[70:71], v[70:71]
	v_max_f32_e32 v66, 0, v66
	v_max_f32_e32 v67, 0, v67
	v_pk_mul_f32 v[64:65], v[64:65], v[64:65]
	v_cvt_pk_bf16_f32 v68, v68, v69
	v_cvt_pk_bf16_f32 v69, v70, v71
	v_cvt_pk_bf16_f32 v70, v64, v65
	v_pk_mul_f32 v[64:65], v[66:67], v[80:81] op_sel_hi:[1,0]
	ds_read2_b32 v[66:67], v146 offset0:128 offset1:144
	v_max_f32_e32 v60, 0, v60
	v_max_f32_e32 v61, 0, v61
	v_max_f32_e32 v62, 0, v62
	v_max_f32_e32 v63, 0, v63
	v_max_f32_e32 v56, 0, v56
	v_max_f32_e32 v57, 0, v57
	v_pk_mul_f32 v[64:65], v[64:65], v[64:65]
	s_waitcnt lgkmcnt(0)
;   DI void operator()(const f32x4 (&acc)[2][2][4][2], const pg8::Unit& u, int wr, int wc, int fr_, int fq_) const {
;     ...
;             } else {
;               if (n == 0) {
;                 const f32x4 v1 = acc[ai][bj][m][1];
;                 u32x4 o4;
;                 { const float t0 = fmaxf(v[0], 0.f) * rinv, t1 = fmaxf(v[1], 0.f) * rinv, t2 = fmaxf(v[2], 0.f) * rinv, t3 = fmaxf(v[3], 0.f) * rinv;
;                   o4.x = pack2(t0 * t0, t1 * t1); o4.y = pack2(t2 * t2, t3 * t3); }
;                 { const float t0 = fmaxf(v1[0], 0.f) * rinv, t1 = fmaxf(v1[1], 0.f) * rinv, t2 = fmaxf(v1[2], 0.f) * rinv, t3 = fmaxf(v1[3], 0.f) * rinv;
;                   o4.z = pack2(t0 * t0, t1 * t1); o4.w = pack2(t2 * t2, t3 * t3); }
;                 *(u32x4*)((u16*)big + (size_t)token * 4096 + u.pn * 256 + bj * 128 + wc * 32 + 8 * fq) = o4;
;               }
	v_pk_mul_f32 v[60:61], v[60:61], v[66:67] op_sel_hi:[1,0]
	v_pk_mul_f32 v[62:63], v[62:63], v[66:67] op_sel_hi:[1,0]
	v_pk_mul_f32 v[56:57], v[56:57], v[66:67] op_sel_hi:[1,0]
	v_cvt_pk_bf16_f32 v71, v64, v65
	v_add_u32_e32 v64, 0x80, v140
	v_pk_mul_f32 v[60:61], v[60:61], v[60:61]
	v_pk_mul_f32 v[62:63], v[62:63], v[62:63]
	v_max_f32_e32 v58, 0, v58
	v_max_f32_e32 v59, 0, v59
	v_pk_mul_f32 v[56:57], v[56:57], v[56:57]
	v_max_f32_e32 v52, 0, v52
	v_max_f32_e32 v53, 0, v53
	v_max_f32_e32 v54, 0, v54
	v_max_f32_e32 v55, 0, v55
	v_max_f32_e32 v44, 0, v44
	v_max_f32_e32 v45, 0, v45
	v_ashrrev_i32_e32 v65, 31, v64
	v_cvt_pk_bf16_f32 v60, v60, v61
	v_cvt_pk_bf16_f32 v61, v62, v63
	v_cvt_pk_bf16_f32 v62, v56, v57
	v_pk_mul_f32 v[56:57], v[58:59], v[66:67] op_sel_hi:[1,0]
	v_pk_mul_f32 v[52:53], v[52:53], v[66:67] op_sel_hi:[1,0]
	v_pk_mul_f32 v[54:55], v[54:55], v[66:67] op_sel_hi:[1,0]
	v_pk_mul_f32 v[44:45], v[44:45], v[66:67] op_sel_hi:[1,0]
	v_lshlrev_b64 v[64:65], 13, v[64:65]
	v_pk_mul_f32 v[56:57], v[56:57], v[56:57]
	v_pk_mul_f32 v[52:53], v[52:53], v[52:53]
	v_pk_mul_f32 v[54:55], v[54:55], v[54:55]
	v_max_f32_e32 v46, 0, v46
	v_max_f32_e32 v47, 0, v47
	v_pk_mul_f32 v[44:45], v[44:45], v[44:45]
	v_cvt_pk_bf16_f32 v63, v56, v57
	v_lshl_add_u64 v[56:57], s[2:3], 0, v[64:65]
	v_cvt_pk_bf16_f32 v52, v52, v53
	v_cvt_pk_bf16_f32 v53, v54, v55
	v_cvt_pk_bf16_f32 v54, v44, v45
	v_pk_mul_f32 v[44:45], v[46:47], v[66:67] op_sel_hi:[1,0]
	v_lshl_add_u64 v[56:57], v[56:57], 0, s[14:15]
	v_pk_mul_f32 v[44:45], v[44:45], v[44:45]
	v_lshl_add_u64 v[56:57], v[56:57], 0, s[24:25]
	v_cvt_pk_bf16_f32 v55, v44, v45
	v_add_u32_e32 v44, 0x90, v140
	v_lshl_add_u64 v[56:57], v[56:57], 0, v[144:145]
	v_ashrrev_i32_e32 v45, 31, v44
	global_store_dwordx4 v[56:57], v[52:55], off offset:256
	v_max_f32_e32 v36, 0, v36
	v_max_f32_e32 v37, 0, v37
	v_lshlrev_b64 v[52:53], 13, v[44:45]
	v_max_f32_e32 v44, v48, v48
	v_mov_b32_e32 v48, v67
	v_max_f32_e32 v38, 0, v38
	v_max_f32_e32 v39, 0, v39
	v_max_f32_e32 v32, 0, v32
	v_max_f32_e32 v33, 0, v33
	v_pk_mul_f32 v[36:37], v[36:37], v[48:49] op_sel_hi:[1,0]
	v_pk_mul_f32 v[38:39], v[38:39], v[48:49] op_sel_hi:[1,0]
	v_pk_mul_f32 v[32:33], v[32:33], v[48:49] op_sel_hi:[1,0]
	v_pk_mul_f32 v[36:37], v[36:37], v[36:37]
	v_pk_mul_f32 v[38:39], v[38:39], v[38:39]
	v_max_f32_e32 v34, 0, v34
	v_max_f32_e32 v35, 0, v35
	v_pk_mul_f32 v[32:33], v[32:33], v[32:33]
	v_cvt_pk_bf16_f32 v36, v36, v37
	v_cvt_pk_bf16_f32 v37, v38, v39
	v_cvt_pk_bf16_f32 v38, v32, v33
	v_pk_mul_f32 v[32:33], v[34:35], v[48:49] op_sel_hi:[1,0]
	ds_read2_b32 v[34:35], v146 offset0:160 offset1:176
	v_max_f32_e32 v28, 0, v28
	v_max_f32_e32 v29, 0, v29
	v_max_f32_e32 v30, 0, v30
	v_max_f32_e32 v31, 0, v31
	v_max_f32_e32 v24, 0, v24
	v_max_f32_e32 v25, 0, v25
	v_pk_mul_f32 v[32:33], v[32:33], v[32:33]
	s_waitcnt lgkmcnt(0)
	v_pk_mul_f32 v[28:29], v[28:29], v[34:35] op_sel_hi:[1,0]
	v_pk_mul_f32 v[30:31], v[30:31], v[34:35] op_sel_hi:[1,0]
	v_pk_mul_f32 v[24:25], v[24:25], v[34:35] op_sel_hi:[1,0]
	v_cvt_pk_bf16_f32 v39, v32, v33
	v_add_u32_e32 v32, 0xa0, v140
	v_pk_mul_f32 v[28:29], v[28:29], v[28:29]
	v_pk_mul_f32 v[30:31], v[30:31], v[30:31]
	v_max_f32_e32 v26, 0, v26
	v_max_f32_e32 v27, 0, v27
	v_pk_mul_f32 v[24:25], v[24:25], v[24:25]
	v_max_f32_e32 v20, 0, v20
	v_max_f32_e32 v21, 0, v21
	v_max_f32_e32 v22, 0, v22
	v_max_f32_e32 v23, 0, v23
	v_max_f32_e32 v12, 0, v12
	v_max_f32_e32 v13, 0, v13
	v_ashrrev_i32_e32 v33, 31, v32
	v_cvt_pk_bf16_f32 v28, v28, v29
	v_cvt_pk_bf16_f32 v29, v30, v31
	v_cvt_pk_bf16_f32 v30, v24, v25
	v_pk_mul_f32 v[24:25], v[26:27], v[34:35] op_sel_hi:[1,0]
	v_pk_mul_f32 v[20:21], v[20:21], v[34:35] op_sel_hi:[1,0]
	v_pk_mul_f32 v[22:23], v[22:23], v[34:35] op_sel_hi:[1,0]
	v_pk_mul_f32 v[12:13], v[12:13], v[34:35] op_sel_hi:[1,0]
	v_lshlrev_b64 v[32:33], 13, v[32:33]
	v_pk_mul_f32 v[24:25], v[24:25], v[24:25]
	v_pk_mul_f32 v[20:21], v[20:21], v[20:21]
	v_pk_mul_f32 v[22:23], v[22:23], v[22:23]
	v_max_f32_e32 v14, 0, v14
	v_max_f32_e32 v15, 0, v15
	v_pk_mul_f32 v[12:13], v[12:13], v[12:13]
	v_cvt_pk_bf16_f32 v31, v24, v25
	v_lshl_add_u64 v[24:25], s[2:3], 0, v[32:33]
	v_cvt_pk_bf16_f32 v20, v20, v21
	v_cvt_pk_bf16_f32 v21, v22, v23
	v_cvt_pk_bf16_f32 v22, v12, v13
	v_pk_mul_f32 v[12:13], v[14:15], v[34:35] op_sel_hi:[1,0]
	v_lshl_add_u64 v[24:25], v[24:25], 0, s[14:15]
	v_pk_mul_f32 v[12:13], v[12:13], v[12:13]
	v_lshl_add_u64 v[24:25], v[24:25], 0, s[24:25]
	v_cvt_pk_bf16_f32 v23, v12, v13
	v_add_u32_e32 v12, 0xb0, v140
	v_lshl_add_u64 v[24:25], v[24:25], 0, v[144:145]
	v_ashrrev_i32_e32 v13, 31, v12
	v_max_f32_e32 v109, v113, v113
	v_max_f32_e32 v110, v114, v114
	v_max_f32_e32 v111, v115, v115
	v_max_f32_e32 v77, v81, v81
	v_max_f32_e32 v78, v82, v82
	v_max_f32_e32 v79, v83, v83
	v_max_f32_e32 v45, v49, v49
	v_max_f32_e32 v46, v50, v50
	v_max_f32_e32 v47, v51, v51
	global_store_dwordx4 v[24:25], v[20:23], off offset:256
	v_max_f32_e32 v14, v18, v18
	v_max_f32_e32 v15, v19, v19
	v_lshlrev_b64 v[20:21], 13, v[12:13]
	v_max_f32_e32 v12, v16, v16
	v_max_f32_e32 v13, v17, v17
	v_max_f32_e32 v108, 0, v108
	v_max_f32_e32 v109, 0, v109
	v_max_f32_e32 v110, 0, v110
	v_max_f32_e32 v111, 0, v111
	v_max_f32_e32 v104, 0, v104
	v_max_f32_e32 v105, 0, v105
	v_max_f32_e32 v76, 0, v76
; #define PG8_WAIT_V(n) asm volatile("s_waitcnt vmcnt(" #n ")" ::: "memory")
; #define PG8_BAR __builtin_amdgcn_s_barrier()
; template <class Epi, class Sched>
; DI void gemm_phase(LAS unsigned char* lds, const Gemm g, const Sched& S, const Epi& E) {
;     ...
;     E(acc, cur, wr, wc, fr, fq);
;     if (!has_next) break;
; #pragma unroll
;     for (int a = 0; a < 2; ++a)
; #pragma unroll
;       for (int b = 0; b < 2; ++b)
; #pragma unroll
;         for (int m = 0; m < 4; ++m)
; #pragma unroll
;           for (int n = 0; n < 2; ++n) acc[a][b][m][n] = (f32x4){0.f, 0.f, 0.f, 0.f};
;     cur = nxt; cA = nA; cB = nB; ++ui;
;   }
;   PG8_WAIT_V(0);
;   if (wr == 0) PG8_BAR;
;   PG8_BAR;
;   DI void operator()(const f32x4 (&acc)[2][2][4][2], const pg8::Unit& u, int wr, int wc, int fr_, int fq_) const {
;     ...
;             } else {
;               if (n == 0) {
;                 const f32x4 v1 = acc[ai][bj][m][1];
;                 u32x4 o4;
;                 { const float t0 = fmaxf(v[0], 0.f) * rinv, t1 = fmaxf(v[1], 0.f) * rinv, t2 = fmaxf(v[2], 0.f) * rinv, t3 = fmaxf(v[3], 0.f) * rinv;
;                   o4.x = pack2(t0 * t0, t1 * t1); o4.y = pack2(t2 * t2, t3 * t3); }
;                 { const float t0 = fmaxf(v1[0], 0.f) * rinv, t1 = fmaxf(v1[1], 0.f) * rinv, t2 = fmaxf(v1[2], 0.f) * rinv, t3 = fmaxf(v1[3], 0.f) * rinv;
;                   o4.z = pack2(t0 * t0, t1 * t1); o4.w = pack2(t2 * t2, t3 * t3); }
;                 *(u32x4*)((u16*)big + (size_t)token * 4096 + u.pn * 256 + bj * 128 + wc * 32 + 8 * fq) = o4;
;               }
	v_max_f32_e32 v77, 0, v77
	v_max_f32_e32 v78, 0, v78
	v_max_f32_e32 v79, 0, v79
	v_max_f32_e32 v72, 0, v72
	v_max_f32_e32 v73, 0, v73
	v_max_f32_e32 v44, 0, v44
	v_max_f32_e32 v45, 0, v45
	v_max_f32_e32 v46, 0, v46
	v_max_f32_e32 v47, 0, v47
	v_max_f32_e32 v40, 0, v40
	v_max_f32_e32 v41, 0, v41
	v_max_f32_e32 v12, 0, v12
	v_max_f32_e32 v13, 0, v13
	v_max_f32_e32 v14, 0, v14
	v_max_f32_e32 v15, 0, v15
	v_mov_b32_e32 v16, v35
	v_max_f32_e32 v8, 0, v8
	v_max_f32_e32 v9, 0, v9
	v_pk_mul_f32 v[108:109], v[108:109], v[112:113] op_sel_hi:[1,0]
	v_pk_mul_f32 v[110:111], v[110:111], v[112:113] op_sel_hi:[1,0]
	v_pk_mul_f32 v[104:105], v[104:105], v[112:113] op_sel_hi:[1,0]
	v_pk_mul_f32 v[76:77], v[76:77], v[80:81] op_sel_hi:[1,0]
	v_pk_mul_f32 v[78:79], v[78:79], v[80:81] op_sel_hi:[1,0]
	v_pk_mul_f32 v[72:73], v[72:73], v[80:81] op_sel_hi:[1,0]
	v_pk_mul_f32 v[44:45], v[44:45], v[48:49] op_sel_hi:[1,0]
	v_pk_mul_f32 v[46:47], v[46:47], v[48:49] op_sel_hi:[1,0]
	v_pk_mul_f32 v[40:41], v[40:41], v[48:49] op_sel_hi:[1,0]
	v_pk_mul_f32 v[12:13], v[12:13], v[16:17] op_sel_hi:[1,0]
	v_pk_mul_f32 v[14:15], v[14:15], v[16:17] op_sel_hi:[1,0]
	v_pk_mul_f32 v[8:9], v[8:9], v[16:17] op_sel_hi:[1,0]
	v_pk_mul_f32 v[108:109], v[108:109], v[108:109]
	v_pk_mul_f32 v[110:111], v[110:111], v[110:111]
	v_max_f32_e32 v106, 0, v106
	v_max_f32_e32 v107, 0, v107
	v_pk_mul_f32 v[104:105], v[104:105], v[104:105]
	v_pk_mul_f32 v[76:77], v[76:77], v[76:77]
	v_pk_mul_f32 v[78:79], v[78:79], v[78:79]
	v_max_f32_e32 v74, 0, v74
	v_max_f32_e32 v75, 0, v75
	v_pk_mul_f32 v[72:73], v[72:73], v[72:73]
	v_pk_mul_f32 v[44:45], v[44:45], v[44:45]
	v_pk_mul_f32 v[46:47], v[46:47], v[46:47]
	v_max_f32_e32 v42, 0, v42
	v_max_f32_e32 v43, 0, v43
	v_pk_mul_f32 v[40:41], v[40:41], v[40:41]
	v_pk_mul_f32 v[12:13], v[12:13], v[12:13]
	v_pk_mul_f32 v[14:15], v[14:15], v[14:15]
	v_max_f32_e32 v10, 0, v10
	v_max_f32_e32 v11, 0, v11
	v_pk_mul_f32 v[8:9], v[8:9], v[8:9]
	v_cvt_pk_bf16_f32 v108, v108, v109
	v_cvt_pk_bf16_f32 v109, v110, v111
	v_cvt_pk_bf16_f32 v110, v104, v105
	v_pk_mul_f32 v[104:105], v[106:107], v[112:113] op_sel_hi:[1,0]
	v_cvt_pk_bf16_f32 v76, v76, v77
	v_cvt_pk_bf16_f32 v77, v78, v79
	v_cvt_pk_bf16_f32 v78, v72, v73
	v_pk_mul_f32 v[72:73], v[74:75], v[80:81] op_sel_hi:[1,0]
	v_cvt_pk_bf16_f32 v44, v44, v45
	v_cvt_pk_bf16_f32 v45, v46, v47
	v_cvt_pk_bf16_f32 v46, v40, v41
	v_pk_mul_f32 v[40:41], v[42:43], v[48:49] op_sel_hi:[1,0]
	v_cvt_pk_bf16_f32 v12, v12, v13
	v_cvt_pk_bf16_f32 v13, v14, v15
	v_cvt_pk_bf16_f32 v14, v8, v9
	v_pk_mul_f32 v[8:9], v[10:11], v[16:17] op_sel_hi:[1,0]
	v_max_f32_e32 v4, 0, v4
	v_max_f32_e32 v5, 0, v5
	v_max_f32_e32 v6, 0, v6
	v_max_f32_e32 v7, 0, v7
	v_max_f32_e32 v0, 0, v0
	v_max_f32_e32 v1, 0, v1
	v_pk_mul_f32 v[104:105], v[104:105], v[104:105]
	v_pk_mul_f32 v[72:73], v[72:73], v[72:73]
	v_pk_mul_f32 v[40:41], v[40:41], v[40:41]
	v_pk_mul_f32 v[8:9], v[8:9], v[8:9]
	v_pk_mul_f32 v[4:5], v[4:5], v[16:17] op_sel_hi:[1,0]
	v_pk_mul_f32 v[6:7], v[6:7], v[16:17] op_sel_hi:[1,0]
	v_pk_mul_f32 v[0:1], v[0:1], v[16:17] op_sel_hi:[1,0]
	v_cvt_pk_bf16_f32 v111, v104, v105
	v_lshl_add_u64 v[104:105], s[2:3], 0, v[116:117]
	v_cvt_pk_bf16_f32 v79, v72, v73
	v_lshl_add_u64 v[72:73], s[2:3], 0, v[84:85]
	v_cvt_pk_bf16_f32 v47, v40, v41
	v_lshl_add_u64 v[40:41], s[2:3], 0, v[52:53]
	v_cvt_pk_bf16_f32 v15, v8, v9
	v_lshl_add_u64 v[8:9], s[2:3], 0, v[20:21]
	v_pk_mul_f32 v[4:5], v[4:5], v[4:5]
	v_pk_mul_f32 v[6:7], v[6:7], v[6:7]
	v_max_f32_e32 v2, 0, v2
	v_max_f32_e32 v3, 0, v3
	v_pk_mul_f32 v[0:1], v[0:1], v[0:1]
	v_lshl_add_u64 v[104:105], v[104:105], 0, s[14:15]
	v_lshl_add_u64 v[72:73], v[72:73], 0, s[14:15]
	v_lshl_add_u64 v[40:41], v[40:41], 0, s[14:15]
	v_lshl_add_u64 v[8:9], v[8:9], 0, s[14:15]
	v_cvt_pk_bf16_f32 v4, v4, v5
	v_cvt_pk_bf16_f32 v5, v6, v7
	v_cvt_pk_bf16_f32 v6, v0, v1
	v_pk_mul_f32 v[0:1], v[2:3], v[16:17] op_sel_hi:[1,0]
	v_lshl_add_u64 v[104:105], v[104:105], 0, s[24:25]
	v_lshl_add_u64 v[72:73], v[72:73], 0, s[24:25]
	v_lshl_add_u64 v[40:41], v[40:41], 0, s[24:25]
	v_lshl_add_u64 v[8:9], v[8:9], 0, s[24:25]
	v_pk_mul_f32 v[0:1], v[0:1], v[0:1]
	v_lshl_add_u64 v[104:105], v[104:105], 0, v[144:145]
	v_lshl_add_u64 v[72:73], v[72:73], 0, v[144:145]
	v_lshl_add_u64 v[40:41], v[40:41], 0, v[144:145]
	v_lshl_add_u64 v[8:9], v[8:9], 0, v[144:145]
	v_cvt_pk_bf16_f32 v7, v0, v1
	s_and_b64 vcc, exec, s[36:37]
	s_mov_b32 s43, s42
	s_mov_b32 s45, s4
	s_mov_b32 s44, s6
	s_mov_b64 s[16:17], s[12:13]
	s_mov_b64 s[14:15], s[10:11]
	v_readlane_b32 s51, v237, 11
	global_store_dwordx4 v[120:121], v[124:127], off
	global_store_dwordx4 v[104:105], v[108:111], off
	global_store_dwordx4 v[104:105], v[100:103], off offset:256
	global_store_dwordx4 v[88:89], v[92:95], off
	global_store_dwordx4 v[72:73], v[76:79], off
	global_store_dwordx4 v[72:73], v[68:71], off offset:256
	global_store_dwordx4 v[56:57], v[60:63], off
	global_store_dwordx4 v[40:41], v[44:47], off
	global_store_dwordx4 v[40:41], v[36:39], off offset:256
	global_store_dwordx4 v[24:25], v[28:31], off
	global_store_dwordx4 v[8:9], v[12:15], off
	global_store_dwordx4 v[8:9], v[4:7], off offset:256
	s_cbranch_vccz .LBB0_1822
	s_waitcnt vmcnt(0)
	s_cmpk_gt_u32 s9, 0xff
	s_cbranch_scc1 .LBB0_1833
	s_barrier

; #define PG8_STAGE(bufoff, gbase, voff) do { _Pragma("unroll") for (int _i = 0; _i < 2; ++_i) \
;     __builtin_amdgcn_global_load_lds((const unsigned*)((const char*)(gbase) + (voff)[_i]), (LAS unsigned*)(lds + (bufoff) + ldsw + _i * 8192), 16, 0, 0); } while (0)
; #define PG8_WAIT_V(n) asm volatile("s_waitcnt vmcnt(" #n ")" ::: "memory")
; #define PG8_BAR __builtin_amdgcn_s_barrier()
; template <class Epi, class Sched>
; DI void gemm_phase(LAS unsigned char* lds, const Gemm g, const Sched& S, const Epi& E) {
;     ...
;   Unit cur, nxt; int ui = 0;
;   if (!S.next(0, cur)) return;
;   f32x4 acc[2][2][4][2];
; #pragma unroll
;   for (int a = 0; a < 2; ++a)
; #pragma unroll
;     for (int b = 0; b < 2; ++b)
; #pragma unroll
;       for (int m = 0; m < 4; ++m)
; #pragma unroll
;         for (int n = 0; n < 2; ++n) acc[a][b][m][n] = (f32x4){0.f, 0.f, 0.f, 0.f};
;   bf16x8 At[4][2], B0[2][2], B1[2][2];
;   const char* cA = (const char*)g.A + (size_t)cur.pm * tstep; const char* cB = (const char*)g.Bt + (size_t)cur.pn * tstep;
;   PG8_STAGE(PG8_SB(0, 0), cB, voffB); PG8_STAGE(PG8_SA(0, 0), cA, voffA); PG8_STAGE(PG8_SB(0, 1), cB + hstep, voffB); PG8_STAGE(PG8_SA(0, 1), cA + hstep, voffA);
;   if (wr == 1) PG8_BAR;
;   PG8_WAIT_V(4); PG8_BAR;
;   PG8_STAGE(PG8_SB(1, 0), cB + kstep, voffB); PG8_STAGE(PG8_SA(1, 0), cA + kstep, voffA); PG8_STAGE(PG8_SB(1, 1), cB + hstep + kstep, voffB);
;   PG8_WAIT_V(6); PG8_BAR;
.LBB0_1896:
	s_add_u32 s2, s4, 0x5fa4100
	s_addc_u32 s3, s5, 0
	s_add_u32 s4, s4, 0x1a3a8100
	s_addc_u32 s5, s5, 0
	s_and_b32 s43, s7, 3
	v_and_b32_e32 v15, 48, v8
	v_lshlrev_b32_e32 v16, 6, v8
	s_movk_i32 s7, 0x3c0
	v_lshlrev_b32_e32 v8, 2, v8
	s_lshl_b32 s44, s6, 6
	s_lshl_b32 s6, s6, 13
	v_and_or_b32 v15, v16, s7, v15
	v_and_b32_e32 v8, 32, v8
	s_add_i32 m0, s39, 0x18000
	v_lshl_add_u64 v[6:7], v[6:7], 0, s[0:1]
	v_bitop3_b32 v16, v15, s6, v8 bitop3:0xde
	s_lshl_b32 s45, s43, 5
	s_lshl_b32 s6, s43, 12
	s_waitcnt vmcnt(4)
	s_barrier
	global_load_lds_dwordx4 v[6:7], off
	v_lshl_add_u64 v[4:5], v[4:5], 0, s[0:1]
	s_add_i32 m0, s39, 0x1a000
	s_add_i32 s46, s39, 0x8000
	s_add_i32 s47, s39, 0xa000
	v_bitop3_b32 v146, v15, s6, v8 bitop3:0xde
	global_load_lds_dwordx4 v[4:5], off
	v_lshl_add_u64 v[2:3], v[2:3], 0, s[0:1]
	s_mov_b32 m0, s46
	s_add_u32 s6, s22, 0x100080
	global_load_lds_dwordx4 v[2:3], off
	v_lshl_add_u64 v[0:1], v[0:1], 0, s[0:1]
	s_mov_b32 m0, s47
	s_addc_u32 s7, s23, 0
	global_load_lds_dwordx4 v[0:1], off
	s_add_i32 m0, s39, 0x1c000
	v_lshl_add_u64 v[0:1], s[6:7], 0, v[144:145]
	global_load_lds_dwordx4 v[0:1], off
	v_lshl_add_u64 v[0:1], s[6:7], 0, v[132:133]
	s_add_i32 m0, s39, 0x1e000
	v_mov_b32_e32 v135, v145
	global_load_lds_dwordx4 v[0:1], off
	v_lshlrev_b32_e32 v0, 16, v9
	v_and_b32_e32 v0, 0xfffe0000, v0
	v_lshl_add_u32 v0, v10, 13, v0
	v_and_b32_e32 v1, 1, v9
	v_lshl_or_b32 v0, v1, 6, v0
	v_lshl_add_u32 v134, v11, 1, v0
	v_lshlrev_b32_e32 v0, 16, v12
	v_and_b32_e32 v0, 0xfffe0000, v0
	s_waitcnt vmcnt(6)
	v_lshl_add_u32 v0, v13, 13, v0
	v_and_b32_e32 v1, 1, v12
	v_lshl_or_b32 v0, v1, 6, v0
	v_lshl_add_u32 v136, v14, 1, v0
	v_mov_b32_e32 v137, v145
	s_mov_b32 s7, 0
	v_add_u32_e32 v147, 0, v16
	s_barrier
	s_barrier
	s_branch .LBB0_1898

; #define PG8_STAGE(bufoff, gbase, voff) do { _Pragma("unroll") for (int _i = 0; _i < 2; ++_i) \
;     __builtin_amdgcn_global_load_lds((const unsigned*)((const char*)(gbase) + (voff)[_i]), (LAS unsigned*)(lds + (bufoff) + ldsw + _i * 8192), 16, 0, 0); } while (0)
; #define PG8_LDA(dst, b, h) do { _Pragma("unroll") for (int m = 0; m < 4; ++m) _Pragma("unroll") for (int k = 0; k < 2; ++k) dst[m][k] = *(const LAS bf16x8*)(lds + PG8_SA(b, h) + aoff + m * 2048 + k * 1024); } while (0)
; #define PG8_LDB(dst, b, h) do { _Pragma("unroll") for (int n = 0; n < 2; ++n) _Pragma("unroll") for (int k = 0; k < 2; ++k) dst[n][k] = *(const LAS bf16x8*)(lds + PG8_SB(b, h) + boff + n * 2048 + k * 1024); } while (0)
; #define PG8_MMA(ai, bj, At, Bt) do { __builtin_amdgcn_s_setprio(1); _Pragma("unroll") for (int m = 0; m < 4; ++m) _Pragma("unroll") for (int n = 0; n < 2; ++n) _Pragma("unroll") for (int k = 0; k < 2; ++k) \
;     acc[ai][bj][m][n] = __builtin_amdgcn_mfma_f32_16x16x32_bf16(Bt[n][k], At[m][k], acc[ai][bj][m][n], 0, 0, 0); __builtin_amdgcn_s_setprio(0); } while (0)
; #define PG8_WAIT_V(n) asm volatile("s_waitcnt vmcnt(" #n ")" ::: "memory")
; #define PG8_WAIT_L(n) asm volatile("s_waitcnt lgkmcnt(" #n ")" ::: "memory")
; #define PG8_BAR __builtin_amdgcn_s_barrier()
; #define PG8_SCHED __builtin_amdgcn_sched_barrier(0)
; template <class Epi, class Sched>
; DI void gemm_phase(LAS unsigned char* lds, const Gemm g, const Sched& S, const Epi& E) {
;     ...
;     for (int t = 0; t < nt; t += 2) {
;       const bool last = (t == nt - 2);
;       const char* a1 = cA + (size_t)(t + 1) * kstep;
;       const char* a2 = last ? nA : cA + (size_t)(t + 2) * kstep; const char* b2 = last ? nB : cB + (size_t)(t + 2) * kstep;
;       const char* a3 = a2 + kstep; const char* b3 = b2 + kstep;
;       PG8_LDB(B0, 0, 0); PG8_SCHED; PG8_LDA(At, 0, 0); PG8_STAGE(PG8_SA(1, 1), a1 + hstep, voffA);
;       PG8_WAIT_L(8); PG8_BAR; PG8_WAIT_L(0); PG8_MMA(0, 0, At, B0); PG8_BAR; PG8_SCHED;
;       PG8_LDB(B1, 0, 1); PG8_STAGE(PG8_SB(0, 0), b2, voffB);
;       PG8_BAR; PG8_WAIT_L(0); PG8_MMA(0, 1, At, B1); PG8_BAR;
;       PG8_LDA(At, 0, 1); PG8_STAGE(PG8_SA(0, 0), a2, voffA);
;       PG8_BAR; PG8_WAIT_L(0); PG8_MMA(1, 0, At, B0); PG8_BAR; PG8_SCHED;
;       PG8_STAGE(PG8_SB(0, 1), b2 + hstep, voffB);
;       PG8_WAIT_V(6); PG8_BAR; PG8_MMA(1, 1, At, B1); PG8_BAR;
.LBB0_1905:
	ds_read_b128 v[138:141], v224
	ds_read_b128 v[148:151], v224 offset:1024
	ds_read_b128 v[152:155], v224 offset:2048
	ds_read_b128 v[156:159], v224 offset:3072
	ds_read_b128 v[160:163], v147
	ds_read_b128 v[164:167], v147 offset:1024
	ds_read_b128 v[168:171], v147 offset:2048
	ds_read_b128 v[172:175], v147 offset:3072
	ds_read_b128 v[176:179], v147 offset:4096
	ds_read_b128 v[196:199], v147 offset:5120
	ds_read_b128 v[200:203], v147 offset:6144
	ds_read_b128 v[204:207], v147 offset:7168
	ds_read_b128 v[208:211], v225
	ds_read_b128 v[212:215], v225 offset:1024
	ds_read_b128 v[216:219], v225 offset:2048
	ds_read_b128 v[220:223], v225 offset:3072
	s_add_u32 s22, s20, 0xfff00080
	s_addc_u32 s23, s21, -1
	s_add_i32 s51, 0, 0x10000
	s_cmp_eq_u32 s50, 60
	s_cselect_b32 s29, s11, s23
	s_cselect_b32 s28, s17, s22
	s_cselect_b32 s23, s7, s49
	s_cselect_b32 s22, s19, s24
	s_add_i32 m0, s39, 0xc000
	s_nop 0
	global_load_lds_dwordx4 v134, s[20:21]
	s_add_i32 m0, s39, 0xe000
	s_nop 0
	global_load_lds_dwordx4 v136, s[20:21]
	s_waitcnt vmcnt(8)
	s_waitcnt lgkmcnt(0)
	s_barrier
	v_mfma_f32_16x16x32_bf16 v[124:127], v[138:141], v[160:163], v[124:127]
	v_mfma_f32_16x16x32_bf16 v[120:123], v[152:155], v[160:163], v[120:123]
	v_mfma_f32_16x16x32_bf16 v[108:111], v[138:141], v[168:171], v[108:111]
	v_mfma_f32_16x16x32_bf16 v[104:107], v[152:155], v[168:171], v[104:107]
	v_mfma_f32_16x16x32_bf16 v[92:95], v[138:141], v[176:179], v[92:95]
	v_mfma_f32_16x16x32_bf16 v[88:91], v[152:155], v[176:179], v[88:91]
	v_mfma_f32_16x16x32_bf16 v[76:79], v[138:141], v[200:203], v[76:79]
	v_mfma_f32_16x16x32_bf16 v[72:75], v[152:155], v[200:203], v[72:75]
	v_mfma_f32_16x16x32_bf16 v[124:127], v[148:151], v[164:167], v[124:127]
	v_mfma_f32_16x16x32_bf16 v[120:123], v[156:159], v[164:167], v[120:123]
	v_mfma_f32_16x16x32_bf16 v[108:111], v[148:151], v[172:175], v[108:111]
	v_mfma_f32_16x16x32_bf16 v[104:107], v[156:159], v[172:175], v[104:107]
	v_mfma_f32_16x16x32_bf16 v[92:95], v[148:151], v[196:199], v[92:95]
	v_mfma_f32_16x16x32_bf16 v[88:91], v[156:159], v[196:199], v[88:91]
	v_mfma_f32_16x16x32_bf16 v[76:79], v[148:151], v[204:207], v[76:79]
	v_mfma_f32_16x16x32_bf16 v[72:75], v[156:159], v[204:207], v[72:75]
	v_mfma_f32_16x16x32_bf16 v[116:119], v[208:211], v[160:163], v[116:119]
	v_mfma_f32_16x16x32_bf16 v[112:115], v[216:219], v[160:163], v[112:115]
	v_mfma_f32_16x16x32_bf16 v[100:103], v[208:211], v[168:171], v[100:103]
	v_mfma_f32_16x16x32_bf16 v[96:99], v[216:219], v[168:171], v[96:99]
	v_mfma_f32_16x16x32_bf16 v[84:87], v[208:211], v[176:179], v[84:87]
	v_mfma_f32_16x16x32_bf16 v[80:83], v[216:219], v[176:179], v[80:83]
	v_mfma_f32_16x16x32_bf16 v[68:71], v[208:211], v[200:203], v[68:71]
	v_mfma_f32_16x16x32_bf16 v[64:67], v[216:219], v[200:203], v[64:67]
	v_mfma_f32_16x16x32_bf16 v[116:119], v[212:215], v[164:167], v[116:119]
	v_mfma_f32_16x16x32_bf16 v[112:115], v[220:223], v[164:167], v[112:115]
	v_mfma_f32_16x16x32_bf16 v[100:103], v[212:215], v[172:175], v[100:103]
	v_mfma_f32_16x16x32_bf16 v[96:99], v[220:223], v[172:175], v[96:99]
	v_mfma_f32_16x16x32_bf16 v[84:87], v[212:215], v[196:199], v[84:87]
	v_mfma_f32_16x16x32_bf16 v[80:83], v[220:223], v[196:199], v[80:83]
	v_mfma_f32_16x16x32_bf16 v[68:71], v[212:215], v[204:207], v[68:71]
	v_mfma_f32_16x16x32_bf16 v[64:67], v[220:223], v[204:207], v[64:67]
	s_barrier
	ds_read_b128 v[160:163], v147 offset:16384
	ds_read_b128 v[164:167], v147 offset:17408
	ds_read_b128 v[168:171], v147 offset:18432
	ds_read_b128 v[172:175], v147 offset:19456
	ds_read_b128 v[176:179], v147 offset:20480
	ds_read_b128 v[196:199], v147 offset:21504
	ds_read_b128 v[200:203], v147 offset:22528
	ds_read_b128 v[204:207], v147 offset:23552
	s_add_i32 s54, 0, 0x14000
	s_add_i32 s51, s51, s38
	s_add_u32 vcc_lo, s22, s0
	s_addc_u32 vcc_hi, s23, s1
	s_mov_b32 m0, s51
	s_nop 0
	global_load_lds_dwordx4 v144, s[22:23]
	s_add_i32 m0, s51, 0x2000
	s_nop 0
	global_load_lds_dwordx4 v132, s[22:23]
	s_mov_b32 m0, s39
	s_add_u32 s100, s28, s0
	s_addc_u32 s101, s29, s1
	global_load_lds_dwordx4 v128, s[28:29]
	s_mov_b32 m0, s40
	s_nop 0
	global_load_lds_dwordx4 v130, s[28:29]
	s_add_u32 s52, s22, 0x100000
	s_addc_u32 s53, s23, 0
	s_add_i32 s51, s54, s38
	s_mov_b32 m0, s51
	s_nop 0
	global_load_lds_dwordx4 v144, s[52:53]
	s_add_i32 m0, s51, 0x2000
	s_nop 0
	global_load_lds_dwordx4 v132, s[52:53]
	s_add_i32 s51, 0, 0x18000
	s_waitcnt vmcnt(8)
	s_waitcnt lgkmcnt(0)
	s_barrier
	v_mfma_f32_16x16x32_bf16 v[60:63], v[138:141], v[160:163], v[60:63]
	v_mfma_f32_16x16x32_bf16 v[56:59], v[152:155], v[160:163], v[56:59]
	v_mfma_f32_16x16x32_bf16 v[44:47], v[138:141], v[168:171], v[44:47]
	v_mfma_f32_16x16x32_bf16 v[40:43], v[152:155], v[168:171], v[40:43]
	v_mfma_f32_16x16x32_bf16 v[28:31], v[138:141], v[176:179], v[28:31]
	v_mfma_f32_16x16x32_bf16 v[24:27], v[152:155], v[176:179], v[24:27]
	v_mfma_f32_16x16x32_bf16 v[12:15], v[138:141], v[200:203], v[12:15]
	v_mfma_f32_16x16x32_bf16 v[8:11], v[152:155], v[200:203], v[8:11]
	v_mfma_f32_16x16x32_bf16 v[60:63], v[148:151], v[164:167], v[60:63]
	v_mfma_f32_16x16x32_bf16 v[56:59], v[156:159], v[164:167], v[56:59]
	v_mfma_f32_16x16x32_bf16 v[44:47], v[148:151], v[172:175], v[44:47]
	v_mfma_f32_16x16x32_bf16 v[40:43], v[156:159], v[172:175], v[40:43]
	v_mfma_f32_16x16x32_bf16 v[28:31], v[148:151], v[196:199], v[28:31]
	v_mfma_f32_16x16x32_bf16 v[24:27], v[156:159], v[196:199], v[24:27]
	v_mfma_f32_16x16x32_bf16 v[12:15], v[148:151], v[204:207], v[12:15]
	v_mfma_f32_16x16x32_bf16 v[8:11], v[156:159], v[204:207], v[8:11]
	v_mfma_f32_16x16x32_bf16 v[52:55], v[208:211], v[160:163], v[52:55]
	v_mfma_f32_16x16x32_bf16 v[48:51], v[216:219], v[160:163], v[48:51]
	v_mfma_f32_16x16x32_bf16 v[36:39], v[208:211], v[168:171], v[36:39]
	v_mfma_f32_16x16x32_bf16 v[32:35], v[216:219], v[168:171], v[32:35]
	v_mfma_f32_16x16x32_bf16 v[20:23], v[208:211], v[176:179], v[20:23]
	v_mfma_f32_16x16x32_bf16 v[16:19], v[216:219], v[176:179], v[16:19]
	v_mfma_f32_16x16x32_bf16 v[4:7], v[208:211], v[200:203], v[4:7]
	v_mfma_f32_16x16x32_bf16 v[0:3], v[216:219], v[200:203], v[0:3]
	v_mfma_f32_16x16x32_bf16 v[52:55], v[212:215], v[164:167], v[52:55]
	v_mfma_f32_16x16x32_bf16 v[48:51], v[220:223], v[164:167], v[48:51]
	v_mfma_f32_16x16x32_bf16 v[36:39], v[212:215], v[172:175], v[36:39]
	v_mfma_f32_16x16x32_bf16 v[32:35], v[220:223], v[172:175], v[32:35]
	v_mfma_f32_16x16x32_bf16 v[20:23], v[212:215], v[196:199], v[20:23]
	v_mfma_f32_16x16x32_bf16 v[16:19], v[220:223], v[196:199], v[16:19]
	v_mfma_f32_16x16x32_bf16 v[4:7], v[212:215], v[204:207], v[4:7]
	v_mfma_f32_16x16x32_bf16 v[0:3], v[220:223], v[204:207], v[0:3]
	s_barrier
; #define PG8_STAGE(bufoff, gbase, voff) do { _Pragma("unroll") for (int _i = 0; _i < 2; ++_i) \
;     __builtin_amdgcn_global_load_lds((const unsigned*)((const char*)(gbase) + (voff)[_i]), (LAS unsigned*)(lds + (bufoff) + ldsw + _i * 8192), 16, 0, 0); } while (0)
; #define PG8_LDA(dst, b, h) do { _Pragma("unroll") for (int m = 0; m < 4; ++m) _Pragma("unroll") for (int k = 0; k < 2; ++k) dst[m][k] = *(const LAS bf16x8*)(lds + PG8_SA(b, h) + aoff + m * 2048 + k * 1024); } while (0)
; #define PG8_LDB(dst, b, h) do { _Pragma("unroll") for (int n = 0; n < 2; ++n) _Pragma("unroll") for (int k = 0; k < 2; ++k) dst[n][k] = *(const LAS bf16x8*)(lds + PG8_SB(b, h) + boff + n * 2048 + k * 1024); } while (0)
; #define PG8_MMA(ai, bj, At, Bt) do { __builtin_amdgcn_s_setprio(1); _Pragma("unroll") for (int m = 0; m < 4; ++m) _Pragma("unroll") for (int n = 0; n < 2; ++n) _Pragma("unroll") for (int k = 0; k < 2; ++k) \
;     acc[ai][bj][m][n] = __builtin_amdgcn_mfma_f32_16x16x32_bf16(Bt[n][k], At[m][k], acc[ai][bj][m][n], 0, 0, 0); __builtin_amdgcn_s_setprio(0); } while (0)
; #define PG8_WAIT_L(n) asm volatile("s_waitcnt lgkmcnt(" #n ")" ::: "memory")
; #define PG8_BAR __builtin_amdgcn_s_barrier()
; #define PG8_SCHED __builtin_amdgcn_sched_barrier(0)
; template <class Epi, class Sched>
; DI void gemm_phase(LAS unsigned char* lds, const Gemm g, const Sched& S, const Epi& E) {
;     ...
;       PG8_LDB(B0, 1, 0); PG8_SCHED; PG8_LDA(At, 1, 0); PG8_STAGE(PG8_SA(0, 1), a2 + hstep, voffA);
;       PG8_WAIT_L(8); PG8_BAR; PG8_WAIT_L(0); PG8_MMA(0, 0, At, B0); PG8_BAR; PG8_SCHED;
;       PG8_LDB(B1, 1, 1); PG8_STAGE(PG8_SB(1, 0), b3, voffB);
;       PG8_BAR; PG8_WAIT_L(0); PG8_MMA(0, 1, At, B1); PG8_BAR;
	ds_read_b128 v[138:141], v226
	ds_read_b128 v[148:151], v226 offset:1024
	ds_read_b128 v[152:155], v226 offset:2048
	ds_read_b128 v[156:159], v226 offset:3072
	ds_read_b128 v[160:163], v147 offset:32768
	ds_read_b128 v[164:167], v147 offset:33792
	ds_read_b128 v[168:171], v147 offset:34816
	ds_read_b128 v[172:175], v147 offset:35840
	ds_read_b128 v[176:179], v147 offset:36864
	ds_read_b128 v[196:199], v147 offset:37888
	ds_read_b128 v[200:203], v147 offset:38912
	ds_read_b128 v[204:207], v147 offset:39936
	ds_read_b128 v[208:211], v227
	ds_read_b128 v[212:215], v227 offset:1024
	ds_read_b128 v[216:219], v227 offset:2048
	ds_read_b128 v[220:223], v227 offset:3072
	s_add_u32 s28, s28, 0x100000
	s_addc_u32 s29, s29, 0
	s_mov_b32 m0, s41
	s_nop 0
	global_load_lds_dwordx4 v128, s[28:29]
	s_mov_b32 m0, s42
	s_nop 0
	global_load_lds_dwordx4 v130, s[28:29]
	s_waitcnt vmcnt(8)
	s_waitcnt lgkmcnt(0)
	s_barrier
	v_mfma_f32_16x16x32_bf16 v[124:127], v[138:141], v[160:163], v[124:127]
	v_mfma_f32_16x16x32_bf16 v[120:123], v[152:155], v[160:163], v[120:123]
	v_mfma_f32_16x16x32_bf16 v[108:111], v[138:141], v[168:171], v[108:111]
	v_mfma_f32_16x16x32_bf16 v[104:107], v[152:155], v[168:171], v[104:107]
	v_mfma_f32_16x16x32_bf16 v[92:95], v[138:141], v[176:179], v[92:95]
	v_mfma_f32_16x16x32_bf16 v[88:91], v[152:155], v[176:179], v[88:91]
	v_mfma_f32_16x16x32_bf16 v[76:79], v[138:141], v[200:203], v[76:79]
	v_mfma_f32_16x16x32_bf16 v[72:75], v[152:155], v[200:203], v[72:75]
	v_mfma_f32_16x16x32_bf16 v[124:127], v[148:151], v[164:167], v[124:127]
	v_mfma_f32_16x16x32_bf16 v[120:123], v[156:159], v[164:167], v[120:123]
	v_mfma_f32_16x16x32_bf16 v[108:111], v[148:151], v[172:175], v[108:111]
	v_mfma_f32_16x16x32_bf16 v[104:107], v[156:159], v[172:175], v[104:107]
	v_mfma_f32_16x16x32_bf16 v[92:95], v[148:151], v[196:199], v[92:95]
	v_mfma_f32_16x16x32_bf16 v[88:91], v[156:159], v[196:199], v[88:91]
	v_mfma_f32_16x16x32_bf16 v[76:79], v[148:151], v[204:207], v[76:79]
	v_mfma_f32_16x16x32_bf16 v[72:75], v[156:159], v[204:207], v[72:75]
	v_mfma_f32_16x16x32_bf16 v[116:119], v[208:211], v[160:163], v[116:119]
	v_mfma_f32_16x16x32_bf16 v[112:115], v[216:219], v[160:163], v[112:115]
	v_mfma_f32_16x16x32_bf16 v[100:103], v[208:211], v[168:171], v[100:103]
	v_mfma_f32_16x16x32_bf16 v[96:99], v[216:219], v[168:171], v[96:99]
	v_mfma_f32_16x16x32_bf16 v[84:87], v[208:211], v[176:179], v[84:87]
	v_mfma_f32_16x16x32_bf16 v[80:83], v[216:219], v[176:179], v[80:83]
	v_mfma_f32_16x16x32_bf16 v[68:71], v[208:211], v[200:203], v[68:71]
	v_mfma_f32_16x16x32_bf16 v[64:67], v[216:219], v[200:203], v[64:67]
	v_mfma_f32_16x16x32_bf16 v[116:119], v[212:215], v[164:167], v[116:119]
	v_mfma_f32_16x16x32_bf16 v[112:115], v[220:223], v[164:167], v[112:115]
	v_mfma_f32_16x16x32_bf16 v[100:103], v[212:215], v[172:175], v[100:103]
	v_mfma_f32_16x16x32_bf16 v[96:99], v[220:223], v[172:175], v[96:99]
	v_mfma_f32_16x16x32_bf16 v[84:87], v[212:215], v[196:199], v[84:87]
	v_mfma_f32_16x16x32_bf16 v[80:83], v[220:223], v[196:199], v[80:83]
	v_mfma_f32_16x16x32_bf16 v[68:71], v[212:215], v[204:207], v[68:71]
	v_mfma_f32_16x16x32_bf16 v[64:67], v[220:223], v[204:207], v[64:67]
	s_barrier
	ds_read_b128 v[160:163], v147 offset:49152
	ds_read_b128 v[164:167], v147 offset:50176
	ds_read_b128 v[168:171], v147 offset:51200
	ds_read_b128 v[172:175], v147 offset:52224
	ds_read_b128 v[176:179], v147 offset:53248
	ds_read_b128 v[196:199], v147 offset:54272
	ds_read_b128 v[200:203], v147 offset:55296
	ds_read_b128 v[204:207], v147 offset:56320
	s_add_i32 s28, 0, 0x1c000
	s_add_i32 s29, s51, s38
	s_mov_b32 m0, s29
	s_nop 0
	global_load_lds_dwordx4 v144, vcc
	s_add_i32 m0, s29, 0x2000
	s_nop 0
	global_load_lds_dwordx4 v132, vcc
	s_mov_b32 m0, s46
	s_nop 0
	global_load_lds_dwordx4 v128, s[100:101]
	s_mov_b32 m0, s47
	s_nop 0
	global_load_lds_dwordx4 v130, s[100:101]
	s_add_u32 s22, s22, 0x100080
	s_addc_u32 s23, s23, 0
	s_add_i32 s28, s28, s38
	s_mov_b32 m0, s28
	s_nop 0
	global_load_lds_dwordx4 v144, s[22:23]
	s_add_i32 m0, s28, 0x2000
	s_nop 0
	global_load_lds_dwordx4 v132, s[22:23]
	s_add_i32 s50, s50, 2
	s_add_u32 s20, s20, 0x100
	s_addc_u32 s21, s21, 0
	s_add_u32 s24, s24, 0x100
	s_addc_u32 s49, s49, 0
	s_cmp_gt_u32 s50, 61
	s_waitcnt vmcnt(8)
	s_waitcnt lgkmcnt(0)
	s_barrier
; template <class Epi, class Sched>
; DI void gemm_phase(LAS unsigned char* lds, const Gemm g, const Sched& S, const Epi& E) {
;     ...
;       PG8_LDA(At, 1, 1); PG8_STAGE(PG8_SA(1, 0), a3, voffA);
;       PG8_BAR; PG8_WAIT_L(0); PG8_MMA(1, 0, At, B0); PG8_BAR; PG8_SCHED;
;       PG8_STAGE(PG8_SB(1, 1), b3 + hstep, voffB);
;       PG8_WAIT_V(6); PG8_BAR; PG8_MMA(1, 1, At, B1); PG8_BAR;
;     }
;     E(acc, cur, wr, wc, fr, fq);
;   DI void operator()(const f32x4 (&acc)[2][2][4][2], const pg8::Unit& u, int wr, int wc, int fr_, int fq_) const {
;     ...
;             } else if (EPI == EPI_RESID) {
;               if (n == 0) {
;                 const int f8 = u.pn * 256 + bj * 128 + wc * 32 + 8 * fq;
;                 const f32x4 v1 = acc[ai][bj][m][1];
;                 f32x4 r0, r1;
;                 if (rsrc) {
;                   r0 = *(const f32x4*)(rsrc + (size_t)token * 1024 + f8); r1 = *(const f32x4*)(rsrc + (size_t)token * 1024 + f8 + 4);
;                 } else {
;                   const u32x4 xu = *(const u32x4*)(xr + (size_t)token * 1024 + f8);
;                   r0 = (f32x4){bf2f(xu.x & 0xffffu), bf2f(xu.x >> 16), bf2f(xu.y & 0xffffu), bf2f(xu.y >> 16)};
;                   r1 = (f32x4){bf2f(xu.z & 0xffffu), bf2f(xu.z >> 16), bf2f(xu.w & 0xffffu), bf2f(xu.w >> 16)};
;                 }
;                 r0 += v; r1 += v1;
;                 st_bf8(xr + (size_t)token * 1024 + f8, r0, r1, 1.f);
;                 ssq += r0[0] * r0[0] + r0[1] * r0[1] + r0[2] * r0[2] + r0[3] * r0[3] + r1[0] * r1[0] + r1[1] * r1[1] + r1[2] * r1[2] + r1[3] * r1[3];
;               }
;             } else {
;               if (n == 0) {
;                 const f32x4 v1 = acc[ai][bj][m][1];
;                 u32x4 o4;
;                 { const float t0 = fmaxf(v[0], 0.f) * rinv, t1 = fmaxf(v[1], 0.f) * rinv, t2 = fmaxf(v[2], 0.f) * rinv, t3 = fmaxf(v[3], 0.f) * rinv;
;                   o4.x = pack2(t0 * t0, t1 * t1); o4.y = pack2(t2 * t2, t3 * t3); }
;                 { const float t0 = fmaxf(v1[0], 0.f) * rinv, t1 = fmaxf(v1[1], 0.f) * rinv, t2 = fmaxf(v1[2], 0.f) * rinv, t3 = fmaxf(v1[3], 0.f) * rinv;
;                   o4.z = pack2(t0 * t0, t1 * t1); o4.w = pack2(t2 * t2, t3 * t3); }
;                 *(u32x4*)((u16*)big + (size_t)token * 4096 + u.pn * 256 + bj * 128 + wc * 32 + 8 * fq) = o4;
;               }
;             }
;           }
;         if (EPI == EPI_RESID) {
	v_mfma_f32_16x16x32_bf16 v[60:63], v[138:141], v[160:163], v[60:63]
	v_mfma_f32_16x16x32_bf16 v[56:59], v[152:155], v[160:163], v[56:59]
	v_mfma_f32_16x16x32_bf16 v[44:47], v[138:141], v[168:171], v[44:47]
	v_mfma_f32_16x16x32_bf16 v[40:43], v[152:155], v[168:171], v[40:43]
	v_mfma_f32_16x16x32_bf16 v[28:31], v[138:141], v[176:179], v[28:31]
	v_mfma_f32_16x16x32_bf16 v[24:27], v[152:155], v[176:179], v[24:27]
	v_mfma_f32_16x16x32_bf16 v[12:15], v[138:141], v[200:203], v[12:15]
	v_mfma_f32_16x16x32_bf16 v[8:11], v[152:155], v[200:203], v[8:11]
	v_mfma_f32_16x16x32_bf16 v[60:63], v[148:151], v[164:167], v[60:63]
	v_mfma_f32_16x16x32_bf16 v[56:59], v[156:159], v[164:167], v[56:59]
	v_mfma_f32_16x16x32_bf16 v[44:47], v[148:151], v[172:175], v[44:47]
	v_mfma_f32_16x16x32_bf16 v[40:43], v[156:159], v[172:175], v[40:43]
	v_mfma_f32_16x16x32_bf16 v[28:31], v[148:151], v[196:199], v[28:31]
	v_mfma_f32_16x16x32_bf16 v[24:27], v[156:159], v[196:199], v[24:27]
	v_mfma_f32_16x16x32_bf16 v[12:15], v[148:151], v[204:207], v[12:15]
	v_mfma_f32_16x16x32_bf16 v[8:11], v[156:159], v[204:207], v[8:11]
	v_mfma_f32_16x16x32_bf16 v[52:55], v[208:211], v[160:163], v[52:55]
	v_mfma_f32_16x16x32_bf16 v[48:51], v[216:219], v[160:163], v[48:51]
	v_mfma_f32_16x16x32_bf16 v[36:39], v[208:211], v[168:171], v[36:39]
	v_mfma_f32_16x16x32_bf16 v[32:35], v[216:219], v[168:171], v[32:35]
	v_mfma_f32_16x16x32_bf16 v[20:23], v[208:211], v[176:179], v[20:23]
	v_mfma_f32_16x16x32_bf16 v[16:19], v[216:219], v[176:179], v[16:19]
	v_mfma_f32_16x16x32_bf16 v[4:7], v[208:211], v[200:203], v[4:7]
	v_mfma_f32_16x16x32_bf16 v[0:3], v[216:219], v[200:203], v[0:3]
	v_mfma_f32_16x16x32_bf16 v[52:55], v[212:215], v[164:167], v[52:55]
	v_mfma_f32_16x16x32_bf16 v[48:51], v[220:223], v[164:167], v[48:51]
	v_mfma_f32_16x16x32_bf16 v[36:39], v[212:215], v[172:175], v[36:39]
	v_mfma_f32_16x16x32_bf16 v[32:35], v[220:223], v[172:175], v[32:35]
	v_mfma_f32_16x16x32_bf16 v[20:23], v[212:215], v[196:199], v[20:23]
	v_mfma_f32_16x16x32_bf16 v[16:19], v[220:223], v[196:199], v[16:19]
	v_mfma_f32_16x16x32_bf16 v[4:7], v[212:215], v[204:207], v[4:7]
	v_mfma_f32_16x16x32_bf16 v[0:3], v[220:223], v[204:207], v[0:3]
	s_barrier
	s_cbranch_scc0 .LBB0_1905
	s_lshl_b32 s7, s18, 8
	v_mov_b32_e32 v139, v182
	s_add_i32 s7, s7, s44
	s_nop 0
	v_and_or_b32 v140, v139, 15, s7
	s_lshl_b32 s7, s16, 8
	v_bfe_u32 v141, v139, 4, 2
	s_or_b32 s7, s7, s45
	v_lshl_or_b32 v138, v141, 3, s7
	v_cmp_eq_u32_e32 vcc, 0, v141
	v_ashrrev_i32_e32 v141, 31, v140
	v_lshlrev_b32_e32 v139, 2, v139
	s_movk_i32 s7, 0x80
	v_lshlrev_b64 v[142:143], 11, v[140:141]
	v_bitop3_b32 v149, v139, 64, v190 bitop3:0x6c
	v_bitop3_b32 v148, v139, s7, v190 bitop3:0x6c
	v_ashrrev_i32_e32 v139, 31, v138
	v_lshl_add_u64 v[142:143], s[4:5], 0, v[142:143]
	v_lshl_add_u64 v[142:143], v[138:139], 1, v[142:143]
	global_load_dwordx4 v[150:153], v[142:143], off
	s_lshl_b32 s16, s16, 2
	s_ashr_i32 s17, s16, 31
	s_waitcnt vmcnt(0)
	v_lshlrev_b32_e32 v154, 16, v150
	v_and_b32_e32 v155, 0xffff0000, v150
	v_lshlrev_b32_e32 v150, 16, v151
	v_and_b32_e32 v151, 0xffff0000, v151
	v_lshlrev_b32_e32 v156, 16, v152
	v_and_b32_e32 v157, 0xffff0000, v152
	v_lshlrev_b32_e32 v152, 16, v153
	v_and_b32_e32 v153, 0xffff0000, v153
	v_pk_add_f32 v[126:127], v[126:127], v[150:151]
	v_pk_add_f32 v[124:125], v[124:125], v[154:155]
	v_pk_add_f32 v[150:151], v[122:123], v[152:153]
	v_pk_add_f32 v[152:153], v[120:121], v[156:157]
	v_cvt_pk_bf16_f32 v120, v124, v125
	v_cvt_pk_bf16_f32 v121, v126, v127
	v_cvt_pk_bf16_f32 v122, v152, v153
	v_cvt_pk_bf16_f32 v123, v150, v151
	global_store_dwordx4 v[142:143], v[120:123], off
	global_load_dwordx4 v[120:123], v[142:143], off offset:256
	v_mul_f32_e32 v154, v125, v125
	v_fmac_f32_e32 v154, v124, v124
	v_fmac_f32_e32 v154, v126, v126
	v_fmac_f32_e32 v154, v127, v127
	v_fmac_f32_e32 v154, v152, v152
	v_fmac_f32_e32 v154, v153, v153
	v_fmac_f32_e32 v154, v150, v150
	v_fmac_f32_e32 v154, v151, v151
	s_waitcnt vmcnt(0)
	v_lshlrev_b32_e32 v124, 16, v120
	v_and_b32_e32 v125, 0xffff0000, v120
	v_lshlrev_b32_e32 v120, 16, v121
	v_and_b32_e32 v121, 0xffff0000, v121
	v_lshlrev_b32_e32 v126, 16, v122
	v_and_b32_e32 v127, 0xffff0000, v122
	v_lshlrev_b32_e32 v122, 16, v123
	v_and_b32_e32 v123, 0xffff0000, v123
	v_pk_add_f32 v[118:119], v[118:119], v[120:121]
	v_pk_add_f32 v[116:117], v[116:117], v[124:125]
	v_pk_add_f32 v[120:121], v[114:115], v[122:123]
	v_pk_add_f32 v[122:123], v[112:113], v[126:127]
	v_cvt_pk_bf16_f32 v112, v116, v117
	v_cvt_pk_bf16_f32 v113, v118, v119
	v_cvt_pk_bf16_f32 v114, v122, v123
	v_cvt_pk_bf16_f32 v115, v120, v121
	global_store_dwordx4 v[142:143], v[112:115], off offset:256
	s_nop 1
	v_mul_f32_e32 v112, v117, v117
	v_fmac_f32_e32 v112, v116, v116
	v_fmac_f32_e32 v112, v118, v118
	v_fmac_f32_e32 v112, v119, v119
	v_fmac_f32_e32 v112, v122, v122
	v_fmac_f32_e32 v112, v123, v123
	v_fmac_f32_e32 v112, v120, v120
	v_fmac_f32_e32 v112, v121, v121
	v_add_f32_e32 v112, v154, v112
	ds_bpermute_b32 v113, v149, v112
	s_waitcnt lgkmcnt(0)
	v_add_f32_e32 v112, v112, v113
	ds_bpermute_b32 v113, v148, v112
	s_and_saveexec_b64 s[18:19], vcc
	s_cbranch_execz .LBB0_1908
	s_waitcnt lgkmcnt(0)
	v_add_f32_e32 v114, v112, v113
	v_lshlrev_b64 v[112:113], 6, v[140:141]
	v_lshl_add_u64 v[112:113], s[2:3], 0, v[112:113]
	v_lshl_add_u64 v[112:113], s[16:17], 2, v[112:113]
	s_lshl_b32 s24, s43, 2
	v_lshl_add_u64 v[112:113], v[112:113], 0, s[24:25]
	global_store_dword v[112:113], v114, off
